# GEMM loops: half-stage skewed pipeline (MFMAs on register-resident k-step right after each barrier), DMA issue interleaved, direct SwiGLU epilogue from accumulators
# speedup vs baseline: 1.1228x; 1.0372x over previous
; DI int otid() { int t = threadIdx.x; asm volatile("" : "+v"(t)); return t; }
; template <bool SWAP, bool HALF>
; DI void gemm_mainloop(const GemmDesc& d, int m0, int n0, bf16_t* smem, f32x16 (&acc)[2][2], int dry) {
;   const int t = otid(), lane = t & 63, w = t >> 6, wm = w >> 1, wn = w & 1, r = lane & 31, hh = lane >> 5;
;   const int lrow = t >> 3, lkc = t & 7;
;   const bf16_t* ap[4]; const bf16_t* bp[4];
; #pragma unroll
;   for (int i = 0; i < 4; ++i) {
;     int am = m0 + lrow + 32 * i; am = am < M ? am : M - 1;
;     ap[i] = d.A + (size_t)am * d.lda + lkc * 8 + (d.a_grp ? (n0 / d.a_grp) * d.a_grp : 0);
;     bp[i] = d.Bt + (size_t)(n0 + lrow + 32 * i) * d.ldb + lkc * 8;
;   }
; #pragma unroll
;   for (int a = 0; a < 2; ++a)
; #pragma unroll
;     for (int b = 0; b < 2; ++b)
; #pragma unroll
;       for (int i = 0; i < 16; ++i) acc[a][b][i] = 0.f;
;   u32x4 ra0[4], rb0[4], ra1[4], rb1[4];
;   const int nk = d.K >> 6;
;   const int lds_w = lrow * LST + lkc * 8;
;     ...
;   gl(ra0, rb0, 0);
;   gl(ra1, rb1, 1);
;   lw(ra0, rb0, 0);
;   gl(ra0, rb0, 2);
;   __syncthreads();
;   ldf(0, 0, 0);
.LBB0_190:
	s_or_b64 exec, exec, s[4:5]
	s_lshl_b32 s33, s7, 7
	s_and_b32 s4, s7, -8
	s_waitcnt vmcnt(0)
	v_ashrrev_i32_e32 v187, 7, v150
	v_bfe_u32 v188, v150, 6, 1
	v_and_b32_e32 v170, 31, v150
	v_bfe_u32 v189, v150, 5, 1
	s_cmp_lg_u32 s4, 16
	s_mov_b64 s[4:5], -1
	s_cbranch_scc0 .LBB0_260
	v_mov_b32_e32 v32, v172
	v_readlane_b32 s76, v228, 60
	v_ashrrev_i32_e32 v10, 3, v32
	v_lshlrev_b32_e32 v0, 3, v32
	v_and_b32_e32 v33, 56, v0
	v_add_u32_e32 v2, s33, v10
	v_lshlrev_b32_e32 v144, 1, v33
	v_readlane_b32 s90, v223, 10
	v_readlane_b32 s91, v223, 11
	v_ashrrev_i32_e32 v3, 31, v2
	v_add_u32_e32 v11, s25, v10
	v_lshl_add_u64 v[4:5], s[90:91], 0, v[144:145]
	v_lshlrev_b64 v[2:3], 11, v[2:3]
	v_lshl_add_u64 v[154:155], v[4:5], 0, v[2:3]
	v_min_i32_e32 v2, 0x801f, v11
	v_ashrrev_i32_e32 v3, 31, v2
	v_lshl_add_u64 v[0:1], s[56:57], 0, v[144:145]
	v_lshlrev_b64 v[2:3], 11, v[2:3]
	v_lshl_add_u64 v[8:9], v[0:1], 0, v[2:3]
	v_min_i32_e32 v2, 0x7fff, v11
	v_ashrrev_i32_e32 v3, 31, v2
	v_min_i32_e32 v6, 0x803f, v11
	v_lshlrev_b64 v[2:3], 11, v[2:3]
	v_ashrrev_i32_e32 v7, 31, v6
	v_lshl_add_u64 v[16:17], v[0:1], 0, v[2:3]
	v_min_i32_e32 v2, 0x7fdf, v11
	v_lshlrev_b64 v[6:7], 11, v[6:7]
	v_ashrrev_i32_e32 v3, 31, v2
	v_lshl_add_u64 v[152:153], v[0:1], 0, v[6:7]
	v_lshlrev_b64 v[2:3], 11, v[2:3]
	v_lshl_add_u64 v[24:25], v[0:1], 0, v[2:3]
	s_mov_b64 s[4:5], 0x10000
	v_lshl_add_u64 v[156:157], v[8:9], 0, s[4:5]
	v_lshl_add_u64 v[158:159], v[154:155], 0, s[4:5]
	s_mov_b64 s[4:5], 0x20000
	v_lshl_add_u64 v[160:161], v[16:17], 0, s[4:5]
	v_lshl_add_u64 v[162:163], v[154:155], 0, s[4:5]
	s_mov_b64 s[4:5], 0x30000
	v_lshl_add_u64 v[164:165], v[24:25], 0, s[4:5]
	v_lshl_add_u64 v[166:167], v[154:155], 0, s[4:5]
	s_movk_i32 s4, 0x48
	v_and_b32_e32 v34, 31, v32
	v_mul_lo_u32 v35, v10, s4
	v_readlane_b32 s77, v228, 61
	v_readlane_b32 s78, v228, 62
	v_readlane_b32 s79, v228, 63
	v_readlane_b32 s80, v223, 0
	v_readlane_b32 s81, v223, 1
	v_readlane_b32 s82, v223, 2
	v_readlane_b32 s83, v223, 3
	v_readlane_b32 s84, v223, 4
	v_readlane_b32 s85, v223, 5
	v_readlane_b32 s86, v223, 6
	v_readlane_b32 s87, v223, 7
	v_readlane_b32 s88, v223, 8
	v_readlane_b32 s89, v223, 9
	s_mov_b32 s4, 0x10000
	v_add_co_u32_e32 v8, vcc, s4, v8
	s_nop 1
	v_addc_co_u32_e32 v9, vcc, 0, v9, vcc
	s_waitcnt vmcnt(19)
	v_add_co_u32_e32 v12, vcc, s4, v154
	s_nop 1
	v_addc_co_u32_e32 v13, vcc, 0, v155, vcc
	s_mov_b32 s4, 0x20000
	v_add_co_u32_e32 v16, vcc, s4, v16
	s_nop 1
	v_addc_co_u32_e32 v17, vcc, 0, v17, vcc
	v_add_co_u32_e32 v20, vcc, s4, v154
	s_nop 1
	v_addc_co_u32_e32 v21, vcc, 0, v155, vcc
	s_mov_b32 s4, 0x30000
	v_add_co_u32_e32 v24, vcc, s4, v24
	s_nop 1
	v_addc_co_u32_e32 v25, vcc, 0, v25, vcc
	v_add_co_u32_e32 v28, vcc, s4, v154
	s_nop 1
	v_addc_co_u32_e32 v29, vcc, 0, v155, vcc
	s_nop 0
	v_add_lshl_u32 v144, v35, v33, 1
	s_waitcnt vmcnt(15)
	s_waitcnt vmcnt(14)
	s_waitcnt vmcnt(13)
	s_waitcnt vmcnt(12)
	s_waitcnt vmcnt(11)
	s_waitcnt vmcnt(10)
	s_waitcnt vmcnt(9)
	s_waitcnt vmcnt(8)
	v_lshrrev_b32_e32 v0, 1, v32
	v_and_or_b32 v1, v0, s72, v34
	v_and_b32_e32 v0, 16, v0
	s_movk_i32 s4, 0x90
	v_mad_u64_u32 v[168:169], s[4:5], v1, s4, v[0:1]
	v_and_b32_e32 v1, 0x5f, v32
	v_mul_u32_u24_e32 v1, 0x48, v1
	v_lshl_add_u32 v169, v1, 1, v0
	v_bfe_u32 v212, v172, 4, 3
	v_lshlrev_b32_e32 v212, 4, v212
	v_xor_b32_e32 v152, v152, v212
	v_xor_b32_e32 v154, v154, v212
	v_xor_b32_e32 v156, v156, v212
	v_xor_b32_e32 v158, v158, v212
	v_xor_b32_e32 v160, v160, v212
	v_xor_b32_e32 v162, v162, v212
	v_xor_b32_e32 v164, v164, v212
	v_xor_b32_e32 v166, v166, v212
	v_lshrrev_b32_e32 v213, 6, v172
	s_nop 1
	v_readfirstlane_b32 s101, v213
	s_lshl_b32 s101, s101, 10
	s_add_u32 m0, s101, 0x0
	s_nop 0
	global_load_lds_dwordx4 v[152:153], off
	s_add_u32 m0, s101, 0x4000
	s_nop 0
	global_load_lds_dwordx4 v[154:155], off
	s_add_u32 m0, s101, 0x1000
	s_nop 0
	global_load_lds_dwordx4 v[156:157], off
	s_add_u32 m0, s101, 0x5000
	s_nop 0
	global_load_lds_dwordx4 v[158:159], off
	s_add_u32 m0, s101, 0x2000
	s_nop 0
	global_load_lds_dwordx4 v[160:161], off
	s_add_u32 m0, s101, 0x6000
	s_nop 0
	global_load_lds_dwordx4 v[162:163], off
	s_add_u32 m0, s101, 0x3000
	s_nop 0
	global_load_lds_dwordx4 v[164:165], off
	s_add_u32 m0, s101, 0x7000
	s_nop 0
	global_load_lds_dwordx4 v[166:167], off
	v_and_b32_e32 v212, 15, v172
	v_bfe_u32 v213, v172, 4, 2
	v_lshrrev_b32_e32 v214, 1, v212
	v_xor_b32_e32 v213, v213, v214
	v_lshlrev_b32_e32 v213, 4, v213
	v_lshl_or_b32 v212, v212, 7, v213
	v_lshrrev_b32_e32 v214, 7, v172
	v_lshl_add_u32 v168, v214, 13, v212
	v_bfe_u32 v214, v172, 6, 1
	v_lshl_add_u32 v169, v214, 13, v212
	v_add_u32_e32 v169, 0x4000, v169
	v_xor_b32_e32 v220, 64, v168
	v_xor_b32_e32 v221, 64, v169
	s_waitcnt vmcnt(0)
	s_waitcnt lgkmcnt(0)
	s_barrier
; #define SB_ __builtin_amdgcn_sched_barrier(0)
; template <bool SWAP, bool HALF>
; DI void gemm_mainloop(const GemmDesc& d, int m0, int n0, bf16_t* smem, f32x16 (&acc)[2][2], int dry) {
;     ...
; #pragma unroll
;   for (int a = 0; a < 2; ++a)
; #pragma unroll
;     for (int b = 0; b < 2; ++b)
; #pragma unroll
;       for (int i = 0; i < 16; ++i) acc[a][b][i] = 0.f;
;     ...
;   auto stage = [&](int cur, u32x4 (&ran)[4], u32x4 (&rbn)[4], int ks) {
;     ldf(cur, 1, 1); SB_;
;     mma(0); SB_;
;     ldf(cur, 2, 0); SB_;
;     lw(ran, rbn, cur ^ 1);
;     gl(ran, rbn, (ks + 3 < nk) ? ks + 3 : nk - 1);
;     SB_;
;     mma(1); SB_;
;     __syncthreads();
;     ldf(cur, 3, 1); SB_;
;     mma(0); SB_;
;     ldf(cur ^ 1, 0, 0);
;     SB_;
;     mma(1); SB_;
;     __syncthreads();
;   };
;   gl(ra0, rb0, 0);
;   gl(ra1, rb1, 1);
;   lw(ra0, rb0, 0);
;   gl(ra0, rb0, 2);
;   __syncthreads();
;   ldf(0, 0, 0);
	v_mov_b32_e32 v0, 0
	v_add_u32_e32 v190, 0x9000, v144
	s_mov_b32 s4, -2
	v_mov_b32_e32 v1, v0
	v_mov_b32_e32 v2, v0
	v_mov_b32_e32 v3, v0
	v_mov_b32_e32 v4, v0
	v_mov_b32_e32 v5, v0
	v_mov_b32_e32 v6, v0
	v_mov_b32_e32 v7, v0
	v_mov_b32_e32 v8, v0
	v_mov_b32_e32 v9, v0
	v_mov_b32_e32 v10, v0
	v_mov_b32_e32 v11, v0
	v_mov_b32_e32 v12, v0
	v_mov_b32_e32 v13, v0
	v_mov_b32_e32 v14, v0
	v_mov_b32_e32 v15, v0
	v_mov_b32_e32 v16, v0
	v_mov_b32_e32 v17, v0
	v_mov_b32_e32 v18, v0
	v_mov_b32_e32 v19, v0
	v_mov_b32_e32 v20, v0
	v_mov_b32_e32 v21, v0
	v_mov_b32_e32 v22, v0
	v_mov_b32_e32 v23, v0
	v_mov_b32_e32 v24, v0
	v_mov_b32_e32 v25, v0
	v_mov_b32_e32 v26, v0
	v_mov_b32_e32 v27, v0
	v_mov_b32_e32 v28, v0
	v_mov_b32_e32 v29, v0
	v_mov_b32_e32 v30, v0
	v_mov_b32_e32 v31, v0
	v_mov_b32_e32 v32, v0
	v_mov_b32_e32 v33, v0
	v_mov_b32_e32 v34, v0
	v_mov_b32_e32 v35, v0
	v_mov_b32_e32 v36, v0
	v_mov_b32_e32 v37, v0
	v_mov_b32_e32 v38, v0
	v_mov_b32_e32 v39, v0
	v_mov_b32_e32 v40, v0
	v_mov_b32_e32 v41, v0
	v_mov_b32_e32 v42, v0
	v_mov_b32_e32 v43, v0
	v_mov_b32_e32 v44, v0
	v_mov_b32_e32 v45, v0
	v_mov_b32_e32 v46, v0
	v_mov_b32_e32 v47, v0
	v_mov_b32_e32 v48, v0
	v_mov_b32_e32 v49, v0
	v_mov_b32_e32 v50, v0
	v_mov_b32_e32 v51, v0
	v_mov_b32_e32 v52, v0
	v_mov_b32_e32 v53, v0
	v_mov_b32_e32 v54, v0
	v_mov_b32_e32 v55, v0
	v_mov_b32_e32 v56, v0
	v_mov_b32_e32 v57, v0
	v_mov_b32_e32 v58, v0
	v_mov_b32_e32 v59, v0
	v_mov_b32_e32 v60, v0
	v_mov_b32_e32 v61, v0
	v_mov_b32_e32 v62, v0
	v_mov_b32_e32 v63, v0
	ds_read_b128 v[64:67], v168 offset:0
	ds_read_b128 v[68:71], v168 offset:2048
	ds_read_b128 v[72:75], v168 offset:4096
	ds_read_b128 v[76:79], v168 offset:6144
	ds_read_b128 v[80:83], v169 offset:0
	ds_read_b128 v[84:87], v169 offset:2048
	ds_read_b128 v[88:91], v169 offset:4096
	ds_read_b128 v[92:95], v169 offset:6144
	s_add_i32 s5, s4, 3
	s_min_u32 s5, s5, 15
	s_lshl_b32 s18, s5, 7
	s_add_u32 m0, s101, 0x8000
	v_lshl_add_u64 v[210:211], v[152:153], 0, s[18:19]
	global_load_lds_dwordx4 v[210:211], off
	s_add_u32 m0, s101, 0xc000
	v_lshl_add_u64 v[210:211], v[154:155], 0, s[18:19]
	global_load_lds_dwordx4 v[210:211], off
	ds_read_b128 v[96:99], v220 offset:0
	ds_read_b128 v[100:103], v220 offset:2048
	ds_read_b128 v[104:107], v220 offset:4096
	ds_read_b128 v[108:111], v220 offset:6144
	ds_read_b128 v[112:115], v221 offset:0
	ds_read_b128 v[116:119], v221 offset:2048
	ds_read_b128 v[120:123], v221 offset:4096
	ds_read_b128 v[124:127], v221 offset:6144
	s_waitcnt lgkmcnt(8)
	v_mfma_f32_16x16x32_bf16 v[0:3], v[80:83], v[64:67], v[0:3]
	v_mfma_f32_16x16x32_bf16 v[4:7], v[84:87], v[64:67], v[4:7]
	s_add_u32 m0, s101, 0x9000
	v_lshl_add_u64 v[210:211], v[156:157], 0, s[18:19]
	global_load_lds_dwordx4 v[210:211], off
	v_mfma_f32_16x16x32_bf16 v[8:11], v[88:91], v[64:67], v[8:11]
	v_mfma_f32_16x16x32_bf16 v[12:15], v[92:95], v[64:67], v[12:15]
	s_add_u32 m0, s101, 0xd000
	v_lshl_add_u64 v[210:211], v[158:159], 0, s[18:19]
	global_load_lds_dwordx4 v[210:211], off
	v_mfma_f32_16x16x32_bf16 v[16:19], v[80:83], v[68:71], v[16:19]
	v_mfma_f32_16x16x32_bf16 v[20:23], v[84:87], v[68:71], v[20:23]
	s_add_u32 m0, s101, 0xa000
	v_lshl_add_u64 v[210:211], v[160:161], 0, s[18:19]
	global_load_lds_dwordx4 v[210:211], off
	v_mfma_f32_16x16x32_bf16 v[24:27], v[88:91], v[68:71], v[24:27]
	v_mfma_f32_16x16x32_bf16 v[28:31], v[92:95], v[68:71], v[28:31]
	s_add_u32 m0, s101, 0xe000
	v_lshl_add_u64 v[210:211], v[162:163], 0, s[18:19]
	global_load_lds_dwordx4 v[210:211], off
	v_mfma_f32_16x16x32_bf16 v[32:35], v[80:83], v[72:75], v[32:35]
	v_mfma_f32_16x16x32_bf16 v[36:39], v[84:87], v[72:75], v[36:39]
	s_add_u32 m0, s101, 0xb000
	v_lshl_add_u64 v[210:211], v[164:165], 0, s[18:19]
	global_load_lds_dwordx4 v[210:211], off
	v_mfma_f32_16x16x32_bf16 v[40:43], v[88:91], v[72:75], v[40:43]
	v_mfma_f32_16x16x32_bf16 v[44:47], v[92:95], v[72:75], v[44:47]
	s_add_u32 m0, s101, 0xf000
	v_lshl_add_u64 v[210:211], v[166:167], 0, s[18:19]
	global_load_lds_dwordx4 v[210:211], off
	v_mfma_f32_16x16x32_bf16 v[48:51], v[80:83], v[76:79], v[48:51]
	v_mfma_f32_16x16x32_bf16 v[52:55], v[84:87], v[76:79], v[52:55]
	v_mfma_f32_16x16x32_bf16 v[56:59], v[88:91], v[76:79], v[56:59]
	v_mfma_f32_16x16x32_bf16 v[60:63], v[92:95], v[76:79], v[60:63]
	s_waitcnt vmcnt(0)
	s_waitcnt lgkmcnt(0)
	s_barrier
; #define SB_ __builtin_amdgcn_sched_barrier(0)
; template <bool SWAP, bool HALF>
; DI void gemm_mainloop(const GemmDesc& d, int m0, int n0, bf16_t* smem, f32x16 (&acc)[2][2], int dry) {
;     ...
;   auto stage = [&](int cur, u32x4 (&ran)[4], u32x4 (&rbn)[4], int ks) {
;     ldf(cur, 1, 1); SB_;
;     mma(0); SB_;
;     ldf(cur, 2, 0); SB_;
;     lw(ran, rbn, cur ^ 1);
;     gl(ran, rbn, (ks + 3 < nk) ? ks + 3 : nk - 1);
;     SB_;
;     mma(1); SB_;
;     __syncthreads();
;     ldf(cur, 3, 1); SB_;
;     mma(0); SB_;
;     ldf(cur ^ 1, 0, 0);
;     SB_;
;     mma(1); SB_;
;     __syncthreads();
;   };
;   gl(ra0, rb0, 0);
;   gl(ra1, rb1, 1);
;   lw(ra0, rb0, 0);
;   gl(ra0, rb0, 2);
;   __syncthreads();
;   ldf(0, 0, 0);
; #pragma unroll 1
;   for (int ks = 0; ks < nk; ks += 2) {
;     stage(0, ra1, rb1, ks);
;     stage(1, ra0, rb0, ks + 1);
;   }
.LBB0_192:
	ds_read_b128 v[64:67], v168 offset:32768
	ds_read_b128 v[68:71], v168 offset:34816
	ds_read_b128 v[72:75], v168 offset:36864
	ds_read_b128 v[76:79], v168 offset:38912
	ds_read_b128 v[80:83], v169 offset:32768
	ds_read_b128 v[84:87], v169 offset:34816
	ds_read_b128 v[88:91], v169 offset:36864
	ds_read_b128 v[92:95], v169 offset:38912
	s_add_i32 s4, s4, 2
	s_add_i32 s5, s4, 2
	s_min_u32 s5, s5, 15
	s_lshl_b32 s18, s5, 7
	s_add_u32 m0, s101, 0x0
	v_lshl_add_u64 v[210:211], v[152:153], 0, s[18:19]
	global_load_lds_dwordx4 v[210:211], off
	s_add_u32 m0, s101, 0x4000
	v_lshl_add_u64 v[210:211], v[154:155], 0, s[18:19]
	global_load_lds_dwordx4 v[210:211], off
	ds_read_b128 v[128:131], v220 offset:32768
	ds_read_b128 v[132:135], v220 offset:34816
	ds_read_b128 v[136:139], v220 offset:36864
	ds_read_b128 v[140:143], v220 offset:38912
	ds_read_b128 v[192:195], v221 offset:32768
	ds_read_b128 v[196:199], v221 offset:34816
	ds_read_b128 v[200:203], v221 offset:36864
	ds_read_b128 v[204:207], v221 offset:38912
	v_mfma_f32_16x16x32_bf16 v[0:3], v[112:115], v[96:99], v[0:3]
	v_mfma_f32_16x16x32_bf16 v[4:7], v[116:119], v[96:99], v[4:7]
	s_add_u32 m0, s101, 0x1000
	v_lshl_add_u64 v[210:211], v[156:157], 0, s[18:19]
	global_load_lds_dwordx4 v[210:211], off
	v_mfma_f32_16x16x32_bf16 v[8:11], v[120:123], v[96:99], v[8:11]
	v_mfma_f32_16x16x32_bf16 v[12:15], v[124:127], v[96:99], v[12:15]
	s_add_u32 m0, s101, 0x5000
	v_lshl_add_u64 v[210:211], v[158:159], 0, s[18:19]
	global_load_lds_dwordx4 v[210:211], off
	v_mfma_f32_16x16x32_bf16 v[16:19], v[112:115], v[100:103], v[16:19]
	v_mfma_f32_16x16x32_bf16 v[20:23], v[116:119], v[100:103], v[20:23]
	s_add_u32 m0, s101, 0x2000
	v_lshl_add_u64 v[210:211], v[160:161], 0, s[18:19]
	global_load_lds_dwordx4 v[210:211], off
	v_mfma_f32_16x16x32_bf16 v[24:27], v[120:123], v[100:103], v[24:27]
	v_mfma_f32_16x16x32_bf16 v[28:31], v[124:127], v[100:103], v[28:31]
	s_add_u32 m0, s101, 0x6000
	v_lshl_add_u64 v[210:211], v[162:163], 0, s[18:19]
	global_load_lds_dwordx4 v[210:211], off
	v_mfma_f32_16x16x32_bf16 v[32:35], v[112:115], v[104:107], v[32:35]
	v_mfma_f32_16x16x32_bf16 v[36:39], v[116:119], v[104:107], v[36:39]
	s_add_u32 m0, s101, 0x3000
	v_lshl_add_u64 v[210:211], v[164:165], 0, s[18:19]
	global_load_lds_dwordx4 v[210:211], off
	v_mfma_f32_16x16x32_bf16 v[40:43], v[120:123], v[104:107], v[40:43]
	v_mfma_f32_16x16x32_bf16 v[44:47], v[124:127], v[104:107], v[44:47]
	s_add_u32 m0, s101, 0x7000
	v_lshl_add_u64 v[210:211], v[166:167], 0, s[18:19]
	global_load_lds_dwordx4 v[210:211], off
	v_mfma_f32_16x16x32_bf16 v[48:51], v[112:115], v[108:111], v[48:51]
	v_mfma_f32_16x16x32_bf16 v[52:55], v[116:119], v[108:111], v[52:55]
	v_mfma_f32_16x16x32_bf16 v[56:59], v[120:123], v[108:111], v[56:59]
	v_mfma_f32_16x16x32_bf16 v[60:63], v[124:127], v[108:111], v[60:63]
	s_waitcnt lgkmcnt(8)
	v_mfma_f32_16x16x32_bf16 v[0:3], v[80:83], v[64:67], v[0:3]
	v_mfma_f32_16x16x32_bf16 v[4:7], v[84:87], v[64:67], v[4:7]
	v_mfma_f32_16x16x32_bf16 v[8:11], v[88:91], v[64:67], v[8:11]
	v_mfma_f32_16x16x32_bf16 v[12:15], v[92:95], v[64:67], v[12:15]
	v_mfma_f32_16x16x32_bf16 v[16:19], v[80:83], v[68:71], v[16:19]
	v_mfma_f32_16x16x32_bf16 v[20:23], v[84:87], v[68:71], v[20:23]
	v_mfma_f32_16x16x32_bf16 v[24:27], v[88:91], v[68:71], v[24:27]
	v_mfma_f32_16x16x32_bf16 v[28:31], v[92:95], v[68:71], v[28:31]
	v_mfma_f32_16x16x32_bf16 v[32:35], v[80:83], v[72:75], v[32:35]
	v_mfma_f32_16x16x32_bf16 v[36:39], v[84:87], v[72:75], v[36:39]
	v_mfma_f32_16x16x32_bf16 v[40:43], v[88:91], v[72:75], v[40:43]
	v_mfma_f32_16x16x32_bf16 v[44:47], v[92:95], v[72:75], v[44:47]
	v_mfma_f32_16x16x32_bf16 v[48:51], v[80:83], v[76:79], v[48:51]
	v_mfma_f32_16x16x32_bf16 v[52:55], v[84:87], v[76:79], v[52:55]
	v_mfma_f32_16x16x32_bf16 v[56:59], v[88:91], v[76:79], v[56:59]
	v_mfma_f32_16x16x32_bf16 v[60:63], v[92:95], v[76:79], v[60:63]
	s_waitcnt vmcnt(0)
	s_waitcnt lgkmcnt(0)
	s_barrier
	ds_read_b128 v[64:67], v168 offset:0
	ds_read_b128 v[68:71], v168 offset:2048
	ds_read_b128 v[72:75], v168 offset:4096
	ds_read_b128 v[76:79], v168 offset:6144
	ds_read_b128 v[80:83], v169 offset:0
	ds_read_b128 v[84:87], v169 offset:2048
	ds_read_b128 v[88:91], v169 offset:4096
	ds_read_b128 v[92:95], v169 offset:6144
	s_add_i32 s5, s4, 3
	s_min_u32 s5, s5, 15
	s_lshl_b32 s18, s5, 7
	s_add_u32 m0, s101, 0x8000
	v_lshl_add_u64 v[210:211], v[152:153], 0, s[18:19]
	global_load_lds_dwordx4 v[210:211], off
	s_add_u32 m0, s101, 0xc000
	v_lshl_add_u64 v[210:211], v[154:155], 0, s[18:19]
	global_load_lds_dwordx4 v[210:211], off
	ds_read_b128 v[96:99], v220 offset:0
	ds_read_b128 v[100:103], v220 offset:2048
	ds_read_b128 v[104:107], v220 offset:4096
	ds_read_b128 v[108:111], v220 offset:6144
	ds_read_b128 v[112:115], v221 offset:0
	ds_read_b128 v[116:119], v221 offset:2048
	ds_read_b128 v[120:123], v221 offset:4096
	ds_read_b128 v[124:127], v221 offset:6144
	v_mfma_f32_16x16x32_bf16 v[0:3], v[192:195], v[128:131], v[0:3]
	v_mfma_f32_16x16x32_bf16 v[4:7], v[196:199], v[128:131], v[4:7]
	s_add_u32 m0, s101, 0x9000
	v_lshl_add_u64 v[210:211], v[156:157], 0, s[18:19]
	global_load_lds_dwordx4 v[210:211], off
	v_mfma_f32_16x16x32_bf16 v[8:11], v[200:203], v[128:131], v[8:11]
	v_mfma_f32_16x16x32_bf16 v[12:15], v[204:207], v[128:131], v[12:15]
	s_add_u32 m0, s101, 0xd000
	v_lshl_add_u64 v[210:211], v[158:159], 0, s[18:19]
	global_load_lds_dwordx4 v[210:211], off
	v_mfma_f32_16x16x32_bf16 v[16:19], v[192:195], v[132:135], v[16:19]
	v_mfma_f32_16x16x32_bf16 v[20:23], v[196:199], v[132:135], v[20:23]
	s_add_u32 m0, s101, 0xa000
	v_lshl_add_u64 v[210:211], v[160:161], 0, s[18:19]
	global_load_lds_dwordx4 v[210:211], off
	v_mfma_f32_16x16x32_bf16 v[24:27], v[200:203], v[132:135], v[24:27]
	v_mfma_f32_16x16x32_bf16 v[28:31], v[204:207], v[132:135], v[28:31]
	s_add_u32 m0, s101, 0xe000
	v_lshl_add_u64 v[210:211], v[162:163], 0, s[18:19]
	global_load_lds_dwordx4 v[210:211], off
	v_mfma_f32_16x16x32_bf16 v[32:35], v[192:195], v[136:139], v[32:35]
	v_mfma_f32_16x16x32_bf16 v[36:39], v[196:199], v[136:139], v[36:39]
	s_add_u32 m0, s101, 0xb000
	v_lshl_add_u64 v[210:211], v[164:165], 0, s[18:19]
	global_load_lds_dwordx4 v[210:211], off
	v_mfma_f32_16x16x32_bf16 v[40:43], v[200:203], v[136:139], v[40:43]
	v_mfma_f32_16x16x32_bf16 v[44:47], v[204:207], v[136:139], v[44:47]
	s_add_u32 m0, s101, 0xf000
	v_lshl_add_u64 v[210:211], v[166:167], 0, s[18:19]
	global_load_lds_dwordx4 v[210:211], off
	v_mfma_f32_16x16x32_bf16 v[48:51], v[192:195], v[140:143], v[48:51]
	v_mfma_f32_16x16x32_bf16 v[52:55], v[196:199], v[140:143], v[52:55]
	v_mfma_f32_16x16x32_bf16 v[56:59], v[200:203], v[140:143], v[56:59]
	v_mfma_f32_16x16x32_bf16 v[60:63], v[204:207], v[140:143], v[60:63]
	s_waitcnt lgkmcnt(8)
; DI float ssq_f(u64 v) { return (float)v * (1.f / 1048576.f); }
; #define SB_ __builtin_amdgcn_sched_barrier(0)
; template <bool SWAP, bool HALF>
; DI void gemm_mainloop(const GemmDesc& d, int m0, int n0, bf16_t* smem, f32x16 (&acc)[2][2], int dry) {
;     ...
;   auto stage = [&](int cur, u32x4 (&ran)[4], u32x4 (&rbn)[4], int ks) {
;     ldf(cur, 1, 1); SB_;
;     mma(0); SB_;
;     ldf(cur, 2, 0); SB_;
;     lw(ran, rbn, cur ^ 1);
;     gl(ran, rbn, (ks + 3 < nk) ? ks + 3 : nk - 1);
;     SB_;
;     mma(1); SB_;
;     __syncthreads();
;     ldf(cur, 3, 1); SB_;
;     mma(0); SB_;
;     ldf(cur ^ 1, 0, 0);
;     SB_;
;     mma(1); SB_;
;     __syncthreads();
;   };
;   gl(ra0, rb0, 0);
;   gl(ra1, rb1, 1);
;   lw(ra0, rb0, 0);
;   gl(ra0, rb0, 2);
;   __syncthreads();
;   ldf(0, 0, 0);
; #pragma unroll 1
;   for (int ks = 0; ks < nk; ks += 2) {
;     stage(0, ra1, rb1, ks);
;     stage(1, ra0, rb0, ks + 1);
;   }
; DI void gemm_tile(const GemmDesc& d, int m0, int n0, bf16_t* smem, int dry) {
;     ...
;   } else if (t < 128) {
;     rs_s[t] = rsqrtf(ssq_f(myss) * d.inv_dim + EPS);
;   }
	v_mfma_f32_16x16x32_bf16 v[0:3], v[80:83], v[64:67], v[0:3]
	v_mfma_f32_16x16x32_bf16 v[4:7], v[84:87], v[64:67], v[4:7]
	v_mfma_f32_16x16x32_bf16 v[8:11], v[88:91], v[64:67], v[8:11]
	v_mfma_f32_16x16x32_bf16 v[12:15], v[92:95], v[64:67], v[12:15]
	v_mfma_f32_16x16x32_bf16 v[16:19], v[80:83], v[68:71], v[16:19]
	v_mfma_f32_16x16x32_bf16 v[20:23], v[84:87], v[68:71], v[20:23]
	v_mfma_f32_16x16x32_bf16 v[24:27], v[88:91], v[68:71], v[24:27]
	v_mfma_f32_16x16x32_bf16 v[28:31], v[92:95], v[68:71], v[28:31]
	v_mfma_f32_16x16x32_bf16 v[32:35], v[80:83], v[72:75], v[32:35]
	v_mfma_f32_16x16x32_bf16 v[36:39], v[84:87], v[72:75], v[36:39]
	v_mfma_f32_16x16x32_bf16 v[40:43], v[88:91], v[72:75], v[40:43]
	v_mfma_f32_16x16x32_bf16 v[44:47], v[92:95], v[72:75], v[44:47]
	v_mfma_f32_16x16x32_bf16 v[48:51], v[80:83], v[76:79], v[48:51]
	v_mfma_f32_16x16x32_bf16 v[52:55], v[84:87], v[76:79], v[52:55]
	v_mfma_f32_16x16x32_bf16 v[56:59], v[88:91], v[76:79], v[56:59]
	v_mfma_f32_16x16x32_bf16 v[60:63], v[92:95], v[76:79], v[60:63]
	s_cmp_lt_u32 s4, 12
	s_waitcnt vmcnt(0)
	s_waitcnt lgkmcnt(0)
	s_barrier
	s_cbranch_scc1 .LBB0_192
	ds_read_b128 v[64:67], v168 offset:32768
	ds_read_b128 v[68:71], v168 offset:34816
	ds_read_b128 v[72:75], v168 offset:36864
	ds_read_b128 v[76:79], v168 offset:38912
	ds_read_b128 v[80:83], v169 offset:32768
	ds_read_b128 v[84:87], v169 offset:34816
	ds_read_b128 v[88:91], v169 offset:36864
	ds_read_b128 v[92:95], v169 offset:38912
	ds_read_b128 v[128:131], v220 offset:32768
	ds_read_b128 v[132:135], v220 offset:34816
	ds_read_b128 v[136:139], v220 offset:36864
	ds_read_b128 v[140:143], v220 offset:38912
	ds_read_b128 v[192:195], v221 offset:32768
	ds_read_b128 v[196:199], v221 offset:34816
	ds_read_b128 v[200:203], v221 offset:36864
	ds_read_b128 v[204:207], v221 offset:38912
	v_mfma_f32_16x16x32_bf16 v[0:3], v[112:115], v[96:99], v[0:3]
	v_mfma_f32_16x16x32_bf16 v[4:7], v[116:119], v[96:99], v[4:7]
	v_mfma_f32_16x16x32_bf16 v[8:11], v[120:123], v[96:99], v[8:11]
	v_mfma_f32_16x16x32_bf16 v[12:15], v[124:127], v[96:99], v[12:15]
	v_mfma_f32_16x16x32_bf16 v[16:19], v[112:115], v[100:103], v[16:19]
	v_mfma_f32_16x16x32_bf16 v[20:23], v[116:119], v[100:103], v[20:23]
	v_mfma_f32_16x16x32_bf16 v[24:27], v[120:123], v[100:103], v[24:27]
	v_mfma_f32_16x16x32_bf16 v[28:31], v[124:127], v[100:103], v[28:31]
	v_mfma_f32_16x16x32_bf16 v[32:35], v[112:115], v[104:107], v[32:35]
	v_mfma_f32_16x16x32_bf16 v[36:39], v[116:119], v[104:107], v[36:39]
	v_mfma_f32_16x16x32_bf16 v[40:43], v[120:123], v[104:107], v[40:43]
	v_mfma_f32_16x16x32_bf16 v[44:47], v[124:127], v[104:107], v[44:47]
	v_mfma_f32_16x16x32_bf16 v[48:51], v[112:115], v[108:111], v[48:51]
	v_mfma_f32_16x16x32_bf16 v[52:55], v[116:119], v[108:111], v[52:55]
	v_mfma_f32_16x16x32_bf16 v[56:59], v[120:123], v[108:111], v[56:59]
	v_mfma_f32_16x16x32_bf16 v[60:63], v[124:127], v[108:111], v[60:63]
	s_waitcnt lgkmcnt(8)
	v_mfma_f32_16x16x32_bf16 v[0:3], v[80:83], v[64:67], v[0:3]
	v_mfma_f32_16x16x32_bf16 v[4:7], v[84:87], v[64:67], v[4:7]
	v_mfma_f32_16x16x32_bf16 v[8:11], v[88:91], v[64:67], v[8:11]
	v_mfma_f32_16x16x32_bf16 v[12:15], v[92:95], v[64:67], v[12:15]
	v_mfma_f32_16x16x32_bf16 v[16:19], v[80:83], v[68:71], v[16:19]
	v_mfma_f32_16x16x32_bf16 v[20:23], v[84:87], v[68:71], v[20:23]
	v_mfma_f32_16x16x32_bf16 v[24:27], v[88:91], v[68:71], v[24:27]
	v_mfma_f32_16x16x32_bf16 v[28:31], v[92:95], v[68:71], v[28:31]
	v_mfma_f32_16x16x32_bf16 v[32:35], v[80:83], v[72:75], v[32:35]
	v_mfma_f32_16x16x32_bf16 v[36:39], v[84:87], v[72:75], v[36:39]
	v_mfma_f32_16x16x32_bf16 v[40:43], v[88:91], v[72:75], v[40:43]
	v_mfma_f32_16x16x32_bf16 v[44:47], v[92:95], v[72:75], v[44:47]
	v_mfma_f32_16x16x32_bf16 v[48:51], v[80:83], v[76:79], v[48:51]
	v_mfma_f32_16x16x32_bf16 v[52:55], v[84:87], v[76:79], v[52:55]
	v_mfma_f32_16x16x32_bf16 v[56:59], v[88:91], v[76:79], v[56:59]
	v_mfma_f32_16x16x32_bf16 v[60:63], v[92:95], v[76:79], v[60:63]
	s_waitcnt lgkmcnt(0)
	s_barrier
	v_mfma_f32_16x16x32_bf16 v[0:3], v[192:195], v[128:131], v[0:3]
	v_mfma_f32_16x16x32_bf16 v[4:7], v[196:199], v[128:131], v[4:7]
	v_mfma_f32_16x16x32_bf16 v[8:11], v[200:203], v[128:131], v[8:11]
	v_mfma_f32_16x16x32_bf16 v[12:15], v[204:207], v[128:131], v[12:15]
	v_mfma_f32_16x16x32_bf16 v[16:19], v[192:195], v[132:135], v[16:19]
	v_mfma_f32_16x16x32_bf16 v[20:23], v[196:199], v[132:135], v[20:23]
	v_mfma_f32_16x16x32_bf16 v[24:27], v[200:203], v[132:135], v[24:27]
	v_mfma_f32_16x16x32_bf16 v[28:31], v[204:207], v[132:135], v[28:31]
	v_mfma_f32_16x16x32_bf16 v[32:35], v[192:195], v[136:139], v[32:35]
	v_mfma_f32_16x16x32_bf16 v[36:39], v[196:199], v[136:139], v[36:39]
	v_mfma_f32_16x16x32_bf16 v[40:43], v[200:203], v[136:139], v[40:43]
	v_mfma_f32_16x16x32_bf16 v[44:47], v[204:207], v[136:139], v[44:47]
	v_mfma_f32_16x16x32_bf16 v[48:51], v[192:195], v[140:143], v[48:51]
	v_mfma_f32_16x16x32_bf16 v[52:55], v[196:199], v[140:143], v[52:55]
	v_mfma_f32_16x16x32_bf16 v[56:59], v[200:203], v[140:143], v[56:59]
	v_mfma_f32_16x16x32_bf16 v[60:63], v[204:207], v[140:143], v[60:63]
	s_and_saveexec_b64 s[4:5], s[42:43]
	s_cbranch_execz .LBB0_195
	s_mov_b32 s8, 0x800000
	s_waitcnt vmcnt(15)
	v_mul_f32_e32 v64, 0x4b800000, v171
	v_cmp_gt_f32_e32 vcc, s8, v171
	v_lshl_add_u32 v65, v150, 2, v181
	s_nop 0
	v_cndmask_b32_e32 v64, v171, v64, vcc
	v_rsq_f32_e32 v64, v64
	s_nop 0
	v_mul_f32_e32 v66, 0x45800000, v64
	v_cndmask_b32_e32 v64, v64, v66, vcc
	ds_write_b32 v65, v64
; DI void gemm_tile(const GemmDesc& d, int m0, int n0, bf16_t* smem, int dry) {
;     ...
; #pragma unroll
;     for (int a = 0; a < 2; ++a)
; #pragma unroll
;       for (int b = 0; b < 2; ++b)
; #pragma unroll
;         for (int g = 0; g < 4; ++g) {
;           f32x4 o;
; #pragma unroll
;           for (int j = 0; j < 4; ++j) o[j] = acc[a][b][4 * g + j];
;           *(f32x4*)(Ct + (wm * 64 + a * 32 + r) * CS + wn * 64 + b * 32 + 8 * g + 4 * hh) = o;
;         }
;   }
;   __syncthreads();
;     ...
;   } else if (n0 < d.n1end) {
;     bf16_t* dst; int ld, nb;
;     if (n0 < d.n0end) { dst = d.d0; ld = d.ld0; nb = n0; } else { dst = d.d1; ld = d.ld1; nb = n0 - d.n0end; }
;     unsigned* kq = (d.kmax && n0 >= d.n0end) ? d.kmax : nullptr;
;     const int mlast = (m0 + 127) < M ? (m0 + 127) : M - 1;
;     const bool onebatch = (m0 / L) == (mlast / L);
;     float kmx = 0.f;
;     u64* sq = nullptr;
;     if (d.ssq_a) { if (n0 < d.ssq_a_end) sq = d.ssq_a; else if (n0 < d.ssq_b_end) sq = d.ssq_b; }
; #pragma unroll 4
;     for (int pass = 0; pass < 16; ++pass) {
;       const int row = pass * 8 + (t >> 5), c4 = t & 31, m = m0 + row;
;       float part = 0.f, kpart = 0.f;
.LBB0_195:
	s_or_b64 exec, exec, s[4:5]
	s_waitcnt vmcnt(15)
	v_lshlrev_b32_e32 v64, 4, v189
	v_lshl_or_b32 v65, v187, 6, v170
	v_lshl_or_b32 v64, v188, 8, v64
	v_mad_u64_u32 v[64:65], s[4:5], v65, s22, v[64:65]
	s_cmp_lt_i32 s7, 16
	s_mov_b64 s[4:5], -1
	v_and_b32_e32 v212, 15, v172
	v_lshrrev_b32_e32 v213, 1, v172
	v_and_or_b32 v212, v213, s72, v212
	v_lshlrev_b32_e32 v213, 2, v172
	v_and_b32_e32 v214, 0x30, v172
	v_and_b32_e32 v213, 0x100, v213
	v_or_b32_e32 v213, v213, v214
	v_mad_u32_u24 v64, v212, s22, v213
	ds_write_b128 v64, v[0:3]
	ds_write_b128 v64, v[4:7] offset:64
	ds_write_b128 v64, v[8:11] offset:128
	ds_write_b128 v64, v[12:15] offset:192
	ds_write_b128 v64, v[16:19] offset:8448
	ds_write_b128 v64, v[20:23] offset:8512
	ds_write_b128 v64, v[24:27] offset:8576
	ds_write_b128 v64, v[28:31] offset:8640
	ds_write_b128 v64, v[32:35] offset:16896
	ds_write_b128 v64, v[36:39] offset:16960
	ds_write_b128 v64, v[40:43] offset:17024
	ds_write_b128 v64, v[44:47] offset:17088
	ds_write_b128 v64, v[48:51] offset:25344
	ds_write_b128 v64, v[52:55] offset:25408
	ds_write_b128 v64, v[56:59] offset:25472
	ds_write_b128 v64, v[60:63] offset:25536
	s_waitcnt lgkmcnt(0)
	s_barrier
	s_cbranch_scc0 .LBB0_253
	s_lshl_b32 s16, s6, 13
	s_cmp_gt_i32 s7, 7
	s_cselect_b64 s[8:9], -1, 0
	s_and_b64 s[4:5], s[8:9], exec
	v_readlane_b32 s6, v228, 29
	s_cselect_b32 s4, 0xfffffc00, 0
	s_cselect_b32 s7, s6, 0
	v_readlane_b32 s6, v228, 30
	s_cselect_b32 s5, 0x4020000, 0
	s_cselect_b32 s10, s6, 0
	s_add_i32 s6, s4, s33
	s_add_u32 s17, s68, s5
	s_addc_u32 s39, s69, 0
	s_min_i32 s4, s25, 0x7fc0
	s_addk_i32 s4, 0x7f
	s_mul_hi_i32 s5, s25, 0x7fc01ff1
	s_mul_hi_i32 s4, s4, 0x7fc01ff1
	v_mov_b32_e32 v2, s7
	s_lshr_b32 s7, s5, 31
	s_ashr_i32 s37, s5, 12
	s_lshr_b32 s5, s4, 31
	s_ashr_i32 s4, s4, 12
	s_add_i32 s37, s37, s7
	s_add_i32 s4, s4, s5
	s_cmp_eq_u32 s37, s4
	v_mov_b32_e32 v3, s10
	s_cselect_b64 s[10:11], -1, 0
	s_cmp_lg_u32 s37, s4
	s_cselect_b64 s[12:13], -1, 0
	s_ashr_i32 s7, s6, 31
	v_and_b32_e32 v4, 15, v150
	s_lshl_b64 s[4:5], s[6:7], 1
	v_cmp_eq_u32_e64 s[44:45], 0, v4
	v_lshl_or_b32 v4, v170, 2, s6
	s_add_u32 s4, s17, s4
	v_ashrrev_i32_e32 v4, 6, v4
	v_ashrrev_i32_e32 v6, 5, v150
	s_addc_u32 s5, s39, s5
	v_lshlrev_b32_e32 v144, 3, v170
	v_ashrrev_i32_e32 v5, 31, v4
	v_lshl_add_u64 v[0:1], s[4:5], 0, v[144:145]
	v_lshl_add_u64 v[2:3], v[4:5], 2, v[2:3]
	v_mul_lo_u32 v4, v6, s22
	s_add_i32 s4, s1, s14
	s_lshl_b32 s1, s1, 10
	v_lshl_add_u32 v9, v170, 4, v4
	v_add_u32_e32 v4, s29, v6
	s_sub_i32 s4, s4, s15
	s_add_i32 s1, s1, s16
	v_lshl_add_u32 v11, s4, 10, v4
	v_add_u32_e32 v4, s1, v4
	s_lshl_b32 s1, s15, 10
	s_mov_b32 s18, 0
	v_readlane_b32 s39, v223, 29
	v_lshlrev_b32_e32 v10, 2, v6
	v_subrev_u32_e32 v12, s1, v4
	v_mov_b32_e32 v8, 0
	s_branch .LBB0_198

; DI int otid() { int t = threadIdx.x; asm volatile("" : "+v"(t)); return t; }
; template <bool SWAP, bool HALF>
; DI void gemm_mainloop(const GemmDesc& d, int m0, int n0, bf16_t* smem, f32x16 (&acc)[2][2], int dry) {
;   const int t = otid(), lane = t & 63, w = t >> 6, wm = w >> 1, wn = w & 1, r = lane & 31, hh = lane >> 5;
;   const int lrow = t >> 3, lkc = t & 7;
;   const bf16_t* ap[4]; const bf16_t* bp[4];
; #pragma unroll
;   for (int i = 0; i < 4; ++i) {
;     int am = m0 + lrow + 32 * i; am = am < M ? am : M - 1;
;     ap[i] = d.A + (size_t)am * d.lda + lkc * 8 + (d.a_grp ? (n0 / d.a_grp) * d.a_grp : 0);
;     bp[i] = d.Bt + (size_t)(n0 + lrow + 32 * i) * d.ldb + lkc * 8;
;     ...
;     const int g = i / (8 * nN), j = i - g * 8 * nN;
;     const int gm = (cx - g * 8) < 8 ? (cx - g * 8) : 8;
;     const int mt = (g * 8 + j % gm) * 8 + x, nt = j / gm;
;     gemm_tile(d, mt * 128, nt * 128, smem, dry);
.LBB0_500:
	s_lshr_b32 s1, s8, 3
	s_and_b32 s1, s1, 0xffffff8
	v_readlane_b32 s5, v228, 38
	s_sub_i32 s5, s5, s1
	s_min_i32 s5, s5, 8
	s_abs_i32 s9, s5
	v_cvt_f32_u32_e32 v0, s9
	s_sub_i32 s10, 0, s9
	s_lshl_b32 s4, s1, 3
	s_sub_i32 s4, s8, s4
	v_rcp_iflag_f32_e32 v0, v0
	s_abs_i32 s7, s4
	s_xor_b32 s6, s4, s5
	s_ashr_i32 s6, s6, 31
	v_mul_f32_e32 v0, 0x4f7ffffe, v0
	v_cvt_u32_f32_e32 v0, v0
	v_mov_b32_e32 v150, v172
	v_mov_b32_e32 v32, v172
	v_readfirstlane_b32 s11, v0
	s_mul_i32 s10, s10, s11
	s_mul_hi_u32 s10, s11, s10
	s_add_i32 s11, s11, s10
	s_mul_hi_u32 s10, s7, s11
	s_mul_i32 s11, s10, s9
	s_sub_i32 s7, s7, s11
	s_add_i32 s11, s10, 1
	s_sub_i32 s12, s7, s9
	s_cmp_ge_u32 s7, s9
	s_cselect_b32 s10, s11, s10
	s_cselect_b32 s7, s12, s7
	s_add_i32 s11, s10, 1
	s_cmp_ge_u32 s7, s9
	s_cselect_b32 s7, s11, s10
	s_xor_b32 s7, s7, s6
	s_sub_i32 s6, s7, s6
	s_mul_i32 s5, s6, s5
	s_sub_i32 s4, s4, s5
	s_add_i32 s1, s1, s4
	s_lshl_b32 s4, s6, 7
	s_lshl_b32 s1, s1, 10
	v_ashrrev_i32_e32 v10, 3, v32
	v_lshlrev_b32_e32 v0, 3, v32
	v_and_b32_e32 v33, 56, v0
	v_add_u32_e32 v2, s4, v10
	v_readlane_b32 s44, v228, 56
	s_or_b32 s9, s1, s29
	v_lshlrev_b32_e32 v144, 1, v33
	v_readlane_b32 s45, v228, 57
	v_ashrrev_i32_e32 v3, 31, v2
	v_add_u32_e32 v11, s9, v10
	v_lshl_add_u64 v[4:5], s[44:45], 0, v[144:145]
	v_lshlrev_b64 v[2:3], 11, v[2:3]
	v_lshl_add_u64 v[154:155], v[4:5], 0, v[2:3]
	v_min_i32_e32 v2, 0x801f, v11
	v_ashrrev_i32_e32 v3, 31, v2
	v_lshl_add_u64 v[0:1], s[68:69], 0, v[144:145]
	v_lshlrev_b64 v[2:3], 11, v[2:3]
	v_lshl_add_u64 v[8:9], v[0:1], 0, v[2:3]
	v_min_i32_e32 v2, 0x7fff, v11
	v_ashrrev_i32_e32 v3, 31, v2
	v_min_i32_e32 v6, 0x803f, v11
	v_lshlrev_b64 v[2:3], 11, v[2:3]
	v_ashrrev_i32_e32 v7, 31, v6
	v_lshl_add_u64 v[16:17], v[0:1], 0, v[2:3]
	v_min_i32_e32 v2, 0x7fdf, v11
	v_lshlrev_b64 v[6:7], 11, v[6:7]
	v_ashrrev_i32_e32 v3, 31, v2
	v_lshl_add_u64 v[152:153], v[0:1], 0, v[6:7]
	v_lshlrev_b64 v[2:3], 11, v[2:3]
	v_lshl_add_u64 v[24:25], v[0:1], 0, v[2:3]
	s_mov_b64 s[6:7], 0x10000
	v_lshl_add_u64 v[156:157], v[8:9], 0, s[6:7]
	v_lshl_add_u64 v[158:159], v[154:155], 0, s[6:7]
	s_mov_b64 s[6:7], 0x20000
	v_lshl_add_u64 v[160:161], v[16:17], 0, s[6:7]
	v_lshl_add_u64 v[162:163], v[154:155], 0, s[6:7]
	s_mov_b64 s[6:7], 0x30000
	s_movk_i32 s1, 0x48
	v_lshl_add_u64 v[164:165], v[24:25], 0, s[6:7]
	v_lshl_add_u64 v[166:167], v[154:155], 0, s[6:7]
	v_and_b32_e32 v34, 31, v32
	v_mul_lo_u32 v35, v10, s1
	v_readlane_b32 s46, v228, 58
	v_readlane_b32 s47, v228, 59
	s_mov_b32 s1, 0x10000
	v_add_co_u32_e32 v8, vcc, s1, v8
	s_nop 1
	v_addc_co_u32_e32 v9, vcc, 0, v9, vcc
	s_waitcnt vmcnt(19)
	v_add_co_u32_e32 v12, vcc, s1, v154
	s_nop 1
	v_addc_co_u32_e32 v13, vcc, 0, v155, vcc
	s_mov_b32 s1, 0x20000
	v_add_co_u32_e32 v16, vcc, s1, v16
	s_nop 1
	v_addc_co_u32_e32 v17, vcc, 0, v17, vcc
	v_add_co_u32_e32 v20, vcc, s1, v154
	s_nop 1
	v_addc_co_u32_e32 v21, vcc, 0, v155, vcc
	s_mov_b32 s1, 0x30000
	v_add_co_u32_e32 v24, vcc, s1, v24
	s_nop 1
	v_addc_co_u32_e32 v25, vcc, 0, v25, vcc
	v_add_co_u32_e32 v28, vcc, s1, v154
	s_nop 1
	v_addc_co_u32_e32 v29, vcc, 0, v155, vcc
	s_nop 0
	v_add_lshl_u32 v144, v35, v33, 1
	s_waitcnt vmcnt(15)
	s_waitcnt vmcnt(14)
	s_waitcnt vmcnt(13)
	s_waitcnt vmcnt(12)
	s_waitcnt vmcnt(11)
	s_waitcnt vmcnt(10)
	s_waitcnt vmcnt(9)
	s_waitcnt vmcnt(8)
	v_lshrrev_b32_e32 v0, 1, v32
	v_and_or_b32 v1, v0, s72, v34
	v_and_b32_e32 v0, 16, v0
	s_movk_i32 s1, 0x90
	v_mad_u64_u32 v[168:169], s[6:7], v1, s1, v[0:1]
	v_and_b32_e32 v1, 0x5f, v32
	v_mul_u32_u24_e32 v1, 0x48, v1
	v_lshl_add_u32 v169, v1, 1, v0
	v_bfe_u32 v212, v172, 4, 3
	v_lshlrev_b32_e32 v212, 4, v212
	v_xor_b32_e32 v152, v152, v212
	v_xor_b32_e32 v154, v154, v212
	v_xor_b32_e32 v156, v156, v212
	v_xor_b32_e32 v158, v158, v212
	v_xor_b32_e32 v160, v160, v212
	v_xor_b32_e32 v162, v162, v212
	v_xor_b32_e32 v164, v164, v212
	v_xor_b32_e32 v166, v166, v212
	v_lshrrev_b32_e32 v213, 6, v172
	s_nop 1
	v_readfirstlane_b32 s101, v213
	s_lshl_b32 s101, s101, 10
	s_add_u32 m0, s101, 0x0
	s_nop 0
	global_load_lds_dwordx4 v[152:153], off
	s_add_u32 m0, s101, 0x4000
	s_nop 0
	global_load_lds_dwordx4 v[154:155], off
	s_add_u32 m0, s101, 0x1000
	s_nop 0
	global_load_lds_dwordx4 v[156:157], off
	s_add_u32 m0, s101, 0x5000
	s_nop 0
	global_load_lds_dwordx4 v[158:159], off
	s_add_u32 m0, s101, 0x2000
	s_nop 0
	global_load_lds_dwordx4 v[160:161], off
	s_add_u32 m0, s101, 0x6000
	s_nop 0
	global_load_lds_dwordx4 v[162:163], off
	s_add_u32 m0, s101, 0x3000
	s_nop 0
	global_load_lds_dwordx4 v[164:165], off
	s_add_u32 m0, s101, 0x7000
	s_nop 0
	global_load_lds_dwordx4 v[166:167], off
	v_and_b32_e32 v212, 15, v172
	v_bfe_u32 v213, v172, 4, 2
	v_lshrrev_b32_e32 v214, 1, v212
	v_xor_b32_e32 v213, v213, v214
	v_lshlrev_b32_e32 v213, 4, v213
	v_lshl_or_b32 v212, v212, 7, v213
	v_lshrrev_b32_e32 v214, 7, v172
	v_lshl_add_u32 v168, v214, 13, v212
	v_bfe_u32 v214, v172, 6, 1
	v_lshl_add_u32 v169, v214, 13, v212
	v_add_u32_e32 v169, 0x4000, v169
	v_xor_b32_e32 v220, 64, v168
	v_xor_b32_e32 v221, 64, v169
	s_waitcnt vmcnt(0)
	s_waitcnt lgkmcnt(0)
	s_barrier
; #define SB_ __builtin_amdgcn_sched_barrier(0)
; template <bool SWAP, bool HALF>
; DI void gemm_mainloop(const GemmDesc& d, int m0, int n0, bf16_t* smem, f32x16 (&acc)[2][2], int dry) {
;     ...
; #pragma unroll
;   for (int a = 0; a < 2; ++a)
; #pragma unroll
;     for (int b = 0; b < 2; ++b)
; #pragma unroll
;       for (int i = 0; i < 16; ++i) acc[a][b][i] = 0.f;
;     ...
;   auto stage = [&](int cur, u32x4 (&ran)[4], u32x4 (&rbn)[4], int ks) {
;     ldf(cur, 1, 1); SB_;
;     mma(0); SB_;
;     ldf(cur, 2, 0); SB_;
;     lw(ran, rbn, cur ^ 1);
;     gl(ran, rbn, (ks + 3 < nk) ? ks + 3 : nk - 1);
;     SB_;
;     mma(1); SB_;
;     __syncthreads();
;     ldf(cur, 3, 1); SB_;
;     mma(0); SB_;
;     ldf(cur ^ 1, 0, 0);
;     SB_;
;     mma(1); SB_;
;     __syncthreads();
;   };
	v_mov_b32_e32 v0, 0
	v_add_u32_e32 v170, 0x9000, v144
	s_mov_b32 s1, -2
	v_mov_b32_e32 v1, v0
	v_mov_b32_e32 v2, v0
	v_mov_b32_e32 v3, v0
	v_mov_b32_e32 v4, v0
	v_mov_b32_e32 v5, v0
	v_mov_b32_e32 v6, v0
	v_mov_b32_e32 v7, v0
	v_mov_b32_e32 v8, v0
	v_mov_b32_e32 v9, v0
	v_mov_b32_e32 v10, v0
	v_mov_b32_e32 v11, v0
	v_mov_b32_e32 v12, v0
	v_mov_b32_e32 v13, v0
	v_mov_b32_e32 v14, v0
	v_mov_b32_e32 v15, v0
	v_mov_b32_e32 v16, v0
	v_mov_b32_e32 v17, v0
	v_mov_b32_e32 v18, v0
	v_mov_b32_e32 v19, v0
	v_mov_b32_e32 v20, v0
	v_mov_b32_e32 v21, v0
	v_mov_b32_e32 v22, v0
	v_mov_b32_e32 v23, v0
	v_mov_b32_e32 v24, v0
	v_mov_b32_e32 v25, v0
	v_mov_b32_e32 v26, v0
	v_mov_b32_e32 v27, v0
	v_mov_b32_e32 v28, v0
	v_mov_b32_e32 v29, v0
	v_mov_b32_e32 v30, v0
	v_mov_b32_e32 v31, v0
	v_mov_b32_e32 v32, v0
	v_mov_b32_e32 v33, v0
	v_mov_b32_e32 v34, v0
	v_mov_b32_e32 v35, v0
	v_mov_b32_e32 v36, v0
	v_mov_b32_e32 v37, v0
	v_mov_b32_e32 v38, v0
	v_mov_b32_e32 v39, v0
	v_mov_b32_e32 v40, v0
	v_mov_b32_e32 v41, v0
	v_mov_b32_e32 v42, v0
	v_mov_b32_e32 v43, v0
	v_mov_b32_e32 v44, v0
	v_mov_b32_e32 v45, v0
	v_mov_b32_e32 v46, v0
	v_mov_b32_e32 v47, v0
	v_mov_b32_e32 v48, v0
	v_mov_b32_e32 v49, v0
	v_mov_b32_e32 v50, v0
	v_mov_b32_e32 v51, v0
	v_mov_b32_e32 v52, v0
	v_mov_b32_e32 v53, v0
	v_mov_b32_e32 v54, v0
	v_mov_b32_e32 v55, v0
	v_mov_b32_e32 v56, v0
	v_mov_b32_e32 v57, v0
	v_mov_b32_e32 v58, v0
	v_mov_b32_e32 v59, v0
	v_mov_b32_e32 v60, v0
	v_mov_b32_e32 v61, v0
	v_mov_b32_e32 v62, v0
	v_mov_b32_e32 v63, v0
	ds_read_b128 v[64:67], v168 offset:0
	ds_read_b128 v[68:71], v168 offset:2048
	ds_read_b128 v[72:75], v168 offset:4096
	ds_read_b128 v[76:79], v168 offset:6144
	ds_read_b128 v[80:83], v169 offset:0
	ds_read_b128 v[84:87], v169 offset:2048
	ds_read_b128 v[88:91], v169 offset:4096
	ds_read_b128 v[92:95], v169 offset:6144
	s_add_i32 s5, s1, 3
	s_min_u32 s5, s5, 15
	s_lshl_b32 s18, s5, 7
	s_add_u32 m0, s101, 0x8000
	v_lshl_add_u64 v[210:211], v[152:153], 0, s[18:19]
	global_load_lds_dwordx4 v[210:211], off
	s_add_u32 m0, s101, 0xc000
	v_lshl_add_u64 v[210:211], v[154:155], 0, s[18:19]
	global_load_lds_dwordx4 v[210:211], off
	ds_read_b128 v[96:99], v220 offset:0
	ds_read_b128 v[100:103], v220 offset:2048
	ds_read_b128 v[104:107], v220 offset:4096
	ds_read_b128 v[108:111], v220 offset:6144
	ds_read_b128 v[112:115], v221 offset:0
	ds_read_b128 v[116:119], v221 offset:2048
	ds_read_b128 v[120:123], v221 offset:4096
	ds_read_b128 v[124:127], v221 offset:6144
	s_waitcnt lgkmcnt(8)
	v_mfma_f32_16x16x32_bf16 v[0:3], v[80:83], v[64:67], v[0:3]
	v_mfma_f32_16x16x32_bf16 v[4:7], v[84:87], v[64:67], v[4:7]
	s_add_u32 m0, s101, 0x9000
	v_lshl_add_u64 v[210:211], v[156:157], 0, s[18:19]
	global_load_lds_dwordx4 v[210:211], off
	v_mfma_f32_16x16x32_bf16 v[8:11], v[88:91], v[64:67], v[8:11]
	v_mfma_f32_16x16x32_bf16 v[12:15], v[92:95], v[64:67], v[12:15]
	s_add_u32 m0, s101, 0xd000
	v_lshl_add_u64 v[210:211], v[158:159], 0, s[18:19]
	global_load_lds_dwordx4 v[210:211], off
	v_mfma_f32_16x16x32_bf16 v[16:19], v[80:83], v[68:71], v[16:19]
	v_mfma_f32_16x16x32_bf16 v[20:23], v[84:87], v[68:71], v[20:23]
	s_add_u32 m0, s101, 0xa000
	v_lshl_add_u64 v[210:211], v[160:161], 0, s[18:19]
	global_load_lds_dwordx4 v[210:211], off
	v_mfma_f32_16x16x32_bf16 v[24:27], v[88:91], v[68:71], v[24:27]
	v_mfma_f32_16x16x32_bf16 v[28:31], v[92:95], v[68:71], v[28:31]
	s_add_u32 m0, s101, 0xe000
	v_lshl_add_u64 v[210:211], v[162:163], 0, s[18:19]
	global_load_lds_dwordx4 v[210:211], off
	v_mfma_f32_16x16x32_bf16 v[32:35], v[80:83], v[72:75], v[32:35]
	v_mfma_f32_16x16x32_bf16 v[36:39], v[84:87], v[72:75], v[36:39]
	s_add_u32 m0, s101, 0xb000
	v_lshl_add_u64 v[210:211], v[164:165], 0, s[18:19]
	global_load_lds_dwordx4 v[210:211], off
	v_mfma_f32_16x16x32_bf16 v[40:43], v[88:91], v[72:75], v[40:43]
	v_mfma_f32_16x16x32_bf16 v[44:47], v[92:95], v[72:75], v[44:47]
	s_add_u32 m0, s101, 0xf000
	v_lshl_add_u64 v[210:211], v[166:167], 0, s[18:19]
	global_load_lds_dwordx4 v[210:211], off
	v_mfma_f32_16x16x32_bf16 v[48:51], v[80:83], v[76:79], v[48:51]
	v_mfma_f32_16x16x32_bf16 v[52:55], v[84:87], v[76:79], v[52:55]
	v_mfma_f32_16x16x32_bf16 v[56:59], v[88:91], v[76:79], v[56:59]
	v_mfma_f32_16x16x32_bf16 v[60:63], v[92:95], v[76:79], v[60:63]
	s_waitcnt vmcnt(0)
	s_waitcnt lgkmcnt(0)
	s_barrier
; #define SB_ __builtin_amdgcn_sched_barrier(0)
; template <bool SWAP, bool HALF>
; DI void gemm_mainloop(const GemmDesc& d, int m0, int n0, bf16_t* smem, f32x16 (&acc)[2][2], int dry) {
;     ...
;   auto stage = [&](int cur, u32x4 (&ran)[4], u32x4 (&rbn)[4], int ks) {
;     ldf(cur, 1, 1); SB_;
;     mma(0); SB_;
;     ldf(cur, 2, 0); SB_;
;     lw(ran, rbn, cur ^ 1);
;     gl(ran, rbn, (ks + 3 < nk) ? ks + 3 : nk - 1);
;     SB_;
;     mma(1); SB_;
;     __syncthreads();
;     ldf(cur, 3, 1); SB_;
;     mma(0); SB_;
;     ldf(cur ^ 1, 0, 0);
;     SB_;
;     mma(1); SB_;
;     __syncthreads();
;   };
;   gl(ra0, rb0, 0);
;   gl(ra1, rb1, 1);
;   lw(ra0, rb0, 0);
;   gl(ra0, rb0, 2);
;   __syncthreads();
;   ldf(0, 0, 0);
; #pragma unroll 1
;   for (int ks = 0; ks < nk; ks += 2) {
;     stage(0, ra1, rb1, ks);
;     stage(1, ra0, rb0, ks + 1);
;   }
.LBB0_501:
	ds_read_b128 v[64:67], v168 offset:32768
	ds_read_b128 v[68:71], v168 offset:34816
	ds_read_b128 v[72:75], v168 offset:36864
	ds_read_b128 v[76:79], v168 offset:38912
	ds_read_b128 v[80:83], v169 offset:32768
	ds_read_b128 v[84:87], v169 offset:34816
	ds_read_b128 v[88:91], v169 offset:36864
	ds_read_b128 v[92:95], v169 offset:38912
	s_add_i32 s1, s1, 2
	s_add_i32 s5, s1, 2
	s_min_u32 s5, s5, 15
	s_lshl_b32 s18, s5, 7
	s_add_u32 m0, s101, 0x0
	v_lshl_add_u64 v[210:211], v[152:153], 0, s[18:19]
	global_load_lds_dwordx4 v[210:211], off
	s_add_u32 m0, s101, 0x4000
	v_lshl_add_u64 v[210:211], v[154:155], 0, s[18:19]
	global_load_lds_dwordx4 v[210:211], off
	ds_read_b128 v[128:131], v220 offset:32768
	ds_read_b128 v[132:135], v220 offset:34816
	ds_read_b128 v[136:139], v220 offset:36864
	ds_read_b128 v[140:143], v220 offset:38912
	ds_read_b128 v[192:195], v221 offset:32768
	ds_read_b128 v[196:199], v221 offset:34816
	ds_read_b128 v[200:203], v221 offset:36864
	ds_read_b128 v[204:207], v221 offset:38912
	v_mfma_f32_16x16x32_bf16 v[0:3], v[112:115], v[96:99], v[0:3]
	v_mfma_f32_16x16x32_bf16 v[4:7], v[116:119], v[96:99], v[4:7]
	s_add_u32 m0, s101, 0x1000
	v_lshl_add_u64 v[210:211], v[156:157], 0, s[18:19]
	global_load_lds_dwordx4 v[210:211], off
	v_mfma_f32_16x16x32_bf16 v[8:11], v[120:123], v[96:99], v[8:11]
	v_mfma_f32_16x16x32_bf16 v[12:15], v[124:127], v[96:99], v[12:15]
	s_add_u32 m0, s101, 0x5000
	v_lshl_add_u64 v[210:211], v[158:159], 0, s[18:19]
	global_load_lds_dwordx4 v[210:211], off
	v_mfma_f32_16x16x32_bf16 v[16:19], v[112:115], v[100:103], v[16:19]
	v_mfma_f32_16x16x32_bf16 v[20:23], v[116:119], v[100:103], v[20:23]
	s_add_u32 m0, s101, 0x2000
	v_lshl_add_u64 v[210:211], v[160:161], 0, s[18:19]
	global_load_lds_dwordx4 v[210:211], off
	v_mfma_f32_16x16x32_bf16 v[24:27], v[120:123], v[100:103], v[24:27]
	v_mfma_f32_16x16x32_bf16 v[28:31], v[124:127], v[100:103], v[28:31]
	s_add_u32 m0, s101, 0x6000
	v_lshl_add_u64 v[210:211], v[162:163], 0, s[18:19]
	global_load_lds_dwordx4 v[210:211], off
	v_mfma_f32_16x16x32_bf16 v[32:35], v[112:115], v[104:107], v[32:35]
	v_mfma_f32_16x16x32_bf16 v[36:39], v[116:119], v[104:107], v[36:39]
	s_add_u32 m0, s101, 0x3000
	v_lshl_add_u64 v[210:211], v[164:165], 0, s[18:19]
	global_load_lds_dwordx4 v[210:211], off
	v_mfma_f32_16x16x32_bf16 v[40:43], v[120:123], v[104:107], v[40:43]
	v_mfma_f32_16x16x32_bf16 v[44:47], v[124:127], v[104:107], v[44:47]
	s_add_u32 m0, s101, 0x7000
	v_lshl_add_u64 v[210:211], v[166:167], 0, s[18:19]
	global_load_lds_dwordx4 v[210:211], off
	v_mfma_f32_16x16x32_bf16 v[48:51], v[112:115], v[108:111], v[48:51]
	v_mfma_f32_16x16x32_bf16 v[52:55], v[116:119], v[108:111], v[52:55]
	v_mfma_f32_16x16x32_bf16 v[56:59], v[120:123], v[108:111], v[56:59]
	v_mfma_f32_16x16x32_bf16 v[60:63], v[124:127], v[108:111], v[60:63]
	s_waitcnt lgkmcnt(8)
	v_mfma_f32_16x16x32_bf16 v[0:3], v[80:83], v[64:67], v[0:3]
	v_mfma_f32_16x16x32_bf16 v[4:7], v[84:87], v[64:67], v[4:7]
	v_mfma_f32_16x16x32_bf16 v[8:11], v[88:91], v[64:67], v[8:11]
	v_mfma_f32_16x16x32_bf16 v[12:15], v[92:95], v[64:67], v[12:15]
	v_mfma_f32_16x16x32_bf16 v[16:19], v[80:83], v[68:71], v[16:19]
	v_mfma_f32_16x16x32_bf16 v[20:23], v[84:87], v[68:71], v[20:23]
	v_mfma_f32_16x16x32_bf16 v[24:27], v[88:91], v[68:71], v[24:27]
	v_mfma_f32_16x16x32_bf16 v[28:31], v[92:95], v[68:71], v[28:31]
	v_mfma_f32_16x16x32_bf16 v[32:35], v[80:83], v[72:75], v[32:35]
	v_mfma_f32_16x16x32_bf16 v[36:39], v[84:87], v[72:75], v[36:39]
	v_mfma_f32_16x16x32_bf16 v[40:43], v[88:91], v[72:75], v[40:43]
	v_mfma_f32_16x16x32_bf16 v[44:47], v[92:95], v[72:75], v[44:47]
	v_mfma_f32_16x16x32_bf16 v[48:51], v[80:83], v[76:79], v[48:51]
	v_mfma_f32_16x16x32_bf16 v[52:55], v[84:87], v[76:79], v[52:55]
	v_mfma_f32_16x16x32_bf16 v[56:59], v[88:91], v[76:79], v[56:59]
	v_mfma_f32_16x16x32_bf16 v[60:63], v[92:95], v[76:79], v[60:63]
	s_waitcnt vmcnt(0)
	s_waitcnt lgkmcnt(0)
	s_barrier
	ds_read_b128 v[64:67], v168 offset:0
	ds_read_b128 v[68:71], v168 offset:2048
	ds_read_b128 v[72:75], v168 offset:4096
	ds_read_b128 v[76:79], v168 offset:6144
	ds_read_b128 v[80:83], v169 offset:0
	ds_read_b128 v[84:87], v169 offset:2048
	ds_read_b128 v[88:91], v169 offset:4096
	ds_read_b128 v[92:95], v169 offset:6144
	s_add_i32 s5, s1, 3
	s_min_u32 s5, s5, 15
	s_lshl_b32 s18, s5, 7
	s_add_u32 m0, s101, 0x8000
	v_lshl_add_u64 v[210:211], v[152:153], 0, s[18:19]
	global_load_lds_dwordx4 v[210:211], off
	s_add_u32 m0, s101, 0xc000
	v_lshl_add_u64 v[210:211], v[154:155], 0, s[18:19]
	global_load_lds_dwordx4 v[210:211], off
	ds_read_b128 v[96:99], v220 offset:0
	ds_read_b128 v[100:103], v220 offset:2048
	ds_read_b128 v[104:107], v220 offset:4096
	ds_read_b128 v[108:111], v220 offset:6144
	ds_read_b128 v[112:115], v221 offset:0
	ds_read_b128 v[116:119], v221 offset:2048
	ds_read_b128 v[120:123], v221 offset:4096
	ds_read_b128 v[124:127], v221 offset:6144
	v_mfma_f32_16x16x32_bf16 v[0:3], v[192:195], v[128:131], v[0:3]
	v_mfma_f32_16x16x32_bf16 v[4:7], v[196:199], v[128:131], v[4:7]
	s_add_u32 m0, s101, 0x9000
	v_lshl_add_u64 v[210:211], v[156:157], 0, s[18:19]
	global_load_lds_dwordx4 v[210:211], off
	v_mfma_f32_16x16x32_bf16 v[8:11], v[200:203], v[128:131], v[8:11]
	v_mfma_f32_16x16x32_bf16 v[12:15], v[204:207], v[128:131], v[12:15]
	s_add_u32 m0, s101, 0xd000
	v_lshl_add_u64 v[210:211], v[158:159], 0, s[18:19]
	global_load_lds_dwordx4 v[210:211], off
	v_mfma_f32_16x16x32_bf16 v[16:19], v[192:195], v[132:135], v[16:19]
	v_mfma_f32_16x16x32_bf16 v[20:23], v[196:199], v[132:135], v[20:23]
	s_add_u32 m0, s101, 0xa000
	v_lshl_add_u64 v[210:211], v[160:161], 0, s[18:19]
	global_load_lds_dwordx4 v[210:211], off
	v_mfma_f32_16x16x32_bf16 v[24:27], v[200:203], v[132:135], v[24:27]
	v_mfma_f32_16x16x32_bf16 v[28:31], v[204:207], v[132:135], v[28:31]
	s_add_u32 m0, s101, 0xe000
	v_lshl_add_u64 v[210:211], v[162:163], 0, s[18:19]
	global_load_lds_dwordx4 v[210:211], off
	v_mfma_f32_16x16x32_bf16 v[32:35], v[192:195], v[136:139], v[32:35]
	v_mfma_f32_16x16x32_bf16 v[36:39], v[196:199], v[136:139], v[36:39]
	s_add_u32 m0, s101, 0xb000
	v_lshl_add_u64 v[210:211], v[164:165], 0, s[18:19]
	global_load_lds_dwordx4 v[210:211], off
	v_mfma_f32_16x16x32_bf16 v[40:43], v[200:203], v[136:139], v[40:43]
	v_mfma_f32_16x16x32_bf16 v[44:47], v[204:207], v[136:139], v[44:47]
	s_add_u32 m0, s101, 0xf000
	v_lshl_add_u64 v[210:211], v[166:167], 0, s[18:19]
	global_load_lds_dwordx4 v[210:211], off
	v_mfma_f32_16x16x32_bf16 v[48:51], v[192:195], v[140:143], v[48:51]
	v_mfma_f32_16x16x32_bf16 v[52:55], v[196:199], v[140:143], v[52:55]
	v_mfma_f32_16x16x32_bf16 v[56:59], v[200:203], v[140:143], v[56:59]
	v_mfma_f32_16x16x32_bf16 v[60:63], v[204:207], v[140:143], v[60:63]
	s_waitcnt lgkmcnt(8)
; #define SB_ __builtin_amdgcn_sched_barrier(0)
; template <bool SWAP, bool HALF>
; DI void gemm_mainloop(const GemmDesc& d, int m0, int n0, bf16_t* smem, f32x16 (&acc)[2][2], int dry) {
;     ...
;   auto stage = [&](int cur, u32x4 (&ran)[4], u32x4 (&rbn)[4], int ks) {
;     ldf(cur, 1, 1); SB_;
;     mma(0); SB_;
;     ldf(cur, 2, 0); SB_;
;     lw(ran, rbn, cur ^ 1);
;     gl(ran, rbn, (ks + 3 < nk) ? ks + 3 : nk - 1);
;     SB_;
;     mma(1); SB_;
;     __syncthreads();
;     ldf(cur, 3, 1); SB_;
;     mma(0); SB_;
;     ldf(cur ^ 1, 0, 0);
;     SB_;
;     mma(1); SB_;
;     __syncthreads();
;   };
;   gl(ra0, rb0, 0);
;   gl(ra1, rb1, 1);
;   lw(ra0, rb0, 0);
;   gl(ra0, rb0, 2);
;   __syncthreads();
;   ldf(0, 0, 0);
; #pragma unroll 1
;   for (int ks = 0; ks < nk; ks += 2) {
;     stage(0, ra1, rb1, ks);
;     stage(1, ra0, rb0, ks + 1);
;   }
	v_mfma_f32_16x16x32_bf16 v[0:3], v[80:83], v[64:67], v[0:3]
	v_mfma_f32_16x16x32_bf16 v[4:7], v[84:87], v[64:67], v[4:7]
	v_mfma_f32_16x16x32_bf16 v[8:11], v[88:91], v[64:67], v[8:11]
	v_mfma_f32_16x16x32_bf16 v[12:15], v[92:95], v[64:67], v[12:15]
	v_mfma_f32_16x16x32_bf16 v[16:19], v[80:83], v[68:71], v[16:19]
	v_mfma_f32_16x16x32_bf16 v[20:23], v[84:87], v[68:71], v[20:23]
	v_mfma_f32_16x16x32_bf16 v[24:27], v[88:91], v[68:71], v[24:27]
	v_mfma_f32_16x16x32_bf16 v[28:31], v[92:95], v[68:71], v[28:31]
	v_mfma_f32_16x16x32_bf16 v[32:35], v[80:83], v[72:75], v[32:35]
	v_mfma_f32_16x16x32_bf16 v[36:39], v[84:87], v[72:75], v[36:39]
	v_mfma_f32_16x16x32_bf16 v[40:43], v[88:91], v[72:75], v[40:43]
	v_mfma_f32_16x16x32_bf16 v[44:47], v[92:95], v[72:75], v[44:47]
	v_mfma_f32_16x16x32_bf16 v[48:51], v[80:83], v[76:79], v[48:51]
	v_mfma_f32_16x16x32_bf16 v[52:55], v[84:87], v[76:79], v[52:55]
	v_mfma_f32_16x16x32_bf16 v[56:59], v[88:91], v[76:79], v[56:59]
	v_mfma_f32_16x16x32_bf16 v[60:63], v[92:95], v[76:79], v[60:63]
	s_cmp_lt_u32 s1, 12
	s_waitcnt vmcnt(0)
	s_waitcnt lgkmcnt(0)
	s_barrier
	s_cbranch_scc1 .LBB0_501
	ds_read_b128 v[64:67], v168 offset:32768
	ds_read_b128 v[68:71], v168 offset:34816
	ds_read_b128 v[72:75], v168 offset:36864
	ds_read_b128 v[76:79], v168 offset:38912
	ds_read_b128 v[80:83], v169 offset:32768
	ds_read_b128 v[84:87], v169 offset:34816
	ds_read_b128 v[88:91], v169 offset:36864
	ds_read_b128 v[92:95], v169 offset:38912
	ds_read_b128 v[128:131], v220 offset:32768
	ds_read_b128 v[132:135], v220 offset:34816
	ds_read_b128 v[136:139], v220 offset:36864
	ds_read_b128 v[140:143], v220 offset:38912
	ds_read_b128 v[192:195], v221 offset:32768
	ds_read_b128 v[196:199], v221 offset:34816
	ds_read_b128 v[200:203], v221 offset:36864
	ds_read_b128 v[204:207], v221 offset:38912
	v_mfma_f32_16x16x32_bf16 v[0:3], v[112:115], v[96:99], v[0:3]
	v_mfma_f32_16x16x32_bf16 v[4:7], v[116:119], v[96:99], v[4:7]
	v_mfma_f32_16x16x32_bf16 v[8:11], v[120:123], v[96:99], v[8:11]
	v_mfma_f32_16x16x32_bf16 v[12:15], v[124:127], v[96:99], v[12:15]
	v_mfma_f32_16x16x32_bf16 v[16:19], v[112:115], v[100:103], v[16:19]
	v_mfma_f32_16x16x32_bf16 v[20:23], v[116:119], v[100:103], v[20:23]
	v_mfma_f32_16x16x32_bf16 v[24:27], v[120:123], v[100:103], v[24:27]
	v_mfma_f32_16x16x32_bf16 v[28:31], v[124:127], v[100:103], v[28:31]
	v_mfma_f32_16x16x32_bf16 v[32:35], v[112:115], v[104:107], v[32:35]
	v_mfma_f32_16x16x32_bf16 v[36:39], v[116:119], v[104:107], v[36:39]
	v_mfma_f32_16x16x32_bf16 v[40:43], v[120:123], v[104:107], v[40:43]
	v_mfma_f32_16x16x32_bf16 v[44:47], v[124:127], v[104:107], v[44:47]
	v_mfma_f32_16x16x32_bf16 v[48:51], v[112:115], v[108:111], v[48:51]
	v_mfma_f32_16x16x32_bf16 v[52:55], v[116:119], v[108:111], v[52:55]
	v_mfma_f32_16x16x32_bf16 v[56:59], v[120:123], v[108:111], v[56:59]
	v_mfma_f32_16x16x32_bf16 v[60:63], v[124:127], v[108:111], v[60:63]
	s_waitcnt lgkmcnt(8)
	v_mfma_f32_16x16x32_bf16 v[0:3], v[80:83], v[64:67], v[0:3]
	v_mfma_f32_16x16x32_bf16 v[4:7], v[84:87], v[64:67], v[4:7]
	v_mfma_f32_16x16x32_bf16 v[8:11], v[88:91], v[64:67], v[8:11]
	v_mfma_f32_16x16x32_bf16 v[12:15], v[92:95], v[64:67], v[12:15]
	v_mfma_f32_16x16x32_bf16 v[16:19], v[80:83], v[68:71], v[16:19]
	v_mfma_f32_16x16x32_bf16 v[20:23], v[84:87], v[68:71], v[20:23]
	v_mfma_f32_16x16x32_bf16 v[24:27], v[88:91], v[68:71], v[24:27]
	v_mfma_f32_16x16x32_bf16 v[28:31], v[92:95], v[68:71], v[28:31]
	v_mfma_f32_16x16x32_bf16 v[32:35], v[80:83], v[72:75], v[32:35]
	v_mfma_f32_16x16x32_bf16 v[36:39], v[84:87], v[72:75], v[36:39]
	v_mfma_f32_16x16x32_bf16 v[40:43], v[88:91], v[72:75], v[40:43]
	v_mfma_f32_16x16x32_bf16 v[44:47], v[92:95], v[72:75], v[44:47]
	v_mfma_f32_16x16x32_bf16 v[48:51], v[80:83], v[76:79], v[48:51]
	v_mfma_f32_16x16x32_bf16 v[52:55], v[84:87], v[76:79], v[52:55]
	v_mfma_f32_16x16x32_bf16 v[56:59], v[88:91], v[76:79], v[56:59]
	v_mfma_f32_16x16x32_bf16 v[60:63], v[92:95], v[76:79], v[60:63]
	s_waitcnt lgkmcnt(0)
	s_barrier
	v_mfma_f32_16x16x32_bf16 v[0:3], v[192:195], v[128:131], v[0:3]
	v_mfma_f32_16x16x32_bf16 v[4:7], v[196:199], v[128:131], v[4:7]
	v_mfma_f32_16x16x32_bf16 v[8:11], v[200:203], v[128:131], v[8:11]
	v_mfma_f32_16x16x32_bf16 v[12:15], v[204:207], v[128:131], v[12:15]
	v_mfma_f32_16x16x32_bf16 v[16:19], v[192:195], v[132:135], v[16:19]
	v_mfma_f32_16x16x32_bf16 v[20:23], v[196:199], v[132:135], v[20:23]
	v_mfma_f32_16x16x32_bf16 v[24:27], v[200:203], v[132:135], v[24:27]
	v_mfma_f32_16x16x32_bf16 v[28:31], v[204:207], v[132:135], v[28:31]
	v_mfma_f32_16x16x32_bf16 v[32:35], v[192:195], v[136:139], v[32:35]
	v_mfma_f32_16x16x32_bf16 v[36:39], v[196:199], v[136:139], v[36:39]
	v_mfma_f32_16x16x32_bf16 v[40:43], v[200:203], v[136:139], v[40:43]
	v_mfma_f32_16x16x32_bf16 v[44:47], v[204:207], v[136:139], v[44:47]
	v_mfma_f32_16x16x32_bf16 v[48:51], v[192:195], v[140:143], v[48:51]
	v_mfma_f32_16x16x32_bf16 v[52:55], v[196:199], v[140:143], v[52:55]
	v_mfma_f32_16x16x32_bf16 v[56:59], v[200:203], v[140:143], v[56:59]
	v_mfma_f32_16x16x32_bf16 v[60:63], v[204:207], v[140:143], v[60:63]
	s_waitcnt vmcnt(7)
; DI float ssq_f(u64 v) { return (float)v * (1.f / 1048576.f); }
; DI void gemm_tile(const GemmDesc& d, int m0, int n0, bf16_t* smem, int dry) {
;     ...
;   u32x2 hpre[16];
;   if (d.epi == EPI_RESID) {
; #pragma unroll
;     for (int pass = 0; pass < 16; ++pass) {
;       int m = m0 + pass * 8 + (t >> 5); m = m < M ? m : M - 1;
;       hpre[pass] = *(const u32x2*)(d.hb + (size_t)m * D + d.c_off + n0 + (t & 31) * 4);
;     }
;   } else if (t < 128) {
;     rs_s[t] = rsqrtf(ssq_f(myss) * d.inv_dim + EPS);
;   }
;   if (half) {
; #pragma unroll
;     for (int a = 0; a < 2; ++a)
; #pragma unroll
;       for (int g = 0; g < 4; ++g) {
;         f32x4 o;
; #pragma unroll
;         for (int j = 0; j < 4; ++j) o[j] = acc[a][0][4 * g + j];
;         *(f32x4*)(Ct + (a * 32 + r) * CS + w * 32 + 8 * g + 4 * hh) = o;
;       }
;   } else {
; #pragma unroll
;     for (int a = 0; a < 2; ++a)
; #pragma unroll
;       for (int b = 0; b < 2; ++b)
; #pragma unroll
;         for (int g = 0; g < 4; ++g) {
;           f32x4 o;
; #pragma unroll
;           for (int j = 0; j < 4; ++j) o[j] = acc[a][b][4 * g + j];
;           *(f32x4*)(Ct + (wm * 64 + a * 32 + r) * CS + wn * 64 + b * 32 + 8 * g + 4 * hh) = o;
;         }
;   }
;   __syncthreads();
;   if (d.epi == EPI_RESID) {
; #pragma unroll
;     for (int pass = 0; pass < 16; ++pass) {
;       const int row = pass * 8 + (t >> 5), c4 = t & 31, m = m0 + row;
;       float part = 0.f;
;       if (m < M) {
;         const f32x4 v = *(const f32x4*)(Ct + row * CS + c4 * 4);
;         const int n = d.c_off + n0 + c4 * 4;
;         f32x4 hv;
;         hv[0] = __uint_as_float(hpre[pass][0] << 16); hv[1] = __uint_as_float(hpre[pass][0] & 0xffff0000u);
;         hv[2] = __uint_as_float(hpre[pass][1] << 16); hv[3] = __uint_as_float(hpre[pass][1] & 0xffff0000u);
; #pragma unroll
;         for (int j = 0; j < 4; ++j) { hv[j] += v[j]; part += hv[j] * hv[j]; }
;         u32x2 o; o[0] = pk_bf16(hv[0], hv[1]); o[1] = pk_bf16(hv[2], hv[3]);
;         *(u32x2*)(d.hb + (size_t)m * D + n) = o;
;       }
	v_ashrrev_i32_e32 v98, 5, v150
	v_add_u32_e32 v92, s9, v98
	s_ashr_i32 s5, s4, 31
	s_lshl_b64 s[6:7], s[4:5], 1
	v_add_u32_e32 v70, 16, v92
	v_add_u32_e32 v72, 24, v92
	s_add_u32 s6, s56, s6
	v_lshlrev_b32_e32 v64, 3, v150
	v_min_i32_e32 v66, 0x803f, v92
	v_add_u32_e32 v68, 8, v92
	v_min_i32_e32 v70, 0x803f, v70
	v_min_i32_e32 v72, 0x803f, v72
	s_addc_u32 s7, s57, s7
	v_and_b32_e32 v144, 0xf8, v64
	v_ashrrev_i32_e32 v67, 31, v66
	v_min_i32_e32 v68, 0x803f, v68
	v_ashrrev_i32_e32 v71, 31, v70
	v_ashrrev_i32_e32 v73, 31, v72
	v_lshl_add_u64 v[64:65], s[6:7], 0, v[144:145]
	v_lshlrev_b64 v[66:67], 11, v[66:67]
	v_ashrrev_i32_e32 v69, 31, v68
	v_lshlrev_b64 v[70:71], 11, v[70:71]
	v_lshlrev_b64 v[72:73], 11, v[72:73]
	v_lshl_add_u64 v[66:67], v[64:65], 0, v[66:67]
	v_lshlrev_b64 v[68:69], 11, v[68:69]
	v_lshl_add_u64 v[70:71], v[64:65], 0, v[70:71]
	v_lshl_add_u64 v[72:73], v[64:65], 0, v[72:73]
	v_lshl_add_u64 v[68:69], v[64:65], 0, v[68:69]
	global_load_dwordx2 v[96:97], v[66:67], off
	global_load_dwordx2 v[94:95], v[68:69], off
	global_load_dwordx2 v[90:91], v[70:71], off
	global_load_dwordx2 v[88:89], v[72:73], off
	v_add_u32_e32 v66, 32, v92
	v_add_u32_e32 v70, 48, v92
	v_add_u32_e32 v72, 56, v92
	v_min_i32_e32 v66, 0x803f, v66
	v_add_u32_e32 v68, 40, v92
	v_min_i32_e32 v70, 0x803f, v70
	v_min_i32_e32 v72, 0x803f, v72
	v_ashrrev_i32_e32 v67, 31, v66
	v_min_i32_e32 v68, 0x803f, v68
	v_ashrrev_i32_e32 v71, 31, v70
	v_ashrrev_i32_e32 v73, 31, v72
	v_lshlrev_b64 v[66:67], 11, v[66:67]
	v_ashrrev_i32_e32 v69, 31, v68
	v_lshlrev_b64 v[70:71], 11, v[70:71]
	v_lshlrev_b64 v[72:73], 11, v[72:73]
	v_lshl_add_u64 v[66:67], v[64:65], 0, v[66:67]
	v_lshlrev_b64 v[68:69], 11, v[68:69]
	v_lshl_add_u64 v[70:71], v[64:65], 0, v[70:71]
	v_lshl_add_u64 v[72:73], v[64:65], 0, v[72:73]
	v_lshl_add_u64 v[68:69], v[64:65], 0, v[68:69]
	global_load_dwordx2 v[86:87], v[66:67], off
	global_load_dwordx2 v[84:85], v[68:69], off
	global_load_dwordx2 v[82:83], v[70:71], off
	global_load_dwordx2 v[80:81], v[72:73], off
	v_add_u32_e32 v66, 64, v92
	v_add_u32_e32 v70, 0x50, v92
	v_add_u32_e32 v72, 0x58, v92
	v_min_i32_e32 v66, 0x803f, v66
	v_add_u32_e32 v68, 0x48, v92
	v_min_i32_e32 v70, 0x803f, v70
	v_min_i32_e32 v72, 0x803f, v72
	v_ashrrev_i32_e32 v67, 31, v66
	v_min_i32_e32 v68, 0x803f, v68
	v_ashrrev_i32_e32 v71, 31, v70
	v_ashrrev_i32_e32 v73, 31, v72
	v_lshlrev_b64 v[66:67], 11, v[66:67]
	v_ashrrev_i32_e32 v69, 31, v68
	v_lshlrev_b64 v[70:71], 11, v[70:71]
	v_lshlrev_b64 v[72:73], 11, v[72:73]
	v_lshl_add_u64 v[66:67], v[64:65], 0, v[66:67]
	v_lshlrev_b64 v[68:69], 11, v[68:69]
	v_lshl_add_u64 v[70:71], v[64:65], 0, v[70:71]
	v_lshl_add_u64 v[72:73], v[64:65], 0, v[72:73]
	v_lshl_add_u64 v[68:69], v[64:65], 0, v[68:69]
	global_load_dwordx2 v[78:79], v[66:67], off
	global_load_dwordx2 v[76:77], v[68:69], off
	global_load_dwordx2 v[74:75], v[70:71], off
	s_nop 0
	global_load_dwordx2 v[72:73], v[72:73], off
	v_add_u32_e32 v70, 0x70, v92
	v_min_i32_e32 v70, 0x803f, v70
	v_ashrrev_i32_e32 v71, 31, v70
	v_lshlrev_b64 v[70:71], 11, v[70:71]
	v_add_u32_e32 v66, 0x60, v92
	v_add_u32_e32 v68, 0x68, v92
	s_waitcnt vmcnt(18)
	v_lshl_add_u64 v[100:101], v[64:65], 0, v[70:71]
	v_add_u32_e32 v70, 0x78, v92
	v_min_i32_e32 v66, 0x803f, v66
	v_min_i32_e32 v68, 0x803f, v68
	v_min_i32_e32 v70, 0x803f, v70
	v_ashrrev_i32_e32 v67, 31, v66
	v_ashrrev_i32_e32 v69, 31, v68
	v_ashrrev_i32_e32 v71, 31, v70
	v_lshlrev_b64 v[66:67], 11, v[66:67]
	v_lshlrev_b64 v[68:69], 11, v[68:69]
	v_lshlrev_b64 v[70:71], 11, v[70:71]
	v_lshl_add_u64 v[66:67], v[64:65], 0, v[66:67]
	v_lshl_add_u64 v[68:69], v[64:65], 0, v[68:69]
	v_lshl_add_u64 v[64:65], v[64:65], 0, v[70:71]
	global_load_dwordx2 v[70:71], v[66:67], off
	s_nop 0
	global_load_dwordx2 v[68:69], v[68:69], off
	s_nop 0
	global_load_dwordx2 v[66:67], v[100:101], off
	s_nop 0
	global_load_dwordx2 v[64:65], v[64:65], off
	v_and_b32_e32 v99, 31, v150
	v_lshrrev_b32_e32 v100, 1, v150
	v_lshlrev_b32_e32 v93, 2, v150
	v_and_or_b32 v101, v100, s72, v99
	v_and_b32_e32 v100, 16, v100
	s_movk_i32 s1, 0x100
	v_and_or_b32 v100, v93, s1, v100
	v_mad_u64_u32 v[100:101], s[6:7], v101, s22, v[100:101]
	v_and_b32_e32 v212, 15, v172
	v_lshrrev_b32_e32 v213, 1, v172
	v_and_or_b32 v212, v213, s72, v212
	v_lshlrev_b32_e32 v213, 2, v172
	v_and_b32_e32 v214, 0x30, v172
	v_and_b32_e32 v213, 0x100, v213
	v_or_b32_e32 v213, v213, v214
	v_mad_u32_u24 v100, v212, s22, v213
	ds_write_b128 v100, v[0:3]
	ds_write_b128 v100, v[4:7] offset:64
	ds_write_b128 v100, v[8:11] offset:128
	ds_write_b128 v100, v[12:15] offset:192
	ds_write_b128 v100, v[16:19] offset:8448
	ds_write_b128 v100, v[20:23] offset:8512
	ds_write_b128 v100, v[24:27] offset:8576
	ds_write_b128 v100, v[28:31] offset:8640
	ds_write_b128 v100, v[32:35] offset:16896
	ds_write_b128 v100, v[36:39] offset:16960
	ds_write_b128 v100, v[40:43] offset:17024
	ds_write_b128 v100, v[44:47] offset:17088
	ds_write_b128 v100, v[48:51] offset:25344
	ds_write_b128 v100, v[52:55] offset:25408
	ds_write_b128 v100, v[56:59] offset:25472
	ds_write_b128 v100, v[60:63] offset:25536
	v_lshl_or_b32 v0, v99, 2, s4
	v_lshlrev_b32_e32 v2, 4, v99
	v_cmp_gt_i32_e64 s[4:5], s23, v92
	v_mov_b32_e32 v4, 0
	v_ashrrev_i32_e32 v93, 31, v92
	v_ashrrev_i32_e32 v1, 31, v0
	s_waitcnt lgkmcnt(0)
	s_barrier
	s_and_saveexec_b64 s[6:7], s[4:5]
	s_cbranch_execz .LBB0_504
	v_mad_u64_u32 v[4:5], s[10:11], v98, s22, v[2:3]
	ds_read_b128 v[4:7], v4
	s_waitcnt vmcnt(15)
	v_lshlrev_b32_e32 v8, 16, v96
	v_and_b32_e32 v9, 0xffff0000, v96
	v_and_b32_e32 v11, 0xffff0000, v97
	v_lshlrev_b32_e32 v10, 16, v97
	s_waitcnt lgkmcnt(0)
	v_pk_add_f32 v[8:9], v[4:5], v[8:9]
	v_pk_add_f32 v[6:7], v[6:7], v[10:11]
	v_pk_mul_f32 v[4:5], v[8:9], v[8:9]
	v_pk_mul_f32 v[10:11], v[6:7], v[6:7]
	v_add_f32_e32 v3, v4, v5
	v_cvt_pk_bf16_f32 v8, v8, v9
	v_cvt_pk_bf16_f32 v9, v6, v7
	v_lshlrev_b64 v[6:7], 11, v[92:93]
	v_add_f32_e32 v3, v10, v3
	v_lshl_add_u64 v[6:7], s[56:57], 0, v[6:7]
	v_add_f32_e32 v4, v11, v3
	v_lshl_add_u64 v[6:7], v[0:1], 1, v[6:7]
	global_store_dwordx2 v[6:7], v[8:9], off

; DI int otid() { int t = threadIdx.x; asm volatile("" : "+v"(t)); return t; }
; template <bool SWAP, bool HALF>
; DI void gemm_mainloop(const GemmDesc& d, int m0, int n0, bf16_t* smem, f32x16 (&acc)[2][2], int dry) {
;   const int t = otid(), lane = t & 63, w = t >> 6, wm = w >> 1, wn = w & 1, r = lane & 31, hh = lane >> 5;
;   const int lrow = t >> 3, lkc = t & 7;
;   const bf16_t* ap[4]; const bf16_t* bp[4];
; #pragma unroll
;   for (int i = 0; i < 4; ++i) {
;     int am = m0 + lrow + 32 * i; am = am < M ? am : M - 1;
;     ap[i] = d.A + (size_t)am * d.lda + lkc * 8 + (d.a_grp ? (n0 / d.a_grp) * d.a_grp : 0);
;     bp[i] = d.Bt + (size_t)(n0 + lrow + 32 * i) * d.ldb + lkc * 8;
;     ...
;   gl(ra0, rb0, 0);
;   gl(ra1, rb1, 1);
;   lw(ra0, rb0, 0);
;   gl(ra0, rb0, 2);
;   __syncthreads();
;   ldf(0, 0, 0);
.LBB0_626:
	s_or_b64 exec, exec, s[4:5]
	v_mov_b32_e32 v32, v172
	v_readlane_b32 s76, v228, 60
	v_ashrrev_i32_e32 v10, 3, v32
	v_add_u32_e32 v11, s6, v10
	v_lshlrev_b32_e32 v0, 3, v32
	v_and_b32_e32 v33, 56, v0
	v_min_i32_e32 v0, 0x803f, v11
	v_lshlrev_b32_e32 v144, 1, v33
	v_ashrrev_i32_e32 v1, 31, v0
	v_lshl_add_u64 v[4:5], s[56:57], 0, v[144:145]
	v_lshlrev_b64 v[0:1], 11, v[0:1]
	v_lshl_add_u64 v[152:153], v[4:5], 0, v[0:1]
	s_lshl_b32 s6, s10, 7
	v_add_u32_e32 v6, s6, v10
	v_readlane_b32 s82, v223, 2
	v_readlane_b32 s83, v223, 3
	v_ashrrev_i32_e32 v7, 31, v6
	v_lshlrev_b64 v[6:7], 11, v[6:7]
	v_lshl_add_u64 v[8:9], s[82:83], 0, v[144:145]
	v_lshl_add_u64 v[154:155], v[8:9], 0, v[6:7]
	v_min_i32_e32 v6, 0x801f, v11
	v_ashrrev_i32_e32 v7, 31, v6
	v_lshlrev_b64 v[6:7], 11, v[6:7]
	v_lshl_add_u64 v[8:9], v[4:5], 0, v[6:7]
	v_min_i32_e32 v6, 0x7fff, v11
	v_ashrrev_i32_e32 v7, 31, v6
	v_lshlrev_b64 v[6:7], 11, v[6:7]
	v_lshl_add_u64 v[16:17], v[4:5], 0, v[6:7]
	v_min_i32_e32 v6, 0x7fdf, v11
	s_mov_b64 s[4:5], 0x10000
	v_ashrrev_i32_e32 v7, 31, v6
	v_lshl_add_u64 v[156:157], v[8:9], 0, s[4:5]
	v_lshl_add_u64 v[158:159], v[154:155], 0, s[4:5]
	s_mov_b64 s[4:5], 0x20000
	v_lshlrev_b64 v[6:7], 11, v[6:7]
	v_lshl_add_u64 v[160:161], v[16:17], 0, s[4:5]
	v_lshl_add_u64 v[162:163], v[154:155], 0, s[4:5]
	v_lshl_add_u64 v[24:25], v[4:5], 0, v[6:7]
	s_mov_b64 s[4:5], 0x30000
	v_lshl_add_u64 v[164:165], v[24:25], 0, s[4:5]
	v_lshl_add_u64 v[166:167], v[154:155], 0, s[4:5]
	s_movk_i32 s4, 0x48
	v_and_b32_e32 v34, 31, v32
	v_mul_lo_u32 v35, v10, s4
	v_readlane_b32 s77, v228, 61
	v_readlane_b32 s78, v228, 62
	v_readlane_b32 s79, v228, 63
	v_readlane_b32 s80, v223, 0
	v_readlane_b32 s81, v223, 1
	v_readlane_b32 s84, v223, 4
	v_readlane_b32 s85, v223, 5
	v_readlane_b32 s86, v223, 6
	v_readlane_b32 s87, v223, 7
	v_readlane_b32 s88, v223, 8
	v_readlane_b32 s89, v223, 9
	v_readlane_b32 s90, v223, 10
	v_readlane_b32 s91, v223, 11
	s_mov_b32 s8, 0x10000
	v_add_co_u32_e64 v8, s[4:5], s8, v8
	s_nop 1
	v_addc_co_u32_e64 v9, s[4:5], 0, v9, s[4:5]
	s_waitcnt vmcnt(19)
	v_add_co_u32_e64 v12, s[4:5], s8, v154
	s_nop 1
	v_addc_co_u32_e64 v13, s[4:5], 0, v155, s[4:5]
	s_mov_b32 s8, 0x20000
	v_add_co_u32_e64 v16, s[4:5], s8, v16
	s_nop 1
	v_addc_co_u32_e64 v17, s[4:5], 0, v17, s[4:5]
	v_add_co_u32_e64 v20, s[4:5], s8, v154
	s_nop 1
	v_addc_co_u32_e64 v21, s[4:5], 0, v155, s[4:5]
	s_mov_b32 s8, 0x30000
	v_add_co_u32_e64 v24, s[4:5], s8, v24
	s_nop 1
	v_addc_co_u32_e64 v25, s[4:5], 0, v25, s[4:5]
	v_add_co_u32_e64 v28, s[4:5], s8, v154
	s_nop 1
	v_addc_co_u32_e64 v29, s[4:5], 0, v155, s[4:5]
	s_nop 0
	v_add_lshl_u32 v144, v35, v33, 1
	s_waitcnt vmcnt(15)
	s_waitcnt vmcnt(14)
	s_waitcnt vmcnt(13)
	s_waitcnt vmcnt(12)
	s_waitcnt vmcnt(11)
	s_waitcnt vmcnt(10)
	s_waitcnt vmcnt(9)
	s_waitcnt vmcnt(8)
	v_lshrrev_b32_e32 v0, 1, v32
	v_and_or_b32 v1, v0, s72, v34
	v_and_b32_e32 v0, 16, v0
	s_movk_i32 s4, 0x90
	v_mad_u64_u32 v[168:169], s[4:5], v1, s4, v[0:1]
	v_and_b32_e32 v1, 0x5f, v32
	v_mul_u32_u24_e32 v1, 0x48, v1
	v_lshl_add_u32 v169, v1, 1, v0
	v_bfe_u32 v212, v172, 4, 3
	v_lshlrev_b32_e32 v212, 4, v212
	v_xor_b32_e32 v152, v152, v212
	v_xor_b32_e32 v154, v154, v212
	v_xor_b32_e32 v156, v156, v212
	v_xor_b32_e32 v158, v158, v212
	v_xor_b32_e32 v160, v160, v212
	v_xor_b32_e32 v162, v162, v212
	v_xor_b32_e32 v164, v164, v212
	v_xor_b32_e32 v166, v166, v212
	v_lshrrev_b32_e32 v213, 6, v172
	s_nop 1
	v_readfirstlane_b32 s101, v213
	s_lshl_b32 s101, s101, 10
	s_add_u32 m0, s101, 0x0
	s_nop 0
	global_load_lds_dwordx4 v[152:153], off
	s_add_u32 m0, s101, 0x4000
	s_nop 0
	global_load_lds_dwordx4 v[154:155], off
	s_add_u32 m0, s101, 0x1000
	s_nop 0
	global_load_lds_dwordx4 v[156:157], off
	s_add_u32 m0, s101, 0x5000
	s_nop 0
	global_load_lds_dwordx4 v[158:159], off
	s_add_u32 m0, s101, 0x2000
	s_nop 0
	global_load_lds_dwordx4 v[160:161], off
	s_add_u32 m0, s101, 0x6000
	s_nop 0
	global_load_lds_dwordx4 v[162:163], off
	s_add_u32 m0, s101, 0x3000
	s_nop 0
	global_load_lds_dwordx4 v[164:165], off
	s_add_u32 m0, s101, 0x7000
	s_nop 0
	global_load_lds_dwordx4 v[166:167], off
	v_and_b32_e32 v212, 15, v172
	v_bfe_u32 v213, v172, 4, 2
	v_lshrrev_b32_e32 v214, 1, v212
	v_xor_b32_e32 v213, v213, v214
	v_lshlrev_b32_e32 v213, 4, v213
	v_lshl_or_b32 v212, v212, 7, v213
	v_lshrrev_b32_e32 v214, 7, v172
	v_lshl_add_u32 v168, v214, 13, v212
	v_bfe_u32 v214, v172, 6, 1
	v_lshl_add_u32 v169, v214, 13, v212
	v_add_u32_e32 v169, 0x4000, v169
	v_xor_b32_e32 v220, 64, v168
	v_xor_b32_e32 v221, 64, v169
	s_waitcnt vmcnt(0)
	s_waitcnt lgkmcnt(0)
	s_barrier
; #define SB_ __builtin_amdgcn_sched_barrier(0)
; template <bool SWAP, bool HALF>
; DI void gemm_mainloop(const GemmDesc& d, int m0, int n0, bf16_t* smem, f32x16 (&acc)[2][2], int dry) {
;     ...
; #pragma unroll
;   for (int a = 0; a < 2; ++a)
; #pragma unroll
;     for (int b = 0; b < 2; ++b)
; #pragma unroll
;       for (int i = 0; i < 16; ++i) acc[a][b][i] = 0.f;
;     ...
;   auto stage = [&](int cur, u32x4 (&ran)[4], u32x4 (&rbn)[4], int ks) {
;     ldf(cur, 1, 1); SB_;
;     mma(0); SB_;
;     ldf(cur, 2, 0); SB_;
;     lw(ran, rbn, cur ^ 1);
;     gl(ran, rbn, (ks + 3 < nk) ? ks + 3 : nk - 1);
;     SB_;
;     mma(1); SB_;
;     __syncthreads();
;     ldf(cur, 3, 1); SB_;
;     mma(0); SB_;
;     ldf(cur ^ 1, 0, 0);
;     SB_;
;     mma(1); SB_;
;     __syncthreads();
;   };
	v_mov_b32_e32 v0, 0
	v_add_u32_e32 v171, 0x9000, v144
	s_mov_b32 s4, -2
	v_mov_b32_e32 v1, v0
	v_mov_b32_e32 v2, v0
	v_mov_b32_e32 v3, v0
	v_mov_b32_e32 v4, v0
	v_mov_b32_e32 v5, v0
	v_mov_b32_e32 v6, v0
	v_mov_b32_e32 v7, v0
	v_mov_b32_e32 v8, v0
	v_mov_b32_e32 v9, v0
	v_mov_b32_e32 v10, v0
	v_mov_b32_e32 v11, v0
	v_mov_b32_e32 v12, v0
	v_mov_b32_e32 v13, v0
	v_mov_b32_e32 v14, v0
	v_mov_b32_e32 v15, v0
	v_mov_b32_e32 v16, v0
	v_mov_b32_e32 v17, v0
	v_mov_b32_e32 v18, v0
	v_mov_b32_e32 v19, v0
	v_mov_b32_e32 v20, v0
	v_mov_b32_e32 v21, v0
	v_mov_b32_e32 v22, v0
	v_mov_b32_e32 v23, v0
	v_mov_b32_e32 v24, v0
	v_mov_b32_e32 v25, v0
	v_mov_b32_e32 v26, v0
	v_mov_b32_e32 v27, v0
	v_mov_b32_e32 v28, v0
	v_mov_b32_e32 v29, v0
	v_mov_b32_e32 v30, v0
	v_mov_b32_e32 v31, v0
	v_mov_b32_e32 v32, v0
	v_mov_b32_e32 v33, v0
	v_mov_b32_e32 v34, v0
	v_mov_b32_e32 v35, v0
	v_mov_b32_e32 v36, v0
	v_mov_b32_e32 v37, v0
	v_mov_b32_e32 v38, v0
	v_mov_b32_e32 v39, v0
	v_mov_b32_e32 v40, v0
	v_mov_b32_e32 v41, v0
	v_mov_b32_e32 v42, v0
	v_mov_b32_e32 v43, v0
	v_mov_b32_e32 v44, v0
	v_mov_b32_e32 v45, v0
	v_mov_b32_e32 v46, v0
	v_mov_b32_e32 v47, v0
	v_mov_b32_e32 v48, v0
	v_mov_b32_e32 v49, v0
	v_mov_b32_e32 v50, v0
	v_mov_b32_e32 v51, v0
	v_mov_b32_e32 v52, v0
	v_mov_b32_e32 v53, v0
	v_mov_b32_e32 v54, v0
	v_mov_b32_e32 v55, v0
	v_mov_b32_e32 v56, v0
	v_mov_b32_e32 v57, v0
	v_mov_b32_e32 v58, v0
	v_mov_b32_e32 v59, v0
	v_mov_b32_e32 v60, v0
	v_mov_b32_e32 v61, v0
	v_mov_b32_e32 v62, v0
	v_mov_b32_e32 v63, v0
	ds_read_b128 v[64:67], v168 offset:0
	ds_read_b128 v[68:71], v168 offset:2048
	ds_read_b128 v[72:75], v168 offset:4096
	ds_read_b128 v[76:79], v168 offset:6144
	ds_read_b128 v[80:83], v169 offset:0
	ds_read_b128 v[84:87], v169 offset:2048
	ds_read_b128 v[88:91], v169 offset:4096
	ds_read_b128 v[92:95], v169 offset:6144
	s_add_i32 s5, s4, 3
	s_min_u32 s5, s5, 15
	s_lshl_b32 s18, s5, 7
	s_add_u32 m0, s101, 0x8000
	v_lshl_add_u64 v[210:211], v[152:153], 0, s[18:19]
	global_load_lds_dwordx4 v[210:211], off
	s_add_u32 m0, s101, 0xc000
	v_lshl_add_u64 v[210:211], v[154:155], 0, s[18:19]
	global_load_lds_dwordx4 v[210:211], off
	ds_read_b128 v[96:99], v220 offset:0
	ds_read_b128 v[100:103], v220 offset:2048
	ds_read_b128 v[104:107], v220 offset:4096
	ds_read_b128 v[108:111], v220 offset:6144
	ds_read_b128 v[112:115], v221 offset:0
	ds_read_b128 v[116:119], v221 offset:2048
	ds_read_b128 v[120:123], v221 offset:4096
	ds_read_b128 v[124:127], v221 offset:6144
	s_waitcnt lgkmcnt(8)
	v_mfma_f32_16x16x32_bf16 v[0:3], v[80:83], v[64:67], v[0:3]
	v_mfma_f32_16x16x32_bf16 v[4:7], v[84:87], v[64:67], v[4:7]
	s_add_u32 m0, s101, 0x9000
	v_lshl_add_u64 v[210:211], v[156:157], 0, s[18:19]
	global_load_lds_dwordx4 v[210:211], off
	v_mfma_f32_16x16x32_bf16 v[8:11], v[88:91], v[64:67], v[8:11]
	v_mfma_f32_16x16x32_bf16 v[12:15], v[92:95], v[64:67], v[12:15]
	s_add_u32 m0, s101, 0xd000
	v_lshl_add_u64 v[210:211], v[158:159], 0, s[18:19]
	global_load_lds_dwordx4 v[210:211], off
	v_mfma_f32_16x16x32_bf16 v[16:19], v[80:83], v[68:71], v[16:19]
	v_mfma_f32_16x16x32_bf16 v[20:23], v[84:87], v[68:71], v[20:23]
	s_add_u32 m0, s101, 0xa000
	v_lshl_add_u64 v[210:211], v[160:161], 0, s[18:19]
	global_load_lds_dwordx4 v[210:211], off
	v_mfma_f32_16x16x32_bf16 v[24:27], v[88:91], v[68:71], v[24:27]
	v_mfma_f32_16x16x32_bf16 v[28:31], v[92:95], v[68:71], v[28:31]
	s_add_u32 m0, s101, 0xe000
	v_lshl_add_u64 v[210:211], v[162:163], 0, s[18:19]
	global_load_lds_dwordx4 v[210:211], off
	v_mfma_f32_16x16x32_bf16 v[32:35], v[80:83], v[72:75], v[32:35]
	v_mfma_f32_16x16x32_bf16 v[36:39], v[84:87], v[72:75], v[36:39]
	s_add_u32 m0, s101, 0xb000
	v_lshl_add_u64 v[210:211], v[164:165], 0, s[18:19]
	global_load_lds_dwordx4 v[210:211], off
	v_mfma_f32_16x16x32_bf16 v[40:43], v[88:91], v[72:75], v[40:43]
	v_mfma_f32_16x16x32_bf16 v[44:47], v[92:95], v[72:75], v[44:47]
	s_add_u32 m0, s101, 0xf000
	v_lshl_add_u64 v[210:211], v[166:167], 0, s[18:19]
	global_load_lds_dwordx4 v[210:211], off
	v_mfma_f32_16x16x32_bf16 v[48:51], v[80:83], v[76:79], v[48:51]
	v_mfma_f32_16x16x32_bf16 v[52:55], v[84:87], v[76:79], v[52:55]
	v_mfma_f32_16x16x32_bf16 v[56:59], v[88:91], v[76:79], v[56:59]
	v_mfma_f32_16x16x32_bf16 v[60:63], v[92:95], v[76:79], v[60:63]
	s_waitcnt vmcnt(0)
	s_waitcnt lgkmcnt(0)
	s_barrier
; #define SB_ __builtin_amdgcn_sched_barrier(0)
; template <bool SWAP, bool HALF>
; DI void gemm_mainloop(const GemmDesc& d, int m0, int n0, bf16_t* smem, f32x16 (&acc)[2][2], int dry) {
;     ...
;   auto stage = [&](int cur, u32x4 (&ran)[4], u32x4 (&rbn)[4], int ks) {
;     ldf(cur, 1, 1); SB_;
;     mma(0); SB_;
;     ldf(cur, 2, 0); SB_;
;     lw(ran, rbn, cur ^ 1);
;     gl(ran, rbn, (ks + 3 < nk) ? ks + 3 : nk - 1);
;     SB_;
;     mma(1); SB_;
;     __syncthreads();
;     ldf(cur, 3, 1); SB_;
;     mma(0); SB_;
;     ldf(cur ^ 1, 0, 0);
;     SB_;
;     mma(1); SB_;
;     __syncthreads();
;   };
;   gl(ra0, rb0, 0);
;   gl(ra1, rb1, 1);
;   lw(ra0, rb0, 0);
;   gl(ra0, rb0, 2);
;   __syncthreads();
;   ldf(0, 0, 0);
; #pragma unroll 1
;   for (int ks = 0; ks < nk; ks += 2) {
;     stage(0, ra1, rb1, ks);
;     stage(1, ra0, rb0, ks + 1);
;   }
.LBB0_627:
	ds_read_b128 v[64:67], v168 offset:32768
	ds_read_b128 v[68:71], v168 offset:34816
	ds_read_b128 v[72:75], v168 offset:36864
	ds_read_b128 v[76:79], v168 offset:38912
	ds_read_b128 v[80:83], v169 offset:32768
	ds_read_b128 v[84:87], v169 offset:34816
	ds_read_b128 v[88:91], v169 offset:36864
	ds_read_b128 v[92:95], v169 offset:38912
	s_add_i32 s4, s4, 2
	s_add_i32 s5, s4, 2
	s_min_u32 s5, s5, 15
	s_lshl_b32 s18, s5, 7
	s_add_u32 m0, s101, 0x0
	v_lshl_add_u64 v[210:211], v[152:153], 0, s[18:19]
	global_load_lds_dwordx4 v[210:211], off
	s_add_u32 m0, s101, 0x4000
	v_lshl_add_u64 v[210:211], v[154:155], 0, s[18:19]
	global_load_lds_dwordx4 v[210:211], off
	ds_read_b128 v[128:131], v220 offset:32768
	ds_read_b128 v[132:135], v220 offset:34816
	ds_read_b128 v[136:139], v220 offset:36864
	ds_read_b128 v[140:143], v220 offset:38912
	ds_read_b128 v[192:195], v221 offset:32768
	ds_read_b128 v[196:199], v221 offset:34816
	ds_read_b128 v[200:203], v221 offset:36864
	ds_read_b128 v[204:207], v221 offset:38912
	v_mfma_f32_16x16x32_bf16 v[0:3], v[112:115], v[96:99], v[0:3]
	v_mfma_f32_16x16x32_bf16 v[4:7], v[116:119], v[96:99], v[4:7]
	s_add_u32 m0, s101, 0x1000
	v_lshl_add_u64 v[210:211], v[156:157], 0, s[18:19]
	global_load_lds_dwordx4 v[210:211], off
	v_mfma_f32_16x16x32_bf16 v[8:11], v[120:123], v[96:99], v[8:11]
	v_mfma_f32_16x16x32_bf16 v[12:15], v[124:127], v[96:99], v[12:15]
	s_add_u32 m0, s101, 0x5000
	v_lshl_add_u64 v[210:211], v[158:159], 0, s[18:19]
	global_load_lds_dwordx4 v[210:211], off
	v_mfma_f32_16x16x32_bf16 v[16:19], v[112:115], v[100:103], v[16:19]
	v_mfma_f32_16x16x32_bf16 v[20:23], v[116:119], v[100:103], v[20:23]
	s_add_u32 m0, s101, 0x2000
	v_lshl_add_u64 v[210:211], v[160:161], 0, s[18:19]
	global_load_lds_dwordx4 v[210:211], off
	v_mfma_f32_16x16x32_bf16 v[24:27], v[120:123], v[100:103], v[24:27]
	v_mfma_f32_16x16x32_bf16 v[28:31], v[124:127], v[100:103], v[28:31]
	s_add_u32 m0, s101, 0x6000
	v_lshl_add_u64 v[210:211], v[162:163], 0, s[18:19]
	global_load_lds_dwordx4 v[210:211], off
	v_mfma_f32_16x16x32_bf16 v[32:35], v[112:115], v[104:107], v[32:35]
	v_mfma_f32_16x16x32_bf16 v[36:39], v[116:119], v[104:107], v[36:39]
	s_add_u32 m0, s101, 0x3000
	v_lshl_add_u64 v[210:211], v[164:165], 0, s[18:19]
	global_load_lds_dwordx4 v[210:211], off
	v_mfma_f32_16x16x32_bf16 v[40:43], v[120:123], v[104:107], v[40:43]
	v_mfma_f32_16x16x32_bf16 v[44:47], v[124:127], v[104:107], v[44:47]
	s_add_u32 m0, s101, 0x7000
	v_lshl_add_u64 v[210:211], v[166:167], 0, s[18:19]
	global_load_lds_dwordx4 v[210:211], off
	v_mfma_f32_16x16x32_bf16 v[48:51], v[112:115], v[108:111], v[48:51]
	v_mfma_f32_16x16x32_bf16 v[52:55], v[116:119], v[108:111], v[52:55]
	v_mfma_f32_16x16x32_bf16 v[56:59], v[120:123], v[108:111], v[56:59]
	v_mfma_f32_16x16x32_bf16 v[60:63], v[124:127], v[108:111], v[60:63]
	s_waitcnt lgkmcnt(8)
	v_mfma_f32_16x16x32_bf16 v[0:3], v[80:83], v[64:67], v[0:3]
	v_mfma_f32_16x16x32_bf16 v[4:7], v[84:87], v[64:67], v[4:7]
	v_mfma_f32_16x16x32_bf16 v[8:11], v[88:91], v[64:67], v[8:11]
	v_mfma_f32_16x16x32_bf16 v[12:15], v[92:95], v[64:67], v[12:15]
	v_mfma_f32_16x16x32_bf16 v[16:19], v[80:83], v[68:71], v[16:19]
	v_mfma_f32_16x16x32_bf16 v[20:23], v[84:87], v[68:71], v[20:23]
	v_mfma_f32_16x16x32_bf16 v[24:27], v[88:91], v[68:71], v[24:27]
	v_mfma_f32_16x16x32_bf16 v[28:31], v[92:95], v[68:71], v[28:31]
	v_mfma_f32_16x16x32_bf16 v[32:35], v[80:83], v[72:75], v[32:35]
	v_mfma_f32_16x16x32_bf16 v[36:39], v[84:87], v[72:75], v[36:39]
	v_mfma_f32_16x16x32_bf16 v[40:43], v[88:91], v[72:75], v[40:43]
	v_mfma_f32_16x16x32_bf16 v[44:47], v[92:95], v[72:75], v[44:47]
	v_mfma_f32_16x16x32_bf16 v[48:51], v[80:83], v[76:79], v[48:51]
	v_mfma_f32_16x16x32_bf16 v[52:55], v[84:87], v[76:79], v[52:55]
	v_mfma_f32_16x16x32_bf16 v[56:59], v[88:91], v[76:79], v[56:59]
	v_mfma_f32_16x16x32_bf16 v[60:63], v[92:95], v[76:79], v[60:63]
	s_waitcnt vmcnt(0)
	s_waitcnt lgkmcnt(0)
	s_barrier
	ds_read_b128 v[64:67], v168 offset:0
	ds_read_b128 v[68:71], v168 offset:2048
	ds_read_b128 v[72:75], v168 offset:4096
	ds_read_b128 v[76:79], v168 offset:6144
	ds_read_b128 v[80:83], v169 offset:0
	ds_read_b128 v[84:87], v169 offset:2048
	ds_read_b128 v[88:91], v169 offset:4096
	ds_read_b128 v[92:95], v169 offset:6144
	s_add_i32 s5, s4, 3
	s_min_u32 s5, s5, 15
	s_lshl_b32 s18, s5, 7
	s_add_u32 m0, s101, 0x8000
	v_lshl_add_u64 v[210:211], v[152:153], 0, s[18:19]
	global_load_lds_dwordx4 v[210:211], off
	s_add_u32 m0, s101, 0xc000
	v_lshl_add_u64 v[210:211], v[154:155], 0, s[18:19]
	global_load_lds_dwordx4 v[210:211], off
	ds_read_b128 v[96:99], v220 offset:0
	ds_read_b128 v[100:103], v220 offset:2048
	ds_read_b128 v[104:107], v220 offset:4096
	ds_read_b128 v[108:111], v220 offset:6144
	ds_read_b128 v[112:115], v221 offset:0
	ds_read_b128 v[116:119], v221 offset:2048
	ds_read_b128 v[120:123], v221 offset:4096
	ds_read_b128 v[124:127], v221 offset:6144
	v_mfma_f32_16x16x32_bf16 v[0:3], v[192:195], v[128:131], v[0:3]
	v_mfma_f32_16x16x32_bf16 v[4:7], v[196:199], v[128:131], v[4:7]
	s_add_u32 m0, s101, 0x9000
	v_lshl_add_u64 v[210:211], v[156:157], 0, s[18:19]
	global_load_lds_dwordx4 v[210:211], off
	v_mfma_f32_16x16x32_bf16 v[8:11], v[200:203], v[128:131], v[8:11]
	v_mfma_f32_16x16x32_bf16 v[12:15], v[204:207], v[128:131], v[12:15]
	s_add_u32 m0, s101, 0xd000
	v_lshl_add_u64 v[210:211], v[158:159], 0, s[18:19]
	global_load_lds_dwordx4 v[210:211], off
	v_mfma_f32_16x16x32_bf16 v[16:19], v[192:195], v[132:135], v[16:19]
	v_mfma_f32_16x16x32_bf16 v[20:23], v[196:199], v[132:135], v[20:23]
	s_add_u32 m0, s101, 0xa000
	v_lshl_add_u64 v[210:211], v[160:161], 0, s[18:19]
	global_load_lds_dwordx4 v[210:211], off
	v_mfma_f32_16x16x32_bf16 v[24:27], v[200:203], v[132:135], v[24:27]
	v_mfma_f32_16x16x32_bf16 v[28:31], v[204:207], v[132:135], v[28:31]
	s_add_u32 m0, s101, 0xe000
	v_lshl_add_u64 v[210:211], v[162:163], 0, s[18:19]
	global_load_lds_dwordx4 v[210:211], off
	v_mfma_f32_16x16x32_bf16 v[32:35], v[192:195], v[136:139], v[32:35]
	v_mfma_f32_16x16x32_bf16 v[36:39], v[196:199], v[136:139], v[36:39]
	s_add_u32 m0, s101, 0xb000
	v_lshl_add_u64 v[210:211], v[164:165], 0, s[18:19]
	global_load_lds_dwordx4 v[210:211], off
	v_mfma_f32_16x16x32_bf16 v[40:43], v[200:203], v[136:139], v[40:43]
	v_mfma_f32_16x16x32_bf16 v[44:47], v[204:207], v[136:139], v[44:47]
	s_add_u32 m0, s101, 0xf000
	v_lshl_add_u64 v[210:211], v[166:167], 0, s[18:19]
	global_load_lds_dwordx4 v[210:211], off
	v_mfma_f32_16x16x32_bf16 v[48:51], v[192:195], v[140:143], v[48:51]
	v_mfma_f32_16x16x32_bf16 v[52:55], v[196:199], v[140:143], v[52:55]
	v_mfma_f32_16x16x32_bf16 v[56:59], v[200:203], v[140:143], v[56:59]
	v_mfma_f32_16x16x32_bf16 v[60:63], v[204:207], v[140:143], v[60:63]
	s_waitcnt lgkmcnt(8)
; DI float ssq_f(u64 v) { return (float)v * (1.f / 1048576.f); }
; #define SB_ __builtin_amdgcn_sched_barrier(0)
; template <bool SWAP, bool HALF>
; DI void gemm_mainloop(const GemmDesc& d, int m0, int n0, bf16_t* smem, f32x16 (&acc)[2][2], int dry) {
;     ...
;   auto stage = [&](int cur, u32x4 (&ran)[4], u32x4 (&rbn)[4], int ks) {
;     ldf(cur, 1, 1); SB_;
;     mma(0); SB_;
;     ldf(cur, 2, 0); SB_;
;     lw(ran, rbn, cur ^ 1);
;     gl(ran, rbn, (ks + 3 < nk) ? ks + 3 : nk - 1);
;     SB_;
;     mma(1); SB_;
;     __syncthreads();
;     ldf(cur, 3, 1); SB_;
;     mma(0); SB_;
;     ldf(cur ^ 1, 0, 0);
;     SB_;
;     mma(1); SB_;
;     __syncthreads();
;   };
;   gl(ra0, rb0, 0);
;   gl(ra1, rb1, 1);
;   lw(ra0, rb0, 0);
;   gl(ra0, rb0, 2);
;   __syncthreads();
;   ldf(0, 0, 0);
; #pragma unroll 1
;   for (int ks = 0; ks < nk; ks += 2) {
;     stage(0, ra1, rb1, ks);
;     stage(1, ra0, rb0, ks + 1);
;   }
; DI void gemm_tile(const GemmDesc& d, int m0, int n0, bf16_t* smem, int dry) {
;     ...
;   } else if (t < 128) {
;     rs_s[t] = rsqrtf(ssq_f(myss) * d.inv_dim + EPS);
;   }
	v_mfma_f32_16x16x32_bf16 v[0:3], v[80:83], v[64:67], v[0:3]
	v_mfma_f32_16x16x32_bf16 v[4:7], v[84:87], v[64:67], v[4:7]
	v_mfma_f32_16x16x32_bf16 v[8:11], v[88:91], v[64:67], v[8:11]
	v_mfma_f32_16x16x32_bf16 v[12:15], v[92:95], v[64:67], v[12:15]
	v_mfma_f32_16x16x32_bf16 v[16:19], v[80:83], v[68:71], v[16:19]
	v_mfma_f32_16x16x32_bf16 v[20:23], v[84:87], v[68:71], v[20:23]
	v_mfma_f32_16x16x32_bf16 v[24:27], v[88:91], v[68:71], v[24:27]
	v_mfma_f32_16x16x32_bf16 v[28:31], v[92:95], v[68:71], v[28:31]
	v_mfma_f32_16x16x32_bf16 v[32:35], v[80:83], v[72:75], v[32:35]
	v_mfma_f32_16x16x32_bf16 v[36:39], v[84:87], v[72:75], v[36:39]
	v_mfma_f32_16x16x32_bf16 v[40:43], v[88:91], v[72:75], v[40:43]
	v_mfma_f32_16x16x32_bf16 v[44:47], v[92:95], v[72:75], v[44:47]
	v_mfma_f32_16x16x32_bf16 v[48:51], v[80:83], v[76:79], v[48:51]
	v_mfma_f32_16x16x32_bf16 v[52:55], v[84:87], v[76:79], v[52:55]
	v_mfma_f32_16x16x32_bf16 v[56:59], v[88:91], v[76:79], v[56:59]
	v_mfma_f32_16x16x32_bf16 v[60:63], v[92:95], v[76:79], v[60:63]
	s_cmp_lt_u32 s4, 12
	s_waitcnt vmcnt(0)
	s_waitcnt lgkmcnt(0)
	s_barrier
	s_cbranch_scc1 .LBB0_627
	ds_read_b128 v[64:67], v168 offset:32768
	ds_read_b128 v[68:71], v168 offset:34816
	ds_read_b128 v[72:75], v168 offset:36864
	ds_read_b128 v[76:79], v168 offset:38912
	ds_read_b128 v[80:83], v169 offset:32768
	ds_read_b128 v[84:87], v169 offset:34816
	ds_read_b128 v[88:91], v169 offset:36864
	ds_read_b128 v[92:95], v169 offset:38912
	ds_read_b128 v[128:131], v220 offset:32768
	ds_read_b128 v[132:135], v220 offset:34816
	ds_read_b128 v[136:139], v220 offset:36864
	ds_read_b128 v[140:143], v220 offset:38912
	ds_read_b128 v[192:195], v221 offset:32768
	ds_read_b128 v[196:199], v221 offset:34816
	ds_read_b128 v[200:203], v221 offset:36864
	ds_read_b128 v[204:207], v221 offset:38912
	v_mfma_f32_16x16x32_bf16 v[0:3], v[112:115], v[96:99], v[0:3]
	v_mfma_f32_16x16x32_bf16 v[4:7], v[116:119], v[96:99], v[4:7]
	v_mfma_f32_16x16x32_bf16 v[8:11], v[120:123], v[96:99], v[8:11]
	v_mfma_f32_16x16x32_bf16 v[12:15], v[124:127], v[96:99], v[12:15]
	v_mfma_f32_16x16x32_bf16 v[16:19], v[112:115], v[100:103], v[16:19]
	v_mfma_f32_16x16x32_bf16 v[20:23], v[116:119], v[100:103], v[20:23]
	v_mfma_f32_16x16x32_bf16 v[24:27], v[120:123], v[100:103], v[24:27]
	v_mfma_f32_16x16x32_bf16 v[28:31], v[124:127], v[100:103], v[28:31]
	v_mfma_f32_16x16x32_bf16 v[32:35], v[112:115], v[104:107], v[32:35]
	v_mfma_f32_16x16x32_bf16 v[36:39], v[116:119], v[104:107], v[36:39]
	v_mfma_f32_16x16x32_bf16 v[40:43], v[120:123], v[104:107], v[40:43]
	v_mfma_f32_16x16x32_bf16 v[44:47], v[124:127], v[104:107], v[44:47]
	v_mfma_f32_16x16x32_bf16 v[48:51], v[112:115], v[108:111], v[48:51]
	v_mfma_f32_16x16x32_bf16 v[52:55], v[116:119], v[108:111], v[52:55]
	v_mfma_f32_16x16x32_bf16 v[56:59], v[120:123], v[108:111], v[56:59]
	v_mfma_f32_16x16x32_bf16 v[60:63], v[124:127], v[108:111], v[60:63]
	s_waitcnt lgkmcnt(8)
	v_mfma_f32_16x16x32_bf16 v[0:3], v[80:83], v[64:67], v[0:3]
	v_mfma_f32_16x16x32_bf16 v[4:7], v[84:87], v[64:67], v[4:7]
	v_mfma_f32_16x16x32_bf16 v[8:11], v[88:91], v[64:67], v[8:11]
	v_mfma_f32_16x16x32_bf16 v[12:15], v[92:95], v[64:67], v[12:15]
	v_mfma_f32_16x16x32_bf16 v[16:19], v[80:83], v[68:71], v[16:19]
	v_mfma_f32_16x16x32_bf16 v[20:23], v[84:87], v[68:71], v[20:23]
	v_mfma_f32_16x16x32_bf16 v[24:27], v[88:91], v[68:71], v[24:27]
	v_mfma_f32_16x16x32_bf16 v[28:31], v[92:95], v[68:71], v[28:31]
	v_mfma_f32_16x16x32_bf16 v[32:35], v[80:83], v[72:75], v[32:35]
	v_mfma_f32_16x16x32_bf16 v[36:39], v[84:87], v[72:75], v[36:39]
	v_mfma_f32_16x16x32_bf16 v[40:43], v[88:91], v[72:75], v[40:43]
	v_mfma_f32_16x16x32_bf16 v[44:47], v[92:95], v[72:75], v[44:47]
	v_mfma_f32_16x16x32_bf16 v[48:51], v[80:83], v[76:79], v[48:51]
	v_mfma_f32_16x16x32_bf16 v[52:55], v[84:87], v[76:79], v[52:55]
	v_mfma_f32_16x16x32_bf16 v[56:59], v[88:91], v[76:79], v[56:59]
	v_mfma_f32_16x16x32_bf16 v[60:63], v[92:95], v[76:79], v[60:63]
	s_waitcnt lgkmcnt(0)
	s_barrier
	v_mfma_f32_16x16x32_bf16 v[0:3], v[192:195], v[128:131], v[0:3]
	v_mfma_f32_16x16x32_bf16 v[4:7], v[196:199], v[128:131], v[4:7]
	v_mfma_f32_16x16x32_bf16 v[8:11], v[200:203], v[128:131], v[8:11]
	v_mfma_f32_16x16x32_bf16 v[12:15], v[204:207], v[128:131], v[12:15]
	v_mfma_f32_16x16x32_bf16 v[16:19], v[192:195], v[132:135], v[16:19]
	v_mfma_f32_16x16x32_bf16 v[20:23], v[196:199], v[132:135], v[20:23]
	v_mfma_f32_16x16x32_bf16 v[24:27], v[200:203], v[132:135], v[24:27]
	v_mfma_f32_16x16x32_bf16 v[28:31], v[204:207], v[132:135], v[28:31]
	v_mfma_f32_16x16x32_bf16 v[32:35], v[192:195], v[136:139], v[32:35]
	v_mfma_f32_16x16x32_bf16 v[36:39], v[196:199], v[136:139], v[36:39]
	v_mfma_f32_16x16x32_bf16 v[40:43], v[200:203], v[136:139], v[40:43]
	v_mfma_f32_16x16x32_bf16 v[44:47], v[204:207], v[136:139], v[44:47]
	v_mfma_f32_16x16x32_bf16 v[48:51], v[192:195], v[140:143], v[48:51]
	v_mfma_f32_16x16x32_bf16 v[52:55], v[196:199], v[140:143], v[52:55]
	v_mfma_f32_16x16x32_bf16 v[56:59], v[200:203], v[140:143], v[56:59]
	v_mfma_f32_16x16x32_bf16 v[60:63], v[204:207], v[140:143], v[60:63]
	s_and_saveexec_b64 s[4:5], vcc
	s_cbranch_execz .LBB0_630
	s_mov_b32 s8, 0x800000
	s_waitcnt vmcnt(15)
	v_mul_f32_e32 v64, 0x4b800000, v170
	v_cmp_gt_f32_e32 vcc, s8, v170
	v_lshl_add_u32 v65, v150, 2, v181
	s_nop 0
	v_cndmask_b32_e32 v64, v170, v64, vcc
	v_rsq_f32_e32 v64, v64
	s_nop 0
	v_mul_f32_e32 v66, 0x45800000, v64
	v_cndmask_b32_e32 v64, v64, v66, vcc
	ds_write_b32 v65, v64
; DI void gemm_tile(const GemmDesc& d, int m0, int n0, bf16_t* smem, int dry) {
;     ...
; #pragma unroll
;     for (int a = 0; a < 2; ++a)
; #pragma unroll
;       for (int b = 0; b < 2; ++b)
; #pragma unroll
;         for (int g = 0; g < 4; ++g) {
;           f32x4 o;
; #pragma unroll
;           for (int j = 0; j < 4; ++j) o[j] = acc[a][b][4 * g + j];
;           *(f32x4*)(Ct + (wm * 64 + a * 32 + r) * CS + wn * 64 + b * 32 + 8 * g + 4 * hh) = o;
;         }
;   }
;   __syncthreads();
;     ...
;   } else if (n0 < d.n1end) {
;     bf16_t* dst; int ld, nb;
;     if (n0 < d.n0end) { dst = d.d0; ld = d.ld0; nb = n0; } else { dst = d.d1; ld = d.ld1; nb = n0 - d.n0end; }
;     unsigned* kq = (d.kmax && n0 >= d.n0end) ? d.kmax : nullptr;
;     const int mlast = (m0 + 127) < M ? (m0 + 127) : M - 1;
;     const bool onebatch = (m0 / L) == (mlast / L);
;     float kmx = 0.f;
;     u64* sq = nullptr;
;     if (d.ssq_a) { if (n0 < d.ssq_a_end) sq = d.ssq_a; else if (n0 < d.ssq_b_end) sq = d.ssq_b; }
; #pragma unroll 4
;     for (int pass = 0; pass < 16; ++pass) {
;       const int row = pass * 8 + (t >> 5), c4 = t & 31, m = m0 + row;
;       float part = 0.f, kpart = 0.f;
.LBB0_630:
	s_or_b64 exec, exec, s[4:5]
	s_waitcnt vmcnt(15)
	v_and_b32_e32 v64, 31, v150
	v_lshrrev_b32_e32 v65, 1, v150
	v_and_or_b32 v67, v65, s72, v64
	v_lshlrev_b32_e32 v66, 2, v150
	v_and_b32_e32 v65, 16, v65
	s_movk_i32 s4, 0x100
	v_and_or_b32 v66, v66, s4, v65
	s_cmp_gt_i32 s10, 5
	v_mad_u64_u32 v[66:67], s[4:5], v67, s22, v[66:67]
	v_and_b32_e32 v212, 15, v172
	v_lshrrev_b32_e32 v213, 1, v172
	v_and_or_b32 v212, v213, s72, v212
	v_lshlrev_b32_e32 v213, 2, v172
	v_and_b32_e32 v214, 0x30, v172
	v_and_b32_e32 v213, 0x100, v213
	v_or_b32_e32 v213, v213, v214
	v_mad_u32_u24 v66, v212, s22, v213
	ds_write_b128 v66, v[0:3]
	ds_write_b128 v66, v[4:7] offset:64
	ds_write_b128 v66, v[8:11] offset:128
	ds_write_b128 v66, v[12:15] offset:192
	ds_write_b128 v66, v[16:19] offset:8448
	ds_write_b128 v66, v[20:23] offset:8512
	ds_write_b128 v66, v[24:27] offset:8576
	ds_write_b128 v66, v[28:31] offset:8640
	ds_write_b128 v66, v[32:35] offset:16896
	ds_write_b128 v66, v[36:39] offset:16960
	ds_write_b128 v66, v[40:43] offset:17024
	ds_write_b128 v66, v[44:47] offset:17088
	ds_write_b128 v66, v[48:51] offset:25344
	ds_write_b128 v66, v[52:55] offset:25408
	ds_write_b128 v66, v[56:59] offset:25472
	ds_write_b128 v66, v[60:63] offset:25536
	s_waitcnt lgkmcnt(0)
	s_barrier
	s_cbranch_scc1 .LBB0_623
	s_lshl_b32 s16, s7, 13
	s_cmp_lg_u32 s10, 5
	v_readlane_b32 s4, v229, 10
	s_cselect_b64 s[8:9], -1, 0
	s_cmp_eq_u32 s10, 5
	v_readlane_b32 s5, v229, 11
	s_cselect_b32 s4, 0, s4
	s_cselect_b32 s5, 0, s5
	s_cmp_gt_i32 s10, 2
	s_cselect_b32 s11, s5, s25
	s_cselect_b32 s10, s4, s24
	s_ashr_i32 s7, s6, 31
	s_lshl_b64 s[4:5], s[6:7], 1
	s_add_u32 s4, s66, s4
	s_addc_u32 s5, s67, s5
	v_lshlrev_b32_e32 v144, 3, v64
	v_ashrrev_i32_e32 v2, 5, v150
	v_lshl_add_u64 v[0:1], s[4:5], 0, v[144:145]
	s_add_i32 s4, s12, s13
	v_mul_lo_u32 v4, v2, s22
	s_sub_i32 s4, s4, s14
	v_lshl_add_u32 v6, v64, 4, v4
	v_add_u32_e32 v4, s29, v2
	s_lshl_b32 s4, s4, 10
	v_add_u32_e32 v8, s4, v4
	s_or_b32 s4, s29, s4
	v_ashrrev_i32_e32 v3, 31, v2
	s_ashr_i32 s5, s4, 31
	v_lshlrev_b32_e32 v7, 2, v2
	v_lshl_add_u64 v[2:3], v[2:3], 0, s[4:5]
	v_lshl_add_u64 v[2:3], v[2:3], 3, s[10:11]
	s_mov_b64 s[4:5], 0x80
	v_lshl_add_u64 v[2:3], v[2:3], 0, s[4:5]
	s_lshl_b32 s4, s12, 10
	s_add_i32 s4, s4, s16
	v_add_u32_e32 v4, s4, v4
	s_lshl_b32 s4, s14, 10
	s_mov_b32 s15, 0
	v_cmp_eq_u32_e64 s[42:43], 0, v64
	v_subrev_u32_e32 v9, s4, v4
	s_branch .LBB0_634

; __global__ void __launch_bounds__(NTHREADS, 2) fwd_kernel(Params p, int ph_begin, int ph_end) {
;     ...
;   for (int l = 0; l < 4; ++l) {
.Ltramp_171:
	s_branch .LBB0_171

; DI int otid() { int t = threadIdx.x; asm volatile("" : "+v"(t)); return t; }
; template <bool SWAP, bool HALF>
; DI void gemm_mainloop(const GemmDesc& d, int m0, int n0, bf16_t* smem, f32x16 (&acc)[2][2], int dry) {
;   const int t = otid(), lane = t & 63, w = t >> 6, wm = w >> 1, wn = w & 1, r = lane & 31, hh = lane >> 5;
;   const int lrow = t >> 3, lkc = t & 7;
;   const bf16_t* ap[4]; const bf16_t* bp[4];
; #pragma unroll
;   for (int i = 0; i < 4; ++i) {
;     int am = m0 + lrow + 32 * i; am = am < M ? am : M - 1;
;     ap[i] = d.A + (size_t)am * d.lda + lkc * 8 + (d.a_grp ? (n0 / d.a_grp) * d.a_grp : 0);
;     bp[i] = d.Bt + (size_t)(n0 + lrow + 32 * i) * d.ldb + lkc * 8;
; DI void gemm_tile(const GemmDesc& d, int m0, int n0, bf16_t* smem, int dry) {
;     ...
;   const bool vtile = (d.epi == EPI_STORE) && (n0 >= d.n1end) && (n0 < d.nvend);
;   float* rs_s = (float*)((unsigned char*)smem + 128 * CS * 4);
;   u64 myss = 0ull;
;   if (d.ssq_in && t < 128) { const int mr = (m0 + t) < M ? (m0 + t) : M - 1; myss = d.ssq_in[mr]; }
;   if (vtile) {
.LBB0_1002:
	s_or_b64 exec, exec, s[4:5]
	s_lshl_b32 s1, s14, 7
	s_and_b32 s4, s14, -8
	s_waitcnt vmcnt(0)
	v_ashrrev_i32_e32 v187, 7, v150
	v_bfe_u32 v188, v150, 6, 1
	v_and_b32_e32 v170, 31, v150
	v_bfe_u32 v189, v150, 5, 1
	s_cmp_lg_u32 s4, 16
	s_mov_b64 s[4:5], -1
	s_cbranch_scc0 .LBB0_1018
	v_mov_b32_e32 v32, v172
	v_readlane_b32 s76, v228, 60
	v_ashrrev_i32_e32 v10, 3, v32
	v_lshlrev_b32_e32 v0, 3, v32
	v_and_b32_e32 v33, 56, v0
	v_add_u32_e32 v2, s1, v10
	v_lshlrev_b32_e32 v144, 1, v33
	v_readlane_b32 s78, v228, 62
	v_readlane_b32 s79, v228, 63
	v_ashrrev_i32_e32 v3, 31, v2
	v_add_u32_e32 v11, s9, v10
	v_lshl_add_u64 v[4:5], s[78:79], 0, v[144:145]
	v_lshlrev_b64 v[2:3], 11, v[2:3]
	v_lshl_add_u64 v[154:155], v[4:5], 0, v[2:3]
	v_min_i32_e32 v2, 0x801f, v11
	v_ashrrev_i32_e32 v3, 31, v2
	v_lshl_add_u64 v[0:1], s[56:57], 0, v[144:145]
	v_lshlrev_b64 v[2:3], 11, v[2:3]
	v_lshl_add_u64 v[8:9], v[0:1], 0, v[2:3]
	v_min_i32_e32 v2, 0x7fff, v11
	v_ashrrev_i32_e32 v3, 31, v2
	v_min_i32_e32 v6, 0x803f, v11
	v_lshlrev_b64 v[2:3], 11, v[2:3]
	v_ashrrev_i32_e32 v7, 31, v6
	v_lshl_add_u64 v[16:17], v[0:1], 0, v[2:3]
	v_min_i32_e32 v2, 0x7fdf, v11
	v_lshlrev_b64 v[6:7], 11, v[6:7]
	v_ashrrev_i32_e32 v3, 31, v2
	v_lshl_add_u64 v[152:153], v[0:1], 0, v[6:7]
	v_lshlrev_b64 v[2:3], 11, v[2:3]
	v_lshl_add_u64 v[24:25], v[0:1], 0, v[2:3]
	s_mov_b64 s[4:5], 0x10000
	v_lshl_add_u64 v[156:157], v[8:9], 0, s[4:5]
	v_lshl_add_u64 v[158:159], v[154:155], 0, s[4:5]
	s_mov_b64 s[4:5], 0x20000
	v_lshl_add_u64 v[160:161], v[16:17], 0, s[4:5]
	v_lshl_add_u64 v[162:163], v[154:155], 0, s[4:5]
	s_mov_b64 s[4:5], 0x30000
	v_lshl_add_u64 v[164:165], v[24:25], 0, s[4:5]
	v_lshl_add_u64 v[166:167], v[154:155], 0, s[4:5]
	s_movk_i32 s4, 0x48
	v_and_b32_e32 v34, 31, v32
	v_mul_lo_u32 v35, v10, s4
	v_readlane_b32 s77, v228, 61
	v_readlane_b32 s80, v223, 0
	v_readlane_b32 s81, v223, 1
	v_readlane_b32 s82, v223, 2
	v_readlane_b32 s83, v223, 3
	v_readlane_b32 s84, v223, 4
	v_readlane_b32 s85, v223, 5
	v_readlane_b32 s86, v223, 6
	v_readlane_b32 s87, v223, 7
	v_readlane_b32 s88, v223, 8
	v_readlane_b32 s89, v223, 9
	v_readlane_b32 s90, v223, 10
	v_readlane_b32 s91, v223, 11
	s_mov_b32 s4, 0x10000
	v_add_co_u32_e32 v8, vcc, s4, v8
	s_nop 1
	v_addc_co_u32_e32 v9, vcc, 0, v9, vcc
	v_add_co_u32_e32 v12, vcc, s4, v154
	s_nop 1
	v_addc_co_u32_e32 v13, vcc, 0, v155, vcc
	s_mov_b32 s4, 0x20000
	v_add_co_u32_e32 v16, vcc, s4, v16
	s_nop 1
	v_addc_co_u32_e32 v17, vcc, 0, v17, vcc
	v_add_co_u32_e32 v20, vcc, s4, v154
	s_nop 1
	v_addc_co_u32_e32 v21, vcc, 0, v155, vcc
	s_mov_b32 s4, 0x30000
	v_add_co_u32_e32 v24, vcc, s4, v24
	s_nop 1
	v_addc_co_u32_e32 v25, vcc, 0, v25, vcc
	v_add_co_u32_e32 v28, vcc, s4, v154
	s_nop 1
	v_addc_co_u32_e32 v29, vcc, 0, v155, vcc
	s_nop 0
	v_add_lshl_u32 v144, v35, v33, 1
	s_waitcnt vmcnt(15)
	s_waitcnt vmcnt(14)
	s_waitcnt vmcnt(13)
	s_waitcnt vmcnt(12)
	s_waitcnt vmcnt(11)
	s_waitcnt vmcnt(10)
	s_waitcnt vmcnt(9)
	s_waitcnt vmcnt(8)
	v_lshrrev_b32_e32 v0, 1, v32
	v_and_or_b32 v1, v0, s72, v34
	v_and_b32_e32 v0, 16, v0
	s_movk_i32 s4, 0x90
	v_mad_u64_u32 v[168:169], s[4:5], v1, s4, v[0:1]
	v_and_b32_e32 v1, 0x5f, v32
	v_mul_u32_u24_e32 v1, 0x48, v1
	v_lshl_add_u32 v169, v1, 1, v0
	v_bfe_u32 v212, v172, 4, 3
	v_lshlrev_b32_e32 v212, 4, v212
	v_xor_b32_e32 v152, v152, v212
	v_xor_b32_e32 v154, v154, v212
	v_xor_b32_e32 v156, v156, v212
	v_xor_b32_e32 v158, v158, v212
	v_xor_b32_e32 v160, v160, v212
	v_xor_b32_e32 v162, v162, v212
	v_xor_b32_e32 v164, v164, v212
	v_xor_b32_e32 v166, v166, v212
	v_lshrrev_b32_e32 v213, 6, v172
	s_nop 1
	v_readfirstlane_b32 s101, v213
	s_lshl_b32 s101, s101, 10
	s_add_u32 m0, s101, 0x0
	s_nop 0
	global_load_lds_dwordx4 v[152:153], off
	s_add_u32 m0, s101, 0x4000
	s_nop 0
	global_load_lds_dwordx4 v[154:155], off
	s_add_u32 m0, s101, 0x1000
	s_nop 0
	global_load_lds_dwordx4 v[156:157], off
	s_add_u32 m0, s101, 0x5000
	s_nop 0
	global_load_lds_dwordx4 v[158:159], off
	s_add_u32 m0, s101, 0x2000
	s_nop 0
	global_load_lds_dwordx4 v[160:161], off
	s_add_u32 m0, s101, 0x6000
	s_nop 0
	global_load_lds_dwordx4 v[162:163], off
	s_add_u32 m0, s101, 0x3000
	s_nop 0
	global_load_lds_dwordx4 v[164:165], off
	s_add_u32 m0, s101, 0x7000
	s_nop 0
	global_load_lds_dwordx4 v[166:167], off
	v_and_b32_e32 v212, 15, v172
	v_bfe_u32 v213, v172, 4, 2
	v_lshrrev_b32_e32 v214, 1, v212
	v_xor_b32_e32 v213, v213, v214
	v_lshlrev_b32_e32 v213, 4, v213
	v_lshl_or_b32 v212, v212, 7, v213
	v_lshrrev_b32_e32 v214, 7, v172
	v_lshl_add_u32 v168, v214, 13, v212
	v_bfe_u32 v214, v172, 6, 1
	v_lshl_add_u32 v169, v214, 13, v212
	v_add_u32_e32 v169, 0x4000, v169
	v_xor_b32_e32 v220, 64, v168
	v_xor_b32_e32 v221, 64, v169
	s_waitcnt vmcnt(0)
	s_waitcnt lgkmcnt(0)
	s_barrier
; #define SB_ __builtin_amdgcn_sched_barrier(0)
; template <bool SWAP, bool HALF>
; DI void gemm_mainloop(const GemmDesc& d, int m0, int n0, bf16_t* smem, f32x16 (&acc)[2][2], int dry) {
;     ...
; #pragma unroll
;   for (int a = 0; a < 2; ++a)
; #pragma unroll
;     for (int b = 0; b < 2; ++b)
; #pragma unroll
;       for (int i = 0; i < 16; ++i) acc[a][b][i] = 0.f;
;     ...
;   auto stage = [&](int cur, u32x4 (&ran)[4], u32x4 (&rbn)[4], int ks) {
;     ldf(cur, 1, 1); SB_;
;     mma(0); SB_;
;     ldf(cur, 2, 0); SB_;
;     lw(ran, rbn, cur ^ 1);
;     gl(ran, rbn, (ks + 3 < nk) ? ks + 3 : nk - 1);
;     SB_;
;     mma(1); SB_;
;     __syncthreads();
;     ldf(cur, 3, 1); SB_;
;     mma(0); SB_;
;     ldf(cur ^ 1, 0, 0);
;     SB_;
;     mma(1); SB_;
;     __syncthreads();
;   };
	v_mov_b32_e32 v0, 0
	v_add_u32_e32 v190, 0x9000, v144
	s_mov_b32 s4, -2
	v_mov_b32_e32 v1, v0
	v_mov_b32_e32 v2, v0
	v_mov_b32_e32 v3, v0
	v_mov_b32_e32 v4, v0
	v_mov_b32_e32 v5, v0
	v_mov_b32_e32 v6, v0
	v_mov_b32_e32 v7, v0
	v_mov_b32_e32 v8, v0
	v_mov_b32_e32 v9, v0
	v_mov_b32_e32 v10, v0
	v_mov_b32_e32 v11, v0
	v_mov_b32_e32 v12, v0
	v_mov_b32_e32 v13, v0
	v_mov_b32_e32 v14, v0
	v_mov_b32_e32 v15, v0
	v_mov_b32_e32 v16, v0
	v_mov_b32_e32 v17, v0
	v_mov_b32_e32 v18, v0
	v_mov_b32_e32 v19, v0
	v_mov_b32_e32 v20, v0
	v_mov_b32_e32 v21, v0
	v_mov_b32_e32 v22, v0
	v_mov_b32_e32 v23, v0
	v_mov_b32_e32 v24, v0
	v_mov_b32_e32 v25, v0
	v_mov_b32_e32 v26, v0
	v_mov_b32_e32 v27, v0
	v_mov_b32_e32 v28, v0
	v_mov_b32_e32 v29, v0
	v_mov_b32_e32 v30, v0
	v_mov_b32_e32 v31, v0
	v_mov_b32_e32 v32, v0
	v_mov_b32_e32 v33, v0
	v_mov_b32_e32 v34, v0
	v_mov_b32_e32 v35, v0
	v_mov_b32_e32 v36, v0
	v_mov_b32_e32 v37, v0
	v_mov_b32_e32 v38, v0
	v_mov_b32_e32 v39, v0
	v_mov_b32_e32 v40, v0
	v_mov_b32_e32 v41, v0
	v_mov_b32_e32 v42, v0
	v_mov_b32_e32 v43, v0
	v_mov_b32_e32 v44, v0
	v_mov_b32_e32 v45, v0
	v_mov_b32_e32 v46, v0
	v_mov_b32_e32 v47, v0
	v_mov_b32_e32 v48, v0
	v_mov_b32_e32 v49, v0
	v_mov_b32_e32 v50, v0
	v_mov_b32_e32 v51, v0
	v_mov_b32_e32 v52, v0
	v_mov_b32_e32 v53, v0
	v_mov_b32_e32 v54, v0
	v_mov_b32_e32 v55, v0
	v_mov_b32_e32 v56, v0
	v_mov_b32_e32 v57, v0
	v_mov_b32_e32 v58, v0
	v_mov_b32_e32 v59, v0
	v_mov_b32_e32 v60, v0
	v_mov_b32_e32 v61, v0
	v_mov_b32_e32 v62, v0
	v_mov_b32_e32 v63, v0
	ds_read_b128 v[64:67], v168 offset:0
	ds_read_b128 v[68:71], v168 offset:2048
	ds_read_b128 v[72:75], v168 offset:4096
	ds_read_b128 v[76:79], v168 offset:6144
	ds_read_b128 v[80:83], v169 offset:0
	ds_read_b128 v[84:87], v169 offset:2048
	ds_read_b128 v[88:91], v169 offset:4096
	ds_read_b128 v[92:95], v169 offset:6144
	s_add_i32 s5, s4, 3
	s_min_u32 s5, s5, 15
	s_lshl_b32 s18, s5, 7
	s_add_u32 m0, s101, 0x8000
	v_lshl_add_u64 v[210:211], v[152:153], 0, s[18:19]
	global_load_lds_dwordx4 v[210:211], off
	s_add_u32 m0, s101, 0xc000
	v_lshl_add_u64 v[210:211], v[154:155], 0, s[18:19]
	global_load_lds_dwordx4 v[210:211], off
	ds_read_b128 v[96:99], v220 offset:0
	ds_read_b128 v[100:103], v220 offset:2048
	ds_read_b128 v[104:107], v220 offset:4096
	ds_read_b128 v[108:111], v220 offset:6144
	ds_read_b128 v[112:115], v221 offset:0
	ds_read_b128 v[116:119], v221 offset:2048
	ds_read_b128 v[120:123], v221 offset:4096
	ds_read_b128 v[124:127], v221 offset:6144
	s_waitcnt lgkmcnt(8)
	v_mfma_f32_16x16x32_bf16 v[0:3], v[80:83], v[64:67], v[0:3]
	v_mfma_f32_16x16x32_bf16 v[4:7], v[84:87], v[64:67], v[4:7]
	s_add_u32 m0, s101, 0x9000
	v_lshl_add_u64 v[210:211], v[156:157], 0, s[18:19]
	global_load_lds_dwordx4 v[210:211], off
	v_mfma_f32_16x16x32_bf16 v[8:11], v[88:91], v[64:67], v[8:11]
	v_mfma_f32_16x16x32_bf16 v[12:15], v[92:95], v[64:67], v[12:15]
	s_add_u32 m0, s101, 0xd000
	v_lshl_add_u64 v[210:211], v[158:159], 0, s[18:19]
	global_load_lds_dwordx4 v[210:211], off
	v_mfma_f32_16x16x32_bf16 v[16:19], v[80:83], v[68:71], v[16:19]
	v_mfma_f32_16x16x32_bf16 v[20:23], v[84:87], v[68:71], v[20:23]
	s_add_u32 m0, s101, 0xa000
	v_lshl_add_u64 v[210:211], v[160:161], 0, s[18:19]
	global_load_lds_dwordx4 v[210:211], off
	v_mfma_f32_16x16x32_bf16 v[24:27], v[88:91], v[68:71], v[24:27]
	v_mfma_f32_16x16x32_bf16 v[28:31], v[92:95], v[68:71], v[28:31]
	s_add_u32 m0, s101, 0xe000
	v_lshl_add_u64 v[210:211], v[162:163], 0, s[18:19]
	global_load_lds_dwordx4 v[210:211], off
	v_mfma_f32_16x16x32_bf16 v[32:35], v[80:83], v[72:75], v[32:35]
	v_mfma_f32_16x16x32_bf16 v[36:39], v[84:87], v[72:75], v[36:39]
	s_add_u32 m0, s101, 0xb000
	v_lshl_add_u64 v[210:211], v[164:165], 0, s[18:19]
	global_load_lds_dwordx4 v[210:211], off
	v_mfma_f32_16x16x32_bf16 v[40:43], v[88:91], v[72:75], v[40:43]
	v_mfma_f32_16x16x32_bf16 v[44:47], v[92:95], v[72:75], v[44:47]
	s_add_u32 m0, s101, 0xf000
	v_lshl_add_u64 v[210:211], v[166:167], 0, s[18:19]
	global_load_lds_dwordx4 v[210:211], off
	v_mfma_f32_16x16x32_bf16 v[48:51], v[80:83], v[76:79], v[48:51]
	v_mfma_f32_16x16x32_bf16 v[52:55], v[84:87], v[76:79], v[52:55]
	v_mfma_f32_16x16x32_bf16 v[56:59], v[88:91], v[76:79], v[56:59]
	v_mfma_f32_16x16x32_bf16 v[60:63], v[92:95], v[76:79], v[60:63]
	s_waitcnt vmcnt(0)
	s_waitcnt lgkmcnt(0)
	s_barrier
; #define SB_ __builtin_amdgcn_sched_barrier(0)
; template <bool SWAP, bool HALF>
; DI void gemm_mainloop(const GemmDesc& d, int m0, int n0, bf16_t* smem, f32x16 (&acc)[2][2], int dry) {
;     ...
;   auto stage = [&](int cur, u32x4 (&ran)[4], u32x4 (&rbn)[4], int ks) {
;     ldf(cur, 1, 1); SB_;
;     mma(0); SB_;
;     ldf(cur, 2, 0); SB_;
;     lw(ran, rbn, cur ^ 1);
;     gl(ran, rbn, (ks + 3 < nk) ? ks + 3 : nk - 1);
;     SB_;
;     mma(1); SB_;
;     __syncthreads();
;     ldf(cur, 3, 1); SB_;
;     mma(0); SB_;
;     ldf(cur ^ 1, 0, 0);
;     SB_;
;     mma(1); SB_;
;     __syncthreads();
;   };
;   gl(ra0, rb0, 0);
;   gl(ra1, rb1, 1);
;   lw(ra0, rb0, 0);
;   gl(ra0, rb0, 2);
;   __syncthreads();
;   ldf(0, 0, 0);
; #pragma unroll 1
;   for (int ks = 0; ks < nk; ks += 2) {
;     stage(0, ra1, rb1, ks);
;     stage(1, ra0, rb0, ks + 1);
;   }
.LBB0_1004:
	ds_read_b128 v[64:67], v168 offset:32768
	ds_read_b128 v[68:71], v168 offset:34816
	ds_read_b128 v[72:75], v168 offset:36864
	ds_read_b128 v[76:79], v168 offset:38912
	ds_read_b128 v[80:83], v169 offset:32768
	ds_read_b128 v[84:87], v169 offset:34816
	ds_read_b128 v[88:91], v169 offset:36864
	ds_read_b128 v[92:95], v169 offset:38912
	s_add_i32 s4, s4, 2
	s_add_i32 s5, s4, 2
	s_min_u32 s5, s5, 15
	s_lshl_b32 s18, s5, 7
	s_add_u32 m0, s101, 0x0
	v_lshl_add_u64 v[210:211], v[152:153], 0, s[18:19]
	global_load_lds_dwordx4 v[210:211], off
	s_add_u32 m0, s101, 0x4000
	v_lshl_add_u64 v[210:211], v[154:155], 0, s[18:19]
	global_load_lds_dwordx4 v[210:211], off
	ds_read_b128 v[128:131], v220 offset:32768
	ds_read_b128 v[132:135], v220 offset:34816
	ds_read_b128 v[136:139], v220 offset:36864
	ds_read_b128 v[140:143], v220 offset:38912
	ds_read_b128 v[192:195], v221 offset:32768
	ds_read_b128 v[196:199], v221 offset:34816
	ds_read_b128 v[200:203], v221 offset:36864
	ds_read_b128 v[204:207], v221 offset:38912
	v_mfma_f32_16x16x32_bf16 v[0:3], v[112:115], v[96:99], v[0:3]
	v_mfma_f32_16x16x32_bf16 v[4:7], v[116:119], v[96:99], v[4:7]
	s_add_u32 m0, s101, 0x1000
	v_lshl_add_u64 v[210:211], v[156:157], 0, s[18:19]
	global_load_lds_dwordx4 v[210:211], off
	v_mfma_f32_16x16x32_bf16 v[8:11], v[120:123], v[96:99], v[8:11]
	v_mfma_f32_16x16x32_bf16 v[12:15], v[124:127], v[96:99], v[12:15]
	s_add_u32 m0, s101, 0x5000
	v_lshl_add_u64 v[210:211], v[158:159], 0, s[18:19]
	global_load_lds_dwordx4 v[210:211], off
	v_mfma_f32_16x16x32_bf16 v[16:19], v[112:115], v[100:103], v[16:19]
	v_mfma_f32_16x16x32_bf16 v[20:23], v[116:119], v[100:103], v[20:23]
	s_add_u32 m0, s101, 0x2000
	v_lshl_add_u64 v[210:211], v[160:161], 0, s[18:19]
	global_load_lds_dwordx4 v[210:211], off
	v_mfma_f32_16x16x32_bf16 v[24:27], v[120:123], v[100:103], v[24:27]
	v_mfma_f32_16x16x32_bf16 v[28:31], v[124:127], v[100:103], v[28:31]
	s_add_u32 m0, s101, 0x6000
	v_lshl_add_u64 v[210:211], v[162:163], 0, s[18:19]
	global_load_lds_dwordx4 v[210:211], off
	v_mfma_f32_16x16x32_bf16 v[32:35], v[112:115], v[104:107], v[32:35]
	v_mfma_f32_16x16x32_bf16 v[36:39], v[116:119], v[104:107], v[36:39]
	s_add_u32 m0, s101, 0x3000
	v_lshl_add_u64 v[210:211], v[164:165], 0, s[18:19]
	global_load_lds_dwordx4 v[210:211], off
	v_mfma_f32_16x16x32_bf16 v[40:43], v[120:123], v[104:107], v[40:43]
	v_mfma_f32_16x16x32_bf16 v[44:47], v[124:127], v[104:107], v[44:47]
	s_add_u32 m0, s101, 0x7000
	v_lshl_add_u64 v[210:211], v[166:167], 0, s[18:19]
	global_load_lds_dwordx4 v[210:211], off
	v_mfma_f32_16x16x32_bf16 v[48:51], v[112:115], v[108:111], v[48:51]
	v_mfma_f32_16x16x32_bf16 v[52:55], v[116:119], v[108:111], v[52:55]
	v_mfma_f32_16x16x32_bf16 v[56:59], v[120:123], v[108:111], v[56:59]
	v_mfma_f32_16x16x32_bf16 v[60:63], v[124:127], v[108:111], v[60:63]
	s_waitcnt lgkmcnt(8)
	v_mfma_f32_16x16x32_bf16 v[0:3], v[80:83], v[64:67], v[0:3]
	v_mfma_f32_16x16x32_bf16 v[4:7], v[84:87], v[64:67], v[4:7]
	v_mfma_f32_16x16x32_bf16 v[8:11], v[88:91], v[64:67], v[8:11]
	v_mfma_f32_16x16x32_bf16 v[12:15], v[92:95], v[64:67], v[12:15]
	v_mfma_f32_16x16x32_bf16 v[16:19], v[80:83], v[68:71], v[16:19]
	v_mfma_f32_16x16x32_bf16 v[20:23], v[84:87], v[68:71], v[20:23]
	v_mfma_f32_16x16x32_bf16 v[24:27], v[88:91], v[68:71], v[24:27]
	v_mfma_f32_16x16x32_bf16 v[28:31], v[92:95], v[68:71], v[28:31]
	v_mfma_f32_16x16x32_bf16 v[32:35], v[80:83], v[72:75], v[32:35]
	v_mfma_f32_16x16x32_bf16 v[36:39], v[84:87], v[72:75], v[36:39]
	v_mfma_f32_16x16x32_bf16 v[40:43], v[88:91], v[72:75], v[40:43]
	v_mfma_f32_16x16x32_bf16 v[44:47], v[92:95], v[72:75], v[44:47]
	v_mfma_f32_16x16x32_bf16 v[48:51], v[80:83], v[76:79], v[48:51]
	v_mfma_f32_16x16x32_bf16 v[52:55], v[84:87], v[76:79], v[52:55]
	v_mfma_f32_16x16x32_bf16 v[56:59], v[88:91], v[76:79], v[56:59]
	v_mfma_f32_16x16x32_bf16 v[60:63], v[92:95], v[76:79], v[60:63]
	s_waitcnt vmcnt(0)
	s_waitcnt lgkmcnt(0)
	s_barrier
	ds_read_b128 v[64:67], v168 offset:0
	ds_read_b128 v[68:71], v168 offset:2048
	ds_read_b128 v[72:75], v168 offset:4096
	ds_read_b128 v[76:79], v168 offset:6144
	ds_read_b128 v[80:83], v169 offset:0
	ds_read_b128 v[84:87], v169 offset:2048
	ds_read_b128 v[88:91], v169 offset:4096
	ds_read_b128 v[92:95], v169 offset:6144
	s_add_i32 s5, s4, 3
	s_min_u32 s5, s5, 15
	s_lshl_b32 s18, s5, 7
	s_add_u32 m0, s101, 0x8000
	v_lshl_add_u64 v[210:211], v[152:153], 0, s[18:19]
	global_load_lds_dwordx4 v[210:211], off
	s_add_u32 m0, s101, 0xc000
	v_lshl_add_u64 v[210:211], v[154:155], 0, s[18:19]
	global_load_lds_dwordx4 v[210:211], off
	ds_read_b128 v[96:99], v220 offset:0
	ds_read_b128 v[100:103], v220 offset:2048
	ds_read_b128 v[104:107], v220 offset:4096
	ds_read_b128 v[108:111], v220 offset:6144
	ds_read_b128 v[112:115], v221 offset:0
	ds_read_b128 v[116:119], v221 offset:2048
	ds_read_b128 v[120:123], v221 offset:4096
	ds_read_b128 v[124:127], v221 offset:6144
	v_mfma_f32_16x16x32_bf16 v[0:3], v[192:195], v[128:131], v[0:3]
	v_mfma_f32_16x16x32_bf16 v[4:7], v[196:199], v[128:131], v[4:7]
	s_add_u32 m0, s101, 0x9000
	v_lshl_add_u64 v[210:211], v[156:157], 0, s[18:19]
	global_load_lds_dwordx4 v[210:211], off
	v_mfma_f32_16x16x32_bf16 v[8:11], v[200:203], v[128:131], v[8:11]
	v_mfma_f32_16x16x32_bf16 v[12:15], v[204:207], v[128:131], v[12:15]
	s_add_u32 m0, s101, 0xd000
	v_lshl_add_u64 v[210:211], v[158:159], 0, s[18:19]
	global_load_lds_dwordx4 v[210:211], off
	v_mfma_f32_16x16x32_bf16 v[16:19], v[192:195], v[132:135], v[16:19]
	v_mfma_f32_16x16x32_bf16 v[20:23], v[196:199], v[132:135], v[20:23]
	s_add_u32 m0, s101, 0xa000
	v_lshl_add_u64 v[210:211], v[160:161], 0, s[18:19]
	global_load_lds_dwordx4 v[210:211], off
	v_mfma_f32_16x16x32_bf16 v[24:27], v[200:203], v[132:135], v[24:27]
	v_mfma_f32_16x16x32_bf16 v[28:31], v[204:207], v[132:135], v[28:31]
	s_add_u32 m0, s101, 0xe000
	v_lshl_add_u64 v[210:211], v[162:163], 0, s[18:19]
	global_load_lds_dwordx4 v[210:211], off
	v_mfma_f32_16x16x32_bf16 v[32:35], v[192:195], v[136:139], v[32:35]
	v_mfma_f32_16x16x32_bf16 v[36:39], v[196:199], v[136:139], v[36:39]
	s_add_u32 m0, s101, 0xb000
	v_lshl_add_u64 v[210:211], v[164:165], 0, s[18:19]
	global_load_lds_dwordx4 v[210:211], off
	v_mfma_f32_16x16x32_bf16 v[40:43], v[200:203], v[136:139], v[40:43]
	v_mfma_f32_16x16x32_bf16 v[44:47], v[204:207], v[136:139], v[44:47]
	s_add_u32 m0, s101, 0xf000
	v_lshl_add_u64 v[210:211], v[166:167], 0, s[18:19]
	global_load_lds_dwordx4 v[210:211], off
	v_mfma_f32_16x16x32_bf16 v[48:51], v[192:195], v[140:143], v[48:51]
	v_mfma_f32_16x16x32_bf16 v[52:55], v[196:199], v[140:143], v[52:55]
	v_mfma_f32_16x16x32_bf16 v[56:59], v[200:203], v[140:143], v[56:59]
	v_mfma_f32_16x16x32_bf16 v[60:63], v[204:207], v[140:143], v[60:63]
	s_waitcnt lgkmcnt(8)
; DI float ssq_f(u64 v) { return (float)v * (1.f / 1048576.f); }
; #define SB_ __builtin_amdgcn_sched_barrier(0)
; template <bool SWAP, bool HALF>
; DI void gemm_mainloop(const GemmDesc& d, int m0, int n0, bf16_t* smem, f32x16 (&acc)[2][2], int dry) {
;     ...
;   auto stage = [&](int cur, u32x4 (&ran)[4], u32x4 (&rbn)[4], int ks) {
;     ldf(cur, 1, 1); SB_;
;     mma(0); SB_;
;     ldf(cur, 2, 0); SB_;
;     lw(ran, rbn, cur ^ 1);
;     gl(ran, rbn, (ks + 3 < nk) ? ks + 3 : nk - 1);
;     SB_;
;     mma(1); SB_;
;     __syncthreads();
;     ldf(cur, 3, 1); SB_;
;     mma(0); SB_;
;     ldf(cur ^ 1, 0, 0);
;     SB_;
;     mma(1); SB_;
;     __syncthreads();
;   };
;   gl(ra0, rb0, 0);
;   gl(ra1, rb1, 1);
;   lw(ra0, rb0, 0);
;   gl(ra0, rb0, 2);
;   __syncthreads();
;   ldf(0, 0, 0);
; #pragma unroll 1
;   for (int ks = 0; ks < nk; ks += 2) {
;     stage(0, ra1, rb1, ks);
;     stage(1, ra0, rb0, ks + 1);
;   }
; DI void gemm_tile(const GemmDesc& d, int m0, int n0, bf16_t* smem, int dry) {
;     ...
;   } else if (t < 128) {
;     rs_s[t] = rsqrtf(ssq_f(myss) * d.inv_dim + EPS);
;   }
	v_mfma_f32_16x16x32_bf16 v[0:3], v[80:83], v[64:67], v[0:3]
	v_mfma_f32_16x16x32_bf16 v[4:7], v[84:87], v[64:67], v[4:7]
	v_mfma_f32_16x16x32_bf16 v[8:11], v[88:91], v[64:67], v[8:11]
	v_mfma_f32_16x16x32_bf16 v[12:15], v[92:95], v[64:67], v[12:15]
	v_mfma_f32_16x16x32_bf16 v[16:19], v[80:83], v[68:71], v[16:19]
	v_mfma_f32_16x16x32_bf16 v[20:23], v[84:87], v[68:71], v[20:23]
	v_mfma_f32_16x16x32_bf16 v[24:27], v[88:91], v[68:71], v[24:27]
	v_mfma_f32_16x16x32_bf16 v[28:31], v[92:95], v[68:71], v[28:31]
	v_mfma_f32_16x16x32_bf16 v[32:35], v[80:83], v[72:75], v[32:35]
	v_mfma_f32_16x16x32_bf16 v[36:39], v[84:87], v[72:75], v[36:39]
	v_mfma_f32_16x16x32_bf16 v[40:43], v[88:91], v[72:75], v[40:43]
	v_mfma_f32_16x16x32_bf16 v[44:47], v[92:95], v[72:75], v[44:47]
	v_mfma_f32_16x16x32_bf16 v[48:51], v[80:83], v[76:79], v[48:51]
	v_mfma_f32_16x16x32_bf16 v[52:55], v[84:87], v[76:79], v[52:55]
	v_mfma_f32_16x16x32_bf16 v[56:59], v[88:91], v[76:79], v[56:59]
	v_mfma_f32_16x16x32_bf16 v[60:63], v[92:95], v[76:79], v[60:63]
	s_cmp_lt_u32 s4, 12
	s_waitcnt vmcnt(0)
	s_waitcnt lgkmcnt(0)
	s_barrier
	s_cbranch_scc1 .LBB0_1004
	ds_read_b128 v[64:67], v168 offset:32768
	ds_read_b128 v[68:71], v168 offset:34816
	ds_read_b128 v[72:75], v168 offset:36864
	ds_read_b128 v[76:79], v168 offset:38912
	ds_read_b128 v[80:83], v169 offset:32768
	ds_read_b128 v[84:87], v169 offset:34816
	ds_read_b128 v[88:91], v169 offset:36864
	ds_read_b128 v[92:95], v169 offset:38912
	ds_read_b128 v[128:131], v220 offset:32768
	ds_read_b128 v[132:135], v220 offset:34816
	ds_read_b128 v[136:139], v220 offset:36864
	ds_read_b128 v[140:143], v220 offset:38912
	ds_read_b128 v[192:195], v221 offset:32768
	ds_read_b128 v[196:199], v221 offset:34816
	ds_read_b128 v[200:203], v221 offset:36864
	ds_read_b128 v[204:207], v221 offset:38912
	v_mfma_f32_16x16x32_bf16 v[0:3], v[112:115], v[96:99], v[0:3]
	v_mfma_f32_16x16x32_bf16 v[4:7], v[116:119], v[96:99], v[4:7]
	v_mfma_f32_16x16x32_bf16 v[8:11], v[120:123], v[96:99], v[8:11]
	v_mfma_f32_16x16x32_bf16 v[12:15], v[124:127], v[96:99], v[12:15]
	v_mfma_f32_16x16x32_bf16 v[16:19], v[112:115], v[100:103], v[16:19]
	v_mfma_f32_16x16x32_bf16 v[20:23], v[116:119], v[100:103], v[20:23]
	v_mfma_f32_16x16x32_bf16 v[24:27], v[120:123], v[100:103], v[24:27]
	v_mfma_f32_16x16x32_bf16 v[28:31], v[124:127], v[100:103], v[28:31]
	v_mfma_f32_16x16x32_bf16 v[32:35], v[112:115], v[104:107], v[32:35]
	v_mfma_f32_16x16x32_bf16 v[36:39], v[116:119], v[104:107], v[36:39]
	v_mfma_f32_16x16x32_bf16 v[40:43], v[120:123], v[104:107], v[40:43]
	v_mfma_f32_16x16x32_bf16 v[44:47], v[124:127], v[104:107], v[44:47]
	v_mfma_f32_16x16x32_bf16 v[48:51], v[112:115], v[108:111], v[48:51]
	v_mfma_f32_16x16x32_bf16 v[52:55], v[116:119], v[108:111], v[52:55]
	v_mfma_f32_16x16x32_bf16 v[56:59], v[120:123], v[108:111], v[56:59]
	v_mfma_f32_16x16x32_bf16 v[60:63], v[124:127], v[108:111], v[60:63]
	s_waitcnt lgkmcnt(8)
	v_mfma_f32_16x16x32_bf16 v[0:3], v[80:83], v[64:67], v[0:3]
	v_mfma_f32_16x16x32_bf16 v[4:7], v[84:87], v[64:67], v[4:7]
	v_mfma_f32_16x16x32_bf16 v[8:11], v[88:91], v[64:67], v[8:11]
	v_mfma_f32_16x16x32_bf16 v[12:15], v[92:95], v[64:67], v[12:15]
	v_mfma_f32_16x16x32_bf16 v[16:19], v[80:83], v[68:71], v[16:19]
	v_mfma_f32_16x16x32_bf16 v[20:23], v[84:87], v[68:71], v[20:23]
	v_mfma_f32_16x16x32_bf16 v[24:27], v[88:91], v[68:71], v[24:27]
	v_mfma_f32_16x16x32_bf16 v[28:31], v[92:95], v[68:71], v[28:31]
	v_mfma_f32_16x16x32_bf16 v[32:35], v[80:83], v[72:75], v[32:35]
	v_mfma_f32_16x16x32_bf16 v[36:39], v[84:87], v[72:75], v[36:39]
	v_mfma_f32_16x16x32_bf16 v[40:43], v[88:91], v[72:75], v[40:43]
	v_mfma_f32_16x16x32_bf16 v[44:47], v[92:95], v[72:75], v[44:47]
	v_mfma_f32_16x16x32_bf16 v[48:51], v[80:83], v[76:79], v[48:51]
	v_mfma_f32_16x16x32_bf16 v[52:55], v[84:87], v[76:79], v[52:55]
	v_mfma_f32_16x16x32_bf16 v[56:59], v[88:91], v[76:79], v[56:59]
	v_mfma_f32_16x16x32_bf16 v[60:63], v[92:95], v[76:79], v[60:63]
	s_waitcnt lgkmcnt(0)
	s_barrier
	v_mfma_f32_16x16x32_bf16 v[0:3], v[192:195], v[128:131], v[0:3]
	v_mfma_f32_16x16x32_bf16 v[4:7], v[196:199], v[128:131], v[4:7]
	v_mfma_f32_16x16x32_bf16 v[8:11], v[200:203], v[128:131], v[8:11]
	v_mfma_f32_16x16x32_bf16 v[12:15], v[204:207], v[128:131], v[12:15]
	v_mfma_f32_16x16x32_bf16 v[16:19], v[192:195], v[132:135], v[16:19]
	v_mfma_f32_16x16x32_bf16 v[20:23], v[196:199], v[132:135], v[20:23]
	v_mfma_f32_16x16x32_bf16 v[24:27], v[200:203], v[132:135], v[24:27]
	v_mfma_f32_16x16x32_bf16 v[28:31], v[204:207], v[132:135], v[28:31]
	v_mfma_f32_16x16x32_bf16 v[32:35], v[192:195], v[136:139], v[32:35]
	v_mfma_f32_16x16x32_bf16 v[36:39], v[196:199], v[136:139], v[36:39]
	v_mfma_f32_16x16x32_bf16 v[40:43], v[200:203], v[136:139], v[40:43]
	v_mfma_f32_16x16x32_bf16 v[44:47], v[204:207], v[136:139], v[44:47]
	v_mfma_f32_16x16x32_bf16 v[48:51], v[192:195], v[140:143], v[48:51]
	v_mfma_f32_16x16x32_bf16 v[52:55], v[196:199], v[140:143], v[52:55]
	v_mfma_f32_16x16x32_bf16 v[56:59], v[200:203], v[140:143], v[56:59]
	v_mfma_f32_16x16x32_bf16 v[60:63], v[204:207], v[140:143], v[60:63]
	s_and_saveexec_b64 s[4:5], s[42:43]
	s_cbranch_execz .LBB0_1007
	s_mov_b32 s15, 0x800000
	s_waitcnt vmcnt(15)
	v_mul_f32_e32 v64, 0x4b800000, v171
	v_cmp_gt_f32_e32 vcc, s15, v171
	v_lshl_add_u32 v65, v150, 2, v181
	s_nop 0
	v_cndmask_b32_e32 v64, v171, v64, vcc
	v_rsq_f32_e32 v64, v64
	s_nop 0
	v_mul_f32_e32 v66, 0x45800000, v64
	v_cndmask_b32_e32 v64, v64, v66, vcc
	ds_write_b32 v65, v64
; DI void gemm_tile(const GemmDesc& d, int m0, int n0, bf16_t* smem, int dry) {
;     ...
; #pragma unroll
;     for (int a = 0; a < 2; ++a)
; #pragma unroll
;       for (int b = 0; b < 2; ++b)
; #pragma unroll
;         for (int g = 0; g < 4; ++g) {
;           f32x4 o;
; #pragma unroll
;           for (int j = 0; j < 4; ++j) o[j] = acc[a][b][4 * g + j];
;           *(f32x4*)(Ct + (wm * 64 + a * 32 + r) * CS + wn * 64 + b * 32 + 8 * g + 4 * hh) = o;
;         }
;   }
;   __syncthreads();
;     ...
;   } else if (n0 < d.n1end) {
;     bf16_t* dst; int ld, nb;
;     if (n0 < d.n0end) { dst = d.d0; ld = d.ld0; nb = n0; } else { dst = d.d1; ld = d.ld1; nb = n0 - d.n0end; }
;     unsigned* kq = (d.kmax && n0 >= d.n0end) ? d.kmax : nullptr;
;     const int mlast = (m0 + 127) < M ? (m0 + 127) : M - 1;
;     const bool onebatch = (m0 / L) == (mlast / L);
;     float kmx = 0.f;
;     u64* sq = nullptr;
;     if (d.ssq_a) { if (n0 < d.ssq_a_end) sq = d.ssq_a; else if (n0 < d.ssq_b_end) sq = d.ssq_b; }
; #pragma unroll 4
;     for (int pass = 0; pass < 16; ++pass) {
;       const int row = pass * 8 + (t >> 5), c4 = t & 31, m = m0 + row;
;       float part = 0.f, kpart = 0.f;
;       if (m < M) {
;         const float rs = rs_s[row];
;         f32x4 v = *(const f32x4*)(Ct + row * CS + c4 * 4);
; #pragma unroll
;         for (int j = 0; j < 4; ++j) { v[j] *= rs; part += v[j] * v[j]; }
;         u32x2 o; o[0] = pk_bf16(v[0], v[1]); o[1] = pk_bf16(v[2], v[3]);
;         *(u32x2*)(dst + (size_t)m * ld + nb + c4 * 4) = o;
.LBB0_1007:
	s_or_b64 exec, exec, s[4:5]
	s_waitcnt vmcnt(15)
	v_lshlrev_b32_e32 v64, 4, v189
	v_lshl_or_b32 v65, v187, 6, v170
	v_lshl_or_b32 v64, v188, 8, v64
	v_mad_u64_u32 v[64:65], s[4:5], v65, s22, v[64:65]
	s_cmp_lt_i32 s14, 16
	s_mov_b64 s[4:5], -1
	v_and_b32_e32 v212, 15, v172
	v_lshrrev_b32_e32 v213, 1, v172
	v_and_or_b32 v212, v213, s72, v212
	v_lshlrev_b32_e32 v213, 2, v172
	v_and_b32_e32 v214, 0x30, v172
	v_and_b32_e32 v213, 0x100, v213
	v_or_b32_e32 v213, v213, v214
	v_mad_u32_u24 v64, v212, s22, v213
	ds_write_b128 v64, v[0:3]
	ds_write_b128 v64, v[4:7] offset:64
	ds_write_b128 v64, v[8:11] offset:128
	ds_write_b128 v64, v[12:15] offset:192
	ds_write_b128 v64, v[16:19] offset:8448
	ds_write_b128 v64, v[20:23] offset:8512
	ds_write_b128 v64, v[24:27] offset:8576
	ds_write_b128 v64, v[28:31] offset:8640
	ds_write_b128 v64, v[32:35] offset:16896
	ds_write_b128 v64, v[36:39] offset:16960
	ds_write_b128 v64, v[40:43] offset:17024
	ds_write_b128 v64, v[44:47] offset:17088
	ds_write_b128 v64, v[48:51] offset:25344
	ds_write_b128 v64, v[52:55] offset:25408
	ds_write_b128 v64, v[56:59] offset:25472
	ds_write_b128 v64, v[60:63] offset:25536
	s_waitcnt lgkmcnt(0)
	s_barrier
	s_cbranch_scc0 .LBB0_1020
	s_lshl_b32 s15, s12, 13
	s_cmp_lt_i32 s14, 8
	s_cselect_b32 s4, 0, 0xfffffc00
	s_cselect_b32 s5, 0, 0x4020000
	s_add_i32 s4, s4, s1
	s_add_u32 s14, s68, s5
	s_addc_u32 s16, s69, 0
	s_ashr_i32 s5, s4, 31
	s_lshl_b64 s[4:5], s[4:5], 1
	s_add_u32 s4, s14, s4
	s_addc_u32 s5, s16, s5
	v_lshlrev_b32_e32 v144, 3, v170
	v_ashrrev_i32_e32 v2, 5, v150
	v_lshl_add_u64 v[0:1], s[4:5], 0, v[144:145]
	s_add_i32 s4, s10, s11
	v_mul_lo_u32 v3, v2, s22
	v_lshlrev_b32_e32 v5, 2, v2
	v_add_u32_e32 v2, s29, v2
	s_sub_i32 s4, s4, s13
	v_lshl_add_u32 v6, s4, 10, v2
	s_lshl_b32 s4, s10, 10
	s_add_i32 s4, s4, s15
	v_add_u32_e32 v2, s4, v2
	s_lshl_b32 s4, s13, 10
	s_mov_b32 s12, 0
	v_lshl_add_u32 v4, v170, 4, v3
	v_subrev_u32_e32 v7, s4, v2
	s_branch .LBB0_1010

; DI int otid() { int t = threadIdx.x; asm volatile("" : "+v"(t)); return t; }
; template <bool SWAP, bool HALF>
; DI void gemm_mainloop(const GemmDesc& d, int m0, int n0, bf16_t* smem, f32x16 (&acc)[2][2], int dry) {
;   const int t = otid(), lane = t & 63, w = t >> 6, wm = w >> 1, wn = w & 1, r = lane & 31, hh = lane >> 5;
;   const int lrow = t >> 3, lkc = t & 7;
;   const bf16_t* ap[4]; const bf16_t* bp[4];
; #pragma unroll
;   for (int i = 0; i < 4; ++i) {
;     int am = m0 + lrow + 32 * i; am = am < M ? am : M - 1;
;     ap[i] = d.A + (size_t)am * d.lda + lkc * 8 + (d.a_grp ? (n0 / d.a_grp) * d.a_grp : 0);
;     bp[i] = d.Bt + (size_t)(n0 + lrow + 32 * i) * d.ldb + lkc * 8;
;     ...
;     const int g = i / (8 * nN), j = i - g * 8 * nN;
;     const int gm = (cx - g * 8) < 8 ? (cx - g * 8) : 8;
;     const int mt = (g * 8 + j % gm) * 8 + x, nt = j / gm;
;     gemm_tile(d, mt * 128, nt * 128, smem, dry);
.LBB0_1218:
	s_lshr_b32 s1, s8, 3
	s_and_b32 s1, s1, 0xffffff8
	v_readlane_b32 s5, v228, 38
	s_sub_i32 s5, s5, s1
	s_min_i32 s5, s5, 8
	s_abs_i32 s9, s5
	v_cvt_f32_u32_e32 v0, s9
	s_sub_i32 s10, 0, s9
	s_lshl_b32 s4, s1, 3
	s_sub_i32 s4, s8, s4
	v_rcp_iflag_f32_e32 v0, v0
	s_abs_i32 s7, s4
	s_xor_b32 s6, s4, s5
	s_ashr_i32 s6, s6, 31
	v_mul_f32_e32 v0, 0x4f7ffffe, v0
	v_cvt_u32_f32_e32 v0, v0
	v_mov_b32_e32 v150, v172
	v_mov_b32_e32 v32, v172
	v_readfirstlane_b32 s11, v0
	s_mul_i32 s10, s10, s11
	s_mul_hi_u32 s10, s11, s10
	s_add_i32 s11, s11, s10
	s_mul_hi_u32 s10, s7, s11
	s_mul_i32 s11, s10, s9
	s_sub_i32 s7, s7, s11
	s_add_i32 s11, s10, 1
	s_sub_i32 s12, s7, s9
	s_cmp_ge_u32 s7, s9
	s_cselect_b32 s10, s11, s10
	s_cselect_b32 s7, s12, s7
	s_add_i32 s11, s10, 1
	s_cmp_ge_u32 s7, s9
	s_cselect_b32 s7, s11, s10
	s_xor_b32 s7, s7, s6
	s_sub_i32 s6, s7, s6
	s_mul_i32 s5, s6, s5
	s_sub_i32 s4, s4, s5
	s_add_i32 s1, s1, s4
	s_lshl_b32 s4, s6, 7
	s_lshl_b32 s1, s1, 10
	v_ashrrev_i32_e32 v10, 3, v32
	v_lshlrev_b32_e32 v0, 3, v32
	v_and_b32_e32 v33, 56, v0
	v_add_u32_e32 v2, s4, v10
	v_readlane_b32 s76, v228, 60
	s_or_b32 s9, s1, s29
	v_lshlrev_b32_e32 v144, 1, v33
	v_readlane_b32 s80, v223, 0
	v_readlane_b32 s81, v223, 1
	v_ashrrev_i32_e32 v3, 31, v2
	v_add_u32_e32 v11, s9, v10
	v_lshl_add_u64 v[4:5], s[80:81], 0, v[144:145]
	v_lshlrev_b64 v[2:3], 11, v[2:3]
	v_lshl_add_u64 v[154:155], v[4:5], 0, v[2:3]
	v_min_i32_e32 v2, 0x801f, v11
	v_ashrrev_i32_e32 v3, 31, v2
	v_lshl_add_u64 v[0:1], s[68:69], 0, v[144:145]
	v_lshlrev_b64 v[2:3], 11, v[2:3]
	v_lshl_add_u64 v[8:9], v[0:1], 0, v[2:3]
	v_min_i32_e32 v2, 0x7fff, v11
	v_ashrrev_i32_e32 v3, 31, v2
	v_min_i32_e32 v6, 0x803f, v11
	v_lshlrev_b64 v[2:3], 11, v[2:3]
	v_ashrrev_i32_e32 v7, 31, v6
	v_lshl_add_u64 v[16:17], v[0:1], 0, v[2:3]
	v_min_i32_e32 v2, 0x7fdf, v11
	v_lshlrev_b64 v[6:7], 11, v[6:7]
	v_ashrrev_i32_e32 v3, 31, v2
	v_lshl_add_u64 v[152:153], v[0:1], 0, v[6:7]
	v_lshlrev_b64 v[2:3], 11, v[2:3]
	v_lshl_add_u64 v[24:25], v[0:1], 0, v[2:3]
	s_mov_b64 s[6:7], 0x10000
	v_lshl_add_u64 v[156:157], v[8:9], 0, s[6:7]
	v_lshl_add_u64 v[158:159], v[154:155], 0, s[6:7]
	s_mov_b64 s[6:7], 0x20000
	v_lshl_add_u64 v[160:161], v[16:17], 0, s[6:7]
	v_lshl_add_u64 v[162:163], v[154:155], 0, s[6:7]
	s_mov_b64 s[6:7], 0x30000
	s_movk_i32 s1, 0x48
	v_lshl_add_u64 v[164:165], v[24:25], 0, s[6:7]
	v_lshl_add_u64 v[166:167], v[154:155], 0, s[6:7]
	v_and_b32_e32 v34, 31, v32
	v_mul_lo_u32 v35, v10, s1
	v_readlane_b32 s77, v228, 61
	v_readlane_b32 s78, v228, 62
	v_readlane_b32 s79, v228, 63
	v_readlane_b32 s82, v223, 2
	v_readlane_b32 s83, v223, 3
	v_readlane_b32 s84, v223, 4
	v_readlane_b32 s85, v223, 5
	v_readlane_b32 s86, v223, 6
	v_readlane_b32 s87, v223, 7
	v_readlane_b32 s88, v223, 8
	v_readlane_b32 s89, v223, 9
	v_readlane_b32 s90, v223, 10
	v_readlane_b32 s91, v223, 11
	s_mov_b32 s1, 0x10000
	v_add_co_u32_e32 v8, vcc, s1, v8
	s_nop 1
	v_addc_co_u32_e32 v9, vcc, 0, v9, vcc
	s_waitcnt vmcnt(19)
	v_add_co_u32_e32 v12, vcc, s1, v154
	s_nop 1
	v_addc_co_u32_e32 v13, vcc, 0, v155, vcc
	s_mov_b32 s1, 0x20000
	v_add_co_u32_e32 v16, vcc, s1, v16
	s_nop 1
	v_addc_co_u32_e32 v17, vcc, 0, v17, vcc
	v_add_co_u32_e32 v20, vcc, s1, v154
	s_nop 1
	v_addc_co_u32_e32 v21, vcc, 0, v155, vcc
	s_mov_b32 s1, 0x30000
	v_add_co_u32_e32 v24, vcc, s1, v24
	s_nop 1
	v_addc_co_u32_e32 v25, vcc, 0, v25, vcc
	v_add_co_u32_e32 v28, vcc, s1, v154
	s_nop 1
	v_addc_co_u32_e32 v29, vcc, 0, v155, vcc
	s_nop 0
	v_add_lshl_u32 v144, v35, v33, 1
	s_waitcnt vmcnt(15)
	s_waitcnt vmcnt(14)
	s_waitcnt vmcnt(13)
	s_waitcnt vmcnt(12)
	s_waitcnt vmcnt(11)
	s_waitcnt vmcnt(10)
	s_waitcnt vmcnt(9)
	s_waitcnt vmcnt(8)
	v_lshrrev_b32_e32 v0, 1, v32
	v_and_or_b32 v1, v0, s72, v34
	v_and_b32_e32 v0, 16, v0
	s_movk_i32 s1, 0x90
	v_mad_u64_u32 v[168:169], s[6:7], v1, s1, v[0:1]
	v_and_b32_e32 v1, 0x5f, v32
	v_mul_u32_u24_e32 v1, 0x48, v1
	v_lshl_add_u32 v169, v1, 1, v0
	v_bfe_u32 v212, v172, 4, 3
	v_lshlrev_b32_e32 v212, 4, v212
	v_xor_b32_e32 v152, v152, v212
	v_xor_b32_e32 v154, v154, v212
	v_xor_b32_e32 v156, v156, v212
	v_xor_b32_e32 v158, v158, v212
	v_xor_b32_e32 v160, v160, v212
	v_xor_b32_e32 v162, v162, v212
	v_xor_b32_e32 v164, v164, v212
	v_xor_b32_e32 v166, v166, v212
	v_lshrrev_b32_e32 v213, 6, v172
	s_nop 1
	v_readfirstlane_b32 s101, v213
	s_lshl_b32 s101, s101, 10
	s_add_u32 m0, s101, 0x0
	s_nop 0
	global_load_lds_dwordx4 v[152:153], off
	s_add_u32 m0, s101, 0x4000
	s_nop 0
	global_load_lds_dwordx4 v[154:155], off
	s_add_u32 m0, s101, 0x1000
	s_nop 0
	global_load_lds_dwordx4 v[156:157], off
	s_add_u32 m0, s101, 0x5000
	s_nop 0
	global_load_lds_dwordx4 v[158:159], off
	s_add_u32 m0, s101, 0x2000
	s_nop 0
	global_load_lds_dwordx4 v[160:161], off
	s_add_u32 m0, s101, 0x6000
	s_nop 0
	global_load_lds_dwordx4 v[162:163], off
	s_add_u32 m0, s101, 0x3000
	s_nop 0
	global_load_lds_dwordx4 v[164:165], off
	s_add_u32 m0, s101, 0x7000
	s_nop 0
	global_load_lds_dwordx4 v[166:167], off
	v_and_b32_e32 v212, 15, v172
	v_bfe_u32 v213, v172, 4, 2
	v_lshrrev_b32_e32 v214, 1, v212
	v_xor_b32_e32 v213, v213, v214
	v_lshlrev_b32_e32 v213, 4, v213
	v_lshl_or_b32 v212, v212, 7, v213
	v_lshrrev_b32_e32 v214, 7, v172
	v_lshl_add_u32 v168, v214, 13, v212
	v_bfe_u32 v214, v172, 6, 1
	v_lshl_add_u32 v169, v214, 13, v212
	v_add_u32_e32 v169, 0x4000, v169
	v_xor_b32_e32 v220, 64, v168
	v_xor_b32_e32 v221, 64, v169
	s_waitcnt vmcnt(0)
	s_waitcnt lgkmcnt(0)
	s_barrier
; #define SB_ __builtin_amdgcn_sched_barrier(0)
; template <bool SWAP, bool HALF>
; DI void gemm_mainloop(const GemmDesc& d, int m0, int n0, bf16_t* smem, f32x16 (&acc)[2][2], int dry) {
;     ...
; #pragma unroll
;   for (int a = 0; a < 2; ++a)
; #pragma unroll
;     for (int b = 0; b < 2; ++b)
; #pragma unroll
;       for (int i = 0; i < 16; ++i) acc[a][b][i] = 0.f;
;     ...
;   auto stage = [&](int cur, u32x4 (&ran)[4], u32x4 (&rbn)[4], int ks) {
;     ldf(cur, 1, 1); SB_;
;     mma(0); SB_;
;     ldf(cur, 2, 0); SB_;
;     lw(ran, rbn, cur ^ 1);
;     gl(ran, rbn, (ks + 3 < nk) ? ks + 3 : nk - 1);
;     SB_;
;     mma(1); SB_;
;     __syncthreads();
;     ldf(cur, 3, 1); SB_;
;     mma(0); SB_;
;     ldf(cur ^ 1, 0, 0);
;     SB_;
;     mma(1); SB_;
;     __syncthreads();
;   };
	v_mov_b32_e32 v0, 0
	v_add_u32_e32 v170, 0x9000, v144
	s_mov_b32 s1, -2
	v_mov_b32_e32 v1, v0
	v_mov_b32_e32 v2, v0
	v_mov_b32_e32 v3, v0
	v_mov_b32_e32 v4, v0
	v_mov_b32_e32 v5, v0
	v_mov_b32_e32 v6, v0
	v_mov_b32_e32 v7, v0
	v_mov_b32_e32 v8, v0
	v_mov_b32_e32 v9, v0
	v_mov_b32_e32 v10, v0
	v_mov_b32_e32 v11, v0
	v_mov_b32_e32 v12, v0
	v_mov_b32_e32 v13, v0
	v_mov_b32_e32 v14, v0
	v_mov_b32_e32 v15, v0
	v_mov_b32_e32 v16, v0
	v_mov_b32_e32 v17, v0
	v_mov_b32_e32 v18, v0
	v_mov_b32_e32 v19, v0
	v_mov_b32_e32 v20, v0
	v_mov_b32_e32 v21, v0
	v_mov_b32_e32 v22, v0
	v_mov_b32_e32 v23, v0
	v_mov_b32_e32 v24, v0
	v_mov_b32_e32 v25, v0
	v_mov_b32_e32 v26, v0
	v_mov_b32_e32 v27, v0
	v_mov_b32_e32 v28, v0
	v_mov_b32_e32 v29, v0
	v_mov_b32_e32 v30, v0
	v_mov_b32_e32 v31, v0
	v_mov_b32_e32 v32, v0
	v_mov_b32_e32 v33, v0
	v_mov_b32_e32 v34, v0
	v_mov_b32_e32 v35, v0
	v_mov_b32_e32 v36, v0
	v_mov_b32_e32 v37, v0
	v_mov_b32_e32 v38, v0
	v_mov_b32_e32 v39, v0
	v_mov_b32_e32 v40, v0
	v_mov_b32_e32 v41, v0
	v_mov_b32_e32 v42, v0
	v_mov_b32_e32 v43, v0
	v_mov_b32_e32 v44, v0
	v_mov_b32_e32 v45, v0
	v_mov_b32_e32 v46, v0
	v_mov_b32_e32 v47, v0
	v_mov_b32_e32 v48, v0
	v_mov_b32_e32 v49, v0
	v_mov_b32_e32 v50, v0
	v_mov_b32_e32 v51, v0
	v_mov_b32_e32 v52, v0
	v_mov_b32_e32 v53, v0
	v_mov_b32_e32 v54, v0
	v_mov_b32_e32 v55, v0
	v_mov_b32_e32 v56, v0
	v_mov_b32_e32 v57, v0
	v_mov_b32_e32 v58, v0
	v_mov_b32_e32 v59, v0
	v_mov_b32_e32 v60, v0
	v_mov_b32_e32 v61, v0
	v_mov_b32_e32 v62, v0
	v_mov_b32_e32 v63, v0
	ds_read_b128 v[64:67], v168 offset:0
	ds_read_b128 v[68:71], v168 offset:2048
	ds_read_b128 v[72:75], v168 offset:4096
	ds_read_b128 v[76:79], v168 offset:6144
	ds_read_b128 v[80:83], v169 offset:0
	ds_read_b128 v[84:87], v169 offset:2048
	ds_read_b128 v[88:91], v169 offset:4096
	ds_read_b128 v[92:95], v169 offset:6144
	s_add_i32 s5, s1, 3
	s_min_u32 s5, s5, 15
	s_lshl_b32 s18, s5, 7
	s_add_u32 m0, s101, 0x8000
	v_lshl_add_u64 v[210:211], v[152:153], 0, s[18:19]
	global_load_lds_dwordx4 v[210:211], off
	s_add_u32 m0, s101, 0xc000
	v_lshl_add_u64 v[210:211], v[154:155], 0, s[18:19]
	global_load_lds_dwordx4 v[210:211], off
	ds_read_b128 v[96:99], v220 offset:0
	ds_read_b128 v[100:103], v220 offset:2048
	ds_read_b128 v[104:107], v220 offset:4096
	ds_read_b128 v[108:111], v220 offset:6144
	ds_read_b128 v[112:115], v221 offset:0
	ds_read_b128 v[116:119], v221 offset:2048
	ds_read_b128 v[120:123], v221 offset:4096
	ds_read_b128 v[124:127], v221 offset:6144
	s_waitcnt lgkmcnt(8)
	v_mfma_f32_16x16x32_bf16 v[0:3], v[80:83], v[64:67], v[0:3]
	v_mfma_f32_16x16x32_bf16 v[4:7], v[84:87], v[64:67], v[4:7]
	s_add_u32 m0, s101, 0x9000
	v_lshl_add_u64 v[210:211], v[156:157], 0, s[18:19]
	global_load_lds_dwordx4 v[210:211], off
	v_mfma_f32_16x16x32_bf16 v[8:11], v[88:91], v[64:67], v[8:11]
	v_mfma_f32_16x16x32_bf16 v[12:15], v[92:95], v[64:67], v[12:15]
	s_add_u32 m0, s101, 0xd000
	v_lshl_add_u64 v[210:211], v[158:159], 0, s[18:19]
	global_load_lds_dwordx4 v[210:211], off
	v_mfma_f32_16x16x32_bf16 v[16:19], v[80:83], v[68:71], v[16:19]
	v_mfma_f32_16x16x32_bf16 v[20:23], v[84:87], v[68:71], v[20:23]
	s_add_u32 m0, s101, 0xa000
	v_lshl_add_u64 v[210:211], v[160:161], 0, s[18:19]
	global_load_lds_dwordx4 v[210:211], off
	v_mfma_f32_16x16x32_bf16 v[24:27], v[88:91], v[68:71], v[24:27]
	v_mfma_f32_16x16x32_bf16 v[28:31], v[92:95], v[68:71], v[28:31]
	s_add_u32 m0, s101, 0xe000
	v_lshl_add_u64 v[210:211], v[162:163], 0, s[18:19]
	global_load_lds_dwordx4 v[210:211], off
	v_mfma_f32_16x16x32_bf16 v[32:35], v[80:83], v[72:75], v[32:35]
	v_mfma_f32_16x16x32_bf16 v[36:39], v[84:87], v[72:75], v[36:39]
	s_add_u32 m0, s101, 0xb000
	v_lshl_add_u64 v[210:211], v[164:165], 0, s[18:19]
	global_load_lds_dwordx4 v[210:211], off
	v_mfma_f32_16x16x32_bf16 v[40:43], v[88:91], v[72:75], v[40:43]
	v_mfma_f32_16x16x32_bf16 v[44:47], v[92:95], v[72:75], v[44:47]
	s_add_u32 m0, s101, 0xf000
	v_lshl_add_u64 v[210:211], v[166:167], 0, s[18:19]
	global_load_lds_dwordx4 v[210:211], off
	v_mfma_f32_16x16x32_bf16 v[48:51], v[80:83], v[76:79], v[48:51]
	v_mfma_f32_16x16x32_bf16 v[52:55], v[84:87], v[76:79], v[52:55]
	v_mfma_f32_16x16x32_bf16 v[56:59], v[88:91], v[76:79], v[56:59]
	v_mfma_f32_16x16x32_bf16 v[60:63], v[92:95], v[76:79], v[60:63]
	s_waitcnt vmcnt(0)
	s_waitcnt lgkmcnt(0)
	s_barrier

; DI int otid() { int t = threadIdx.x; asm volatile("" : "+v"(t)); return t; }
; template <bool SWAP, bool HALF>
; DI void gemm_mainloop(const GemmDesc& d, int m0, int n0, bf16_t* smem, f32x16 (&acc)[2][2], int dry) {
;   const int t = otid(), lane = t & 63, w = t >> 6, wm = w >> 1, wn = w & 1, r = lane & 31, hh = lane >> 5;
;   const int lrow = t >> 3, lkc = t & 7;
;   const bf16_t* ap[4]; const bf16_t* bp[4];
; #pragma unroll
;   for (int i = 0; i < 4; ++i) {
;     int am = m0 + lrow + 32 * i; am = am < M ? am : M - 1;
;     ap[i] = d.A + (size_t)am * d.lda + lkc * 8 + (d.a_grp ? (n0 / d.a_grp) * d.a_grp : 0);
;     bp[i] = d.Bt + (size_t)(n0 + lrow + 32 * i) * d.ldb + lkc * 8;
;   }
; #pragma unroll
;   for (int a = 0; a < 2; ++a)
; #pragma unroll
;     for (int b = 0; b < 2; ++b)
; #pragma unroll
;       for (int i = 0; i < 16; ++i) acc[a][b][i] = 0.f;
;     ...
;   gl(ra0, rb0, 0);
;   gl(ra1, rb1, 1);
;   lw(ra0, rb0, 0);
;   gl(ra0, rb0, 2);
;   __syncthreads();
;   ldf(0, 0, 0);
.LBB0_1461:
	s_or_b64 exec, exec, s[4:5]
	v_mov_b32_e32 v32, v172
	s_mov_b64 s[4:5], 0x10000
	v_ashrrev_i32_e32 v10, 3, v32
	v_lshlrev_b32_e32 v0, 3, v32
	v_and_b32_e32 v33, 56, v0
	v_lshl_add_u32 v2, s13, 7, v10
	v_lshlrev_b32_e32 v144, 1, v33
	v_ashrrev_i32_e32 v3, 31, v2
	v_add_u32_e32 v11, s14, v10
	v_lshl_add_u64 v[4:5], s[6:7], 0, v[144:145]
	v_lshlrev_b64 v[2:3], 11, v[2:3]
	v_lshl_add_u64 v[154:155], v[4:5], 0, v[2:3]
	v_min_i32_e32 v2, 0x801f, v11
	v_ashrrev_i32_e32 v3, 31, v2
	v_lshl_add_u64 v[0:1], s[56:57], 0, v[144:145]
	v_lshlrev_b64 v[2:3], 11, v[2:3]
	v_lshl_add_u64 v[8:9], v[0:1], 0, v[2:3]
	v_min_i32_e32 v2, 0x7fff, v11
	v_ashrrev_i32_e32 v3, 31, v2
	v_min_i32_e32 v6, 0x803f, v11
	v_lshlrev_b64 v[2:3], 11, v[2:3]
	v_ashrrev_i32_e32 v7, 31, v6
	v_lshl_add_u64 v[16:17], v[0:1], 0, v[2:3]
	v_min_i32_e32 v2, 0x7fdf, v11
	v_lshlrev_b64 v[6:7], 11, v[6:7]
	v_ashrrev_i32_e32 v3, 31, v2
	v_lshl_add_u64 v[152:153], v[0:1], 0, v[6:7]
	v_lshlrev_b64 v[2:3], 11, v[2:3]
	v_lshl_add_u64 v[24:25], v[0:1], 0, v[2:3]
	v_lshl_add_u64 v[156:157], v[8:9], 0, s[4:5]
	v_lshl_add_u64 v[158:159], v[154:155], 0, s[4:5]
	s_mov_b64 s[4:5], 0x20000
	v_lshl_add_u64 v[160:161], v[16:17], 0, s[4:5]
	v_lshl_add_u64 v[162:163], v[154:155], 0, s[4:5]
	s_mov_b64 s[4:5], 0x30000
	v_lshl_add_u64 v[164:165], v[24:25], 0, s[4:5]
	v_lshl_add_u64 v[166:167], v[154:155], 0, s[4:5]
	s_movk_i32 s4, 0x48
	v_and_b32_e32 v34, 31, v32
	v_mul_lo_u32 v35, v10, s4
	s_mov_b32 s15, 0x10000
	v_add_co_u32_e64 v8, s[4:5], s15, v8
	s_mov_b32 s14, 0
	s_nop 0
	v_addc_co_u32_e64 v9, s[4:5], 0, v9, s[4:5]
	s_waitcnt vmcnt(19)
	v_add_co_u32_e64 v12, s[4:5], s15, v154
	s_nop 1
	v_addc_co_u32_e64 v13, s[4:5], 0, v155, s[4:5]
	s_mov_b32 s15, 0x20000
	v_add_co_u32_e64 v16, s[4:5], s15, v16
	s_nop 1
	v_addc_co_u32_e64 v17, s[4:5], 0, v17, s[4:5]
	v_add_co_u32_e64 v20, s[4:5], s15, v154
	s_nop 1
	v_addc_co_u32_e64 v21, s[4:5], 0, v155, s[4:5]
	s_mov_b32 s15, 0x30000
	v_add_co_u32_e64 v24, s[4:5], s15, v24
	s_nop 1
	v_addc_co_u32_e64 v25, s[4:5], 0, v25, s[4:5]
	v_add_co_u32_e64 v28, s[4:5], s15, v154
	s_nop 1
	v_addc_co_u32_e64 v29, s[4:5], 0, v155, s[4:5]
	s_nop 0
	v_add_lshl_u32 v144, v35, v33, 1
	s_waitcnt vmcnt(15)
	s_waitcnt vmcnt(14)
	s_waitcnt vmcnt(13)
	s_waitcnt vmcnt(12)
	s_waitcnt vmcnt(11)
	s_waitcnt vmcnt(10)
	s_waitcnt vmcnt(9)
	s_waitcnt vmcnt(8)
	v_lshrrev_b32_e32 v0, 1, v32
	v_and_or_b32 v1, v0, s72, v34
	v_and_b32_e32 v0, 16, v0
	s_movk_i32 s4, 0x90
	v_mad_u64_u32 v[168:169], s[4:5], v1, s4, v[0:1]
	v_and_b32_e32 v1, 0x5f, v32
	v_mul_u32_u24_e32 v1, 0x48, v1
	v_lshl_add_u32 v169, v1, 1, v0
	v_bfe_u32 v212, v172, 4, 3
	v_lshlrev_b32_e32 v212, 4, v212
	v_xor_b32_e32 v152, v152, v212
	v_xor_b32_e32 v154, v154, v212
	v_xor_b32_e32 v156, v156, v212
	v_xor_b32_e32 v158, v158, v212
	v_xor_b32_e32 v160, v160, v212
	v_xor_b32_e32 v162, v162, v212
	v_xor_b32_e32 v164, v164, v212
	v_xor_b32_e32 v166, v166, v212
	v_lshrrev_b32_e32 v213, 6, v172
	s_nop 1
	v_readfirstlane_b32 s101, v213
	s_lshl_b32 s101, s101, 10
	s_add_u32 m0, s101, 0x0
	s_nop 0
	global_load_lds_dwordx4 v[152:153], off
	s_add_u32 m0, s101, 0x4000
	s_nop 0
	global_load_lds_dwordx4 v[154:155], off
	s_add_u32 m0, s101, 0x1000
	s_nop 0
	global_load_lds_dwordx4 v[156:157], off
	s_add_u32 m0, s101, 0x5000
	s_nop 0
	global_load_lds_dwordx4 v[158:159], off
	s_add_u32 m0, s101, 0x2000
	s_nop 0
	global_load_lds_dwordx4 v[160:161], off
	s_add_u32 m0, s101, 0x6000
	s_nop 0
	global_load_lds_dwordx4 v[162:163], off
	s_add_u32 m0, s101, 0x3000
	s_nop 0
	global_load_lds_dwordx4 v[164:165], off
	s_add_u32 m0, s101, 0x7000
	s_nop 0
	global_load_lds_dwordx4 v[166:167], off
	v_and_b32_e32 v212, 15, v172
	v_bfe_u32 v213, v172, 4, 2
	v_lshrrev_b32_e32 v214, 1, v212
	v_xor_b32_e32 v213, v213, v214
	v_lshlrev_b32_e32 v213, 4, v213
	v_lshl_or_b32 v212, v212, 7, v213
	v_lshrrev_b32_e32 v214, 7, v172
	v_lshl_add_u32 v168, v214, 13, v212
	v_bfe_u32 v214, v172, 6, 1
	v_lshl_add_u32 v169, v214, 13, v212
	v_add_u32_e32 v169, 0x4000, v169
	v_xor_b32_e32 v220, 64, v168
	v_xor_b32_e32 v221, 64, v169
	s_waitcnt vmcnt(0)
	s_waitcnt lgkmcnt(0)
	s_barrier
	v_mov_b32_e32 v0, 0
	v_add_u32_e32 v171, 0x9000, v144
	v_mov_b32_e32 v1, v0
	v_mov_b32_e32 v2, v0
	v_mov_b32_e32 v3, v0
	v_mov_b32_e32 v4, v0
	v_mov_b32_e32 v5, v0
	v_mov_b32_e32 v6, v0
	v_mov_b32_e32 v7, v0
	v_mov_b32_e32 v8, v0
	v_mov_b32_e32 v9, v0
	v_mov_b32_e32 v10, v0
	v_mov_b32_e32 v11, v0
	v_mov_b32_e32 v12, v0
	v_mov_b32_e32 v13, v0
	v_mov_b32_e32 v14, v0
	v_mov_b32_e32 v15, v0
	v_mov_b32_e32 v16, v0
	v_mov_b32_e32 v17, v0
	v_mov_b32_e32 v18, v0
	v_mov_b32_e32 v19, v0
	v_mov_b32_e32 v20, v0
	v_mov_b32_e32 v21, v0
	v_mov_b32_e32 v22, v0
	v_mov_b32_e32 v23, v0
	v_mov_b32_e32 v24, v0
	v_mov_b32_e32 v25, v0
	v_mov_b32_e32 v26, v0
	v_mov_b32_e32 v27, v0
	v_mov_b32_e32 v28, v0
	v_mov_b32_e32 v29, v0
	v_mov_b32_e32 v30, v0
	v_mov_b32_e32 v31, v0
	v_mov_b32_e32 v32, v0
	v_mov_b32_e32 v33, v0
	v_mov_b32_e32 v34, v0
	v_mov_b32_e32 v35, v0
	v_mov_b32_e32 v36, v0
	v_mov_b32_e32 v37, v0
	v_mov_b32_e32 v38, v0
	v_mov_b32_e32 v39, v0
	v_mov_b32_e32 v40, v0
	v_mov_b32_e32 v41, v0
	v_mov_b32_e32 v42, v0
	v_mov_b32_e32 v43, v0
	v_mov_b32_e32 v44, v0
	v_mov_b32_e32 v45, v0
	v_mov_b32_e32 v46, v0
	v_mov_b32_e32 v47, v0
	v_mov_b32_e32 v48, v0
	v_mov_b32_e32 v49, v0
	v_mov_b32_e32 v50, v0
	v_mov_b32_e32 v51, v0
	v_mov_b32_e32 v52, v0
	v_mov_b32_e32 v53, v0
	v_mov_b32_e32 v54, v0
	v_mov_b32_e32 v55, v0
	v_mov_b32_e32 v56, v0
	v_mov_b32_e32 v57, v0
	v_mov_b32_e32 v58, v0
	v_mov_b32_e32 v59, v0
	v_mov_b32_e32 v60, v0
	v_mov_b32_e32 v61, v0
	v_mov_b32_e32 v62, v0
	v_mov_b32_e32 v63, v0
	ds_read_b128 v[64:67], v168 offset:0
	ds_read_b128 v[68:71], v168 offset:2048
	ds_read_b128 v[72:75], v168 offset:4096
	ds_read_b128 v[76:79], v168 offset:6144
	ds_read_b128 v[80:83], v169 offset:0
	ds_read_b128 v[84:87], v169 offset:2048
	ds_read_b128 v[88:91], v169 offset:4096
	ds_read_b128 v[92:95], v169 offset:6144
	s_add_i32 s4, s14, 1
	s_min_u32 s4, s4, 15
	s_lshl_b32 s18, s4, 7
	s_add_u32 m0, s101, 0x8000
	v_lshl_add_u64 v[210:211], v[152:153], 0, s[18:19]
	global_load_lds_dwordx4 v[210:211], off
	s_add_u32 m0, s101, 0xc000
	v_lshl_add_u64 v[210:211], v[154:155], 0, s[18:19]
	global_load_lds_dwordx4 v[210:211], off
	ds_read_b128 v[96:99], v220 offset:0
	ds_read_b128 v[100:103], v220 offset:2048
	ds_read_b128 v[104:107], v220 offset:4096
	ds_read_b128 v[108:111], v220 offset:6144
	ds_read_b128 v[112:115], v221 offset:0
	ds_read_b128 v[116:119], v221 offset:2048
	ds_read_b128 v[120:123], v221 offset:4096
	ds_read_b128 v[124:127], v221 offset:6144
	s_waitcnt lgkmcnt(8)
; #define SB_ __builtin_amdgcn_sched_barrier(0)
; template <bool SWAP, bool HALF>
; DI void gemm_mainloop(const GemmDesc& d, int m0, int n0, bf16_t* smem, f32x16 (&acc)[2][2], int dry) {
;     ...
;   auto stage = [&](int cur, u32x4 (&ran)[4], u32x4 (&rbn)[4], int ks) {
;     ldf(cur, 1, 1); SB_;
;     mma(0); SB_;
;     ldf(cur, 2, 0); SB_;
;     lw(ran, rbn, cur ^ 1);
;     gl(ran, rbn, (ks + 3 < nk) ? ks + 3 : nk - 1);
;     SB_;
;     mma(1); SB_;
;     __syncthreads();
;     ldf(cur, 3, 1); SB_;
;     mma(0); SB_;
;     ldf(cur ^ 1, 0, 0);
;     SB_;
;     mma(1); SB_;
;     __syncthreads();
;   };
;   gl(ra0, rb0, 0);
;   gl(ra1, rb1, 1);
;   lw(ra0, rb0, 0);
;   gl(ra0, rb0, 2);
;   __syncthreads();
;   ldf(0, 0, 0);
; #pragma unroll 1
;   for (int ks = 0; ks < nk; ks += 2) {
;     stage(0, ra1, rb1, ks);
;     stage(1, ra0, rb0, ks + 1);
;   }
	v_mfma_f32_16x16x32_bf16 v[0:3], v[80:83], v[64:67], v[0:3]
	v_mfma_f32_16x16x32_bf16 v[4:7], v[84:87], v[64:67], v[4:7]
	s_add_u32 m0, s101, 0x9000
	v_lshl_add_u64 v[210:211], v[156:157], 0, s[18:19]
	global_load_lds_dwordx4 v[210:211], off
	v_mfma_f32_16x16x32_bf16 v[8:11], v[88:91], v[64:67], v[8:11]
	v_mfma_f32_16x16x32_bf16 v[12:15], v[92:95], v[64:67], v[12:15]
	s_add_u32 m0, s101, 0xd000
	v_lshl_add_u64 v[210:211], v[158:159], 0, s[18:19]
	global_load_lds_dwordx4 v[210:211], off
	v_mfma_f32_16x16x32_bf16 v[16:19], v[80:83], v[68:71], v[16:19]
	v_mfma_f32_16x16x32_bf16 v[20:23], v[84:87], v[68:71], v[20:23]
	s_add_u32 m0, s101, 0xa000
	v_lshl_add_u64 v[210:211], v[160:161], 0, s[18:19]
	global_load_lds_dwordx4 v[210:211], off
	v_mfma_f32_16x16x32_bf16 v[24:27], v[88:91], v[68:71], v[24:27]
	v_mfma_f32_16x16x32_bf16 v[28:31], v[92:95], v[68:71], v[28:31]
	s_add_u32 m0, s101, 0xe000
	v_lshl_add_u64 v[210:211], v[162:163], 0, s[18:19]
	global_load_lds_dwordx4 v[210:211], off
	v_mfma_f32_16x16x32_bf16 v[32:35], v[80:83], v[72:75], v[32:35]
	v_mfma_f32_16x16x32_bf16 v[36:39], v[84:87], v[72:75], v[36:39]
	s_add_u32 m0, s101, 0xb000
	v_lshl_add_u64 v[210:211], v[164:165], 0, s[18:19]
	global_load_lds_dwordx4 v[210:211], off
	v_mfma_f32_16x16x32_bf16 v[40:43], v[88:91], v[72:75], v[40:43]
	v_mfma_f32_16x16x32_bf16 v[44:47], v[92:95], v[72:75], v[44:47]
	s_add_u32 m0, s101, 0xf000
	v_lshl_add_u64 v[210:211], v[166:167], 0, s[18:19]
	global_load_lds_dwordx4 v[210:211], off
	v_mfma_f32_16x16x32_bf16 v[48:51], v[80:83], v[76:79], v[48:51]
	v_mfma_f32_16x16x32_bf16 v[52:55], v[84:87], v[76:79], v[52:55]
	v_mfma_f32_16x16x32_bf16 v[56:59], v[88:91], v[76:79], v[56:59]
	v_mfma_f32_16x16x32_bf16 v[60:63], v[92:95], v[76:79], v[60:63]
	s_waitcnt vmcnt(0)
	s_waitcnt lgkmcnt(0)
	s_barrier
.LBB0_1462:
	ds_read_b128 v[64:67], v168 offset:32768
	ds_read_b128 v[68:71], v168 offset:34816
	ds_read_b128 v[72:75], v168 offset:36864
	ds_read_b128 v[76:79], v168 offset:38912
	ds_read_b128 v[80:83], v169 offset:32768
	ds_read_b128 v[84:87], v169 offset:34816
	ds_read_b128 v[88:91], v169 offset:36864
	ds_read_b128 v[92:95], v169 offset:38912
	s_add_i32 s4, s14, 2
	s_min_u32 s4, s4, 15
	s_lshl_b32 s18, s4, 7
	s_add_u32 m0, s101, 0x0
	v_lshl_add_u64 v[210:211], v[152:153], 0, s[18:19]
	global_load_lds_dwordx4 v[210:211], off
	s_add_u32 m0, s101, 0x4000
	v_lshl_add_u64 v[210:211], v[154:155], 0, s[18:19]
	global_load_lds_dwordx4 v[210:211], off
	ds_read_b128 v[128:131], v220 offset:32768
	ds_read_b128 v[132:135], v220 offset:34816
	ds_read_b128 v[136:139], v220 offset:36864
	ds_read_b128 v[140:143], v220 offset:38912
	ds_read_b128 v[192:195], v221 offset:32768
	ds_read_b128 v[196:199], v221 offset:34816
	ds_read_b128 v[200:203], v221 offset:36864
	ds_read_b128 v[204:207], v221 offset:38912
	v_mfma_f32_16x16x32_bf16 v[0:3], v[112:115], v[96:99], v[0:3]
	v_mfma_f32_16x16x32_bf16 v[4:7], v[116:119], v[96:99], v[4:7]
	s_add_u32 m0, s101, 0x1000
	v_lshl_add_u64 v[210:211], v[156:157], 0, s[18:19]
	global_load_lds_dwordx4 v[210:211], off
	v_mfma_f32_16x16x32_bf16 v[8:11], v[120:123], v[96:99], v[8:11]
	v_mfma_f32_16x16x32_bf16 v[12:15], v[124:127], v[96:99], v[12:15]
	s_add_u32 m0, s101, 0x5000
	v_lshl_add_u64 v[210:211], v[158:159], 0, s[18:19]
	global_load_lds_dwordx4 v[210:211], off
	v_mfma_f32_16x16x32_bf16 v[16:19], v[112:115], v[100:103], v[16:19]
	v_mfma_f32_16x16x32_bf16 v[20:23], v[116:119], v[100:103], v[20:23]
	s_add_u32 m0, s101, 0x2000
	v_lshl_add_u64 v[210:211], v[160:161], 0, s[18:19]
	global_load_lds_dwordx4 v[210:211], off
	v_mfma_f32_16x16x32_bf16 v[24:27], v[120:123], v[100:103], v[24:27]
	v_mfma_f32_16x16x32_bf16 v[28:31], v[124:127], v[100:103], v[28:31]
	s_add_u32 m0, s101, 0x6000
	v_lshl_add_u64 v[210:211], v[162:163], 0, s[18:19]
	global_load_lds_dwordx4 v[210:211], off
	v_mfma_f32_16x16x32_bf16 v[32:35], v[112:115], v[104:107], v[32:35]
	v_mfma_f32_16x16x32_bf16 v[36:39], v[116:119], v[104:107], v[36:39]
	s_add_u32 m0, s101, 0x3000
	v_lshl_add_u64 v[210:211], v[164:165], 0, s[18:19]
	global_load_lds_dwordx4 v[210:211], off
	v_mfma_f32_16x16x32_bf16 v[40:43], v[120:123], v[104:107], v[40:43]
	v_mfma_f32_16x16x32_bf16 v[44:47], v[124:127], v[104:107], v[44:47]
	s_add_u32 m0, s101, 0x7000
	v_lshl_add_u64 v[210:211], v[166:167], 0, s[18:19]
	global_load_lds_dwordx4 v[210:211], off
	v_mfma_f32_16x16x32_bf16 v[48:51], v[112:115], v[108:111], v[48:51]
	v_mfma_f32_16x16x32_bf16 v[52:55], v[116:119], v[108:111], v[52:55]
	v_mfma_f32_16x16x32_bf16 v[56:59], v[120:123], v[108:111], v[56:59]
	v_mfma_f32_16x16x32_bf16 v[60:63], v[124:127], v[108:111], v[60:63]
	s_waitcnt lgkmcnt(8)
	v_mfma_f32_16x16x32_bf16 v[0:3], v[80:83], v[64:67], v[0:3]
	v_mfma_f32_16x16x32_bf16 v[4:7], v[84:87], v[64:67], v[4:7]
	v_mfma_f32_16x16x32_bf16 v[8:11], v[88:91], v[64:67], v[8:11]
	v_mfma_f32_16x16x32_bf16 v[12:15], v[92:95], v[64:67], v[12:15]
	v_mfma_f32_16x16x32_bf16 v[16:19], v[80:83], v[68:71], v[16:19]
	v_mfma_f32_16x16x32_bf16 v[20:23], v[84:87], v[68:71], v[20:23]
	v_mfma_f32_16x16x32_bf16 v[24:27], v[88:91], v[68:71], v[24:27]
	v_mfma_f32_16x16x32_bf16 v[28:31], v[92:95], v[68:71], v[28:31]
	v_mfma_f32_16x16x32_bf16 v[32:35], v[80:83], v[72:75], v[32:35]
	v_mfma_f32_16x16x32_bf16 v[36:39], v[84:87], v[72:75], v[36:39]
	v_mfma_f32_16x16x32_bf16 v[40:43], v[88:91], v[72:75], v[40:43]
	v_mfma_f32_16x16x32_bf16 v[44:47], v[92:95], v[72:75], v[44:47]
	v_mfma_f32_16x16x32_bf16 v[48:51], v[80:83], v[76:79], v[48:51]
	v_mfma_f32_16x16x32_bf16 v[52:55], v[84:87], v[76:79], v[52:55]
	v_mfma_f32_16x16x32_bf16 v[56:59], v[88:91], v[76:79], v[56:59]
	v_mfma_f32_16x16x32_bf16 v[60:63], v[92:95], v[76:79], v[60:63]
	s_waitcnt vmcnt(0)
	s_waitcnt lgkmcnt(0)
	s_barrier
; #define SB_ __builtin_amdgcn_sched_barrier(0)
; template <bool SWAP, bool HALF>
; DI void gemm_mainloop(const GemmDesc& d, int m0, int n0, bf16_t* smem, f32x16 (&acc)[2][2], int dry) {
;     ...
;   auto stage = [&](int cur, u32x4 (&ran)[4], u32x4 (&rbn)[4], int ks) {
;     ldf(cur, 1, 1); SB_;
;     mma(0); SB_;
;     ldf(cur, 2, 0); SB_;
;     lw(ran, rbn, cur ^ 1);
;     gl(ran, rbn, (ks + 3 < nk) ? ks + 3 : nk - 1);
;     SB_;
;     mma(1); SB_;
;     __syncthreads();
;     ldf(cur, 3, 1); SB_;
;     mma(0); SB_;
;     ldf(cur ^ 1, 0, 0);
;     SB_;
;     mma(1); SB_;
;     __syncthreads();
;   };
;   gl(ra0, rb0, 0);
;   gl(ra1, rb1, 1);
;   lw(ra0, rb0, 0);
;   gl(ra0, rb0, 2);
;   __syncthreads();
;   ldf(0, 0, 0);
; #pragma unroll 1
;   for (int ks = 0; ks < nk; ks += 2) {
;     stage(0, ra1, rb1, ks);
;     stage(1, ra0, rb0, ks + 1);
;   }
	ds_read_b128 v[64:67], v168 offset:0
	ds_read_b128 v[68:71], v168 offset:2048
	ds_read_b128 v[72:75], v168 offset:4096
	ds_read_b128 v[76:79], v168 offset:6144
	ds_read_b128 v[80:83], v169 offset:0
	ds_read_b128 v[84:87], v169 offset:2048
	ds_read_b128 v[88:91], v169 offset:4096
	ds_read_b128 v[92:95], v169 offset:6144
	s_add_i32 s4, s14, 3
	s_min_u32 s4, s4, 15
	s_lshl_b32 s18, s4, 7
	s_add_u32 m0, s101, 0x8000
	v_lshl_add_u64 v[210:211], v[152:153], 0, s[18:19]
	global_load_lds_dwordx4 v[210:211], off
	s_add_u32 m0, s101, 0xc000
	v_lshl_add_u64 v[210:211], v[154:155], 0, s[18:19]
	global_load_lds_dwordx4 v[210:211], off
	ds_read_b128 v[96:99], v220 offset:0
	ds_read_b128 v[100:103], v220 offset:2048
	ds_read_b128 v[104:107], v220 offset:4096
	ds_read_b128 v[108:111], v220 offset:6144
	ds_read_b128 v[112:115], v221 offset:0
	ds_read_b128 v[116:119], v221 offset:2048
	ds_read_b128 v[120:123], v221 offset:4096
	ds_read_b128 v[124:127], v221 offset:6144
	v_mfma_f32_16x16x32_bf16 v[0:3], v[192:195], v[128:131], v[0:3]
	v_mfma_f32_16x16x32_bf16 v[4:7], v[196:199], v[128:131], v[4:7]
	s_add_u32 m0, s101, 0x9000
	v_lshl_add_u64 v[210:211], v[156:157], 0, s[18:19]
	global_load_lds_dwordx4 v[210:211], off
	v_mfma_f32_16x16x32_bf16 v[8:11], v[200:203], v[128:131], v[8:11]
	v_mfma_f32_16x16x32_bf16 v[12:15], v[204:207], v[128:131], v[12:15]
	s_add_u32 m0, s101, 0xd000
	v_lshl_add_u64 v[210:211], v[158:159], 0, s[18:19]
	global_load_lds_dwordx4 v[210:211], off
	v_mfma_f32_16x16x32_bf16 v[16:19], v[192:195], v[132:135], v[16:19]
	v_mfma_f32_16x16x32_bf16 v[20:23], v[196:199], v[132:135], v[20:23]
	s_add_u32 m0, s101, 0xa000
	v_lshl_add_u64 v[210:211], v[160:161], 0, s[18:19]
	global_load_lds_dwordx4 v[210:211], off
	v_mfma_f32_16x16x32_bf16 v[24:27], v[200:203], v[132:135], v[24:27]
	v_mfma_f32_16x16x32_bf16 v[28:31], v[204:207], v[132:135], v[28:31]
	s_add_u32 m0, s101, 0xe000
	v_lshl_add_u64 v[210:211], v[162:163], 0, s[18:19]
	global_load_lds_dwordx4 v[210:211], off
	v_mfma_f32_16x16x32_bf16 v[32:35], v[192:195], v[136:139], v[32:35]
	v_mfma_f32_16x16x32_bf16 v[36:39], v[196:199], v[136:139], v[36:39]
	s_add_u32 m0, s101, 0xb000
	v_lshl_add_u64 v[210:211], v[164:165], 0, s[18:19]
	global_load_lds_dwordx4 v[210:211], off
	v_mfma_f32_16x16x32_bf16 v[40:43], v[200:203], v[136:139], v[40:43]
	v_mfma_f32_16x16x32_bf16 v[44:47], v[204:207], v[136:139], v[44:47]
	s_add_u32 m0, s101, 0xf000
	v_lshl_add_u64 v[210:211], v[166:167], 0, s[18:19]
	global_load_lds_dwordx4 v[210:211], off
	v_mfma_f32_16x16x32_bf16 v[48:51], v[192:195], v[140:143], v[48:51]
	v_mfma_f32_16x16x32_bf16 v[52:55], v[196:199], v[140:143], v[52:55]
	v_mfma_f32_16x16x32_bf16 v[56:59], v[200:203], v[140:143], v[56:59]
	v_mfma_f32_16x16x32_bf16 v[60:63], v[204:207], v[140:143], v[60:63]
	s_waitcnt lgkmcnt(8)
	v_mfma_f32_16x16x32_bf16 v[0:3], v[80:83], v[64:67], v[0:3]
	v_mfma_f32_16x16x32_bf16 v[4:7], v[84:87], v[64:67], v[4:7]
	v_mfma_f32_16x16x32_bf16 v[8:11], v[88:91], v[64:67], v[8:11]
	v_mfma_f32_16x16x32_bf16 v[12:15], v[92:95], v[64:67], v[12:15]
	v_mfma_f32_16x16x32_bf16 v[16:19], v[80:83], v[68:71], v[16:19]
	v_mfma_f32_16x16x32_bf16 v[20:23], v[84:87], v[68:71], v[20:23]
	v_mfma_f32_16x16x32_bf16 v[24:27], v[88:91], v[68:71], v[24:27]
	v_mfma_f32_16x16x32_bf16 v[28:31], v[92:95], v[68:71], v[28:31]
	v_mfma_f32_16x16x32_bf16 v[32:35], v[80:83], v[72:75], v[32:35]
	v_mfma_f32_16x16x32_bf16 v[36:39], v[84:87], v[72:75], v[36:39]
	v_mfma_f32_16x16x32_bf16 v[40:43], v[88:91], v[72:75], v[40:43]
	v_mfma_f32_16x16x32_bf16 v[44:47], v[92:95], v[72:75], v[44:47]
	v_mfma_f32_16x16x32_bf16 v[48:51], v[80:83], v[76:79], v[48:51]
	v_mfma_f32_16x16x32_bf16 v[52:55], v[84:87], v[76:79], v[52:55]
	v_mfma_f32_16x16x32_bf16 v[56:59], v[88:91], v[76:79], v[56:59]
	v_mfma_f32_16x16x32_bf16 v[60:63], v[92:95], v[76:79], v[60:63]
	s_add_i32 s4, s14, 2
	s_cmp_lt_u32 s14, 12
	s_mov_b32 s14, s4
	s_waitcnt vmcnt(0)
	s_waitcnt lgkmcnt(0)
	s_barrier
	s_cbranch_scc1 .LBB0_1462
	ds_read_b128 v[64:67], v168 offset:32768
	ds_read_b128 v[68:71], v168 offset:34816
	ds_read_b128 v[72:75], v168 offset:36864
	ds_read_b128 v[76:79], v168 offset:38912
	ds_read_b128 v[80:83], v169 offset:32768
	ds_read_b128 v[84:87], v169 offset:34816
	ds_read_b128 v[88:91], v169 offset:36864
	ds_read_b128 v[92:95], v169 offset:38912
	ds_read_b128 v[128:131], v220 offset:32768
	ds_read_b128 v[132:135], v220 offset:34816
	ds_read_b128 v[136:139], v220 offset:36864
	ds_read_b128 v[140:143], v220 offset:38912
	ds_read_b128 v[192:195], v221 offset:32768
	ds_read_b128 v[196:199], v221 offset:34816
	ds_read_b128 v[200:203], v221 offset:36864
	ds_read_b128 v[204:207], v221 offset:38912
	v_mfma_f32_16x16x32_bf16 v[0:3], v[112:115], v[96:99], v[0:3]
	v_mfma_f32_16x16x32_bf16 v[4:7], v[116:119], v[96:99], v[4:7]
	v_mfma_f32_16x16x32_bf16 v[8:11], v[120:123], v[96:99], v[8:11]
	v_mfma_f32_16x16x32_bf16 v[12:15], v[124:127], v[96:99], v[12:15]
	v_mfma_f32_16x16x32_bf16 v[16:19], v[112:115], v[100:103], v[16:19]
	v_mfma_f32_16x16x32_bf16 v[20:23], v[116:119], v[100:103], v[20:23]
	v_mfma_f32_16x16x32_bf16 v[24:27], v[120:123], v[100:103], v[24:27]
	v_mfma_f32_16x16x32_bf16 v[28:31], v[124:127], v[100:103], v[28:31]
	v_mfma_f32_16x16x32_bf16 v[32:35], v[112:115], v[104:107], v[32:35]
	v_mfma_f32_16x16x32_bf16 v[36:39], v[116:119], v[104:107], v[36:39]
	v_mfma_f32_16x16x32_bf16 v[40:43], v[120:123], v[104:107], v[40:43]
	v_mfma_f32_16x16x32_bf16 v[44:47], v[124:127], v[104:107], v[44:47]
	v_mfma_f32_16x16x32_bf16 v[48:51], v[112:115], v[108:111], v[48:51]
	v_mfma_f32_16x16x32_bf16 v[52:55], v[116:119], v[108:111], v[52:55]
	v_mfma_f32_16x16x32_bf16 v[56:59], v[120:123], v[108:111], v[56:59]
	v_mfma_f32_16x16x32_bf16 v[60:63], v[124:127], v[108:111], v[60:63]
	s_waitcnt lgkmcnt(8)
	v_mfma_f32_16x16x32_bf16 v[0:3], v[80:83], v[64:67], v[0:3]
	v_mfma_f32_16x16x32_bf16 v[4:7], v[84:87], v[64:67], v[4:7]
	v_mfma_f32_16x16x32_bf16 v[8:11], v[88:91], v[64:67], v[8:11]
	v_mfma_f32_16x16x32_bf16 v[12:15], v[92:95], v[64:67], v[12:15]
	v_mfma_f32_16x16x32_bf16 v[16:19], v[80:83], v[68:71], v[16:19]
	v_mfma_f32_16x16x32_bf16 v[20:23], v[84:87], v[68:71], v[20:23]
	v_mfma_f32_16x16x32_bf16 v[24:27], v[88:91], v[68:71], v[24:27]
	v_mfma_f32_16x16x32_bf16 v[28:31], v[92:95], v[68:71], v[28:31]
	v_mfma_f32_16x16x32_bf16 v[32:35], v[80:83], v[72:75], v[32:35]
	v_mfma_f32_16x16x32_bf16 v[36:39], v[84:87], v[72:75], v[36:39]
	v_mfma_f32_16x16x32_bf16 v[40:43], v[88:91], v[72:75], v[40:43]
	v_mfma_f32_16x16x32_bf16 v[44:47], v[92:95], v[72:75], v[44:47]
	v_mfma_f32_16x16x32_bf16 v[48:51], v[80:83], v[76:79], v[48:51]
	v_mfma_f32_16x16x32_bf16 v[52:55], v[84:87], v[76:79], v[52:55]
	v_mfma_f32_16x16x32_bf16 v[56:59], v[88:91], v[76:79], v[56:59]
	v_mfma_f32_16x16x32_bf16 v[60:63], v[92:95], v[76:79], v[60:63]
	s_waitcnt lgkmcnt(0)
	s_barrier
; DI float fexp2(float x) { return __builtin_amdgcn_exp2f(x); }
; #define SB_ __builtin_amdgcn_sched_barrier(0)
; template <bool SWAP, bool HALF>
; DI void gemm_mainloop(const GemmDesc& d, int m0, int n0, bf16_t* smem, f32x16 (&acc)[2][2], int dry) {
;     ...
;   auto stage = [&](int cur, u32x4 (&ran)[4], u32x4 (&rbn)[4], int ks) {
;     ldf(cur, 1, 1); SB_;
;     mma(0); SB_;
;     ldf(cur, 2, 0); SB_;
;     lw(ran, rbn, cur ^ 1);
;     gl(ran, rbn, (ks + 3 < nk) ? ks + 3 : nk - 1);
;     SB_;
;     mma(1); SB_;
;     __syncthreads();
;     ldf(cur, 3, 1); SB_;
;     mma(0); SB_;
;     ldf(cur ^ 1, 0, 0);
;     SB_;
;     mma(1); SB_;
;     __syncthreads();
;   };
; DI void gemm_tile(const GemmDesc& d, int m0, int n0, bf16_t* smem, int dry) {
;     ...
;   } else if (d.epi == EPI_SWIGLU) {
; #pragma unroll 2
;     for (int pass = 0; pass < 8; ++pass) {
;       const int row = pass * 16 + (t >> 4), c4 = t & 15, m = m0 + row;
;       if (m < M) {
;         const float rs = rs_s[row];
;         const int ac = c4 * 4, cb = (ac >> 5) * 64 + (ac & 31);
;         const f32x4 gt = *(const f32x4*)(Ct + row * CS + cb);
;         const f32x4 up = *(const f32x4*)(Ct + row * CS + cb + 32);
;         float v[4];
; #pragma unroll
;         for (int j = 0; j < 4; ++j) {
;           const float gg = gt[j] * rs;
;           v[j] = gg * __builtin_amdgcn_rcpf(1.f + fexp2(-gg * 1.44269504f)) * (up[j] * rs);
;         }
;         u32x2 o; o[0] = pk_bf16(v[0], v[1]); o[1] = pk_bf16(v[2], v[3]);
;         *(u32x2*)(d.act + (size_t)m * DFF + (n0 >> 1) + ac) = o;
;       }
;     }
	v_mfma_f32_16x16x32_bf16 v[0:3], v[192:195], v[128:131], v[0:3]
	v_mfma_f32_16x16x32_bf16 v[4:7], v[196:199], v[128:131], v[4:7]
	v_mfma_f32_16x16x32_bf16 v[8:11], v[200:203], v[128:131], v[8:11]
	v_mfma_f32_16x16x32_bf16 v[12:15], v[204:207], v[128:131], v[12:15]
	v_mfma_f32_16x16x32_bf16 v[16:19], v[192:195], v[132:135], v[16:19]
	v_mfma_f32_16x16x32_bf16 v[20:23], v[196:199], v[132:135], v[20:23]
	v_mfma_f32_16x16x32_bf16 v[24:27], v[200:203], v[132:135], v[24:27]
	v_mfma_f32_16x16x32_bf16 v[28:31], v[204:207], v[132:135], v[28:31]
	v_mfma_f32_16x16x32_bf16 v[32:35], v[192:195], v[136:139], v[32:35]
	v_mfma_f32_16x16x32_bf16 v[36:39], v[196:199], v[136:139], v[36:39]
	v_mfma_f32_16x16x32_bf16 v[40:43], v[200:203], v[136:139], v[40:43]
	v_mfma_f32_16x16x32_bf16 v[44:47], v[204:207], v[136:139], v[44:47]
	v_mfma_f32_16x16x32_bf16 v[48:51], v[192:195], v[140:143], v[48:51]
	v_mfma_f32_16x16x32_bf16 v[52:55], v[196:199], v[140:143], v[52:55]
	v_mfma_f32_16x16x32_bf16 v[56:59], v[200:203], v[140:143], v[56:59]
	v_mfma_f32_16x16x32_bf16 v[60:63], v[204:207], v[140:143], v[60:63]
	s_and_saveexec_b64 s[4:5], vcc
	s_cbranch_execz .LBB0_1465
	s_mov_b32 s14, 0x800000
	s_waitcnt vmcnt(15)
	v_mul_f32_e32 v64, 0x4b800000, v170
	v_cmp_gt_f32_e32 vcc, s14, v170
	s_nop 1
	v_cndmask_b32_e32 v64, v170, v64, vcc
	v_rsq_f32_e32 v64, v64
	s_nop 0
	v_mul_f32_e32 v65, 0x45800000, v64
	v_cndmask_b32_e32 v64, v64, v65, vcc
	v_lshl_add_u32 v65, v150, 2, v181
	ds_write_b32 v65, v64
.LBB0_1465:
	s_or_b64 exec, exec, s[4:5]
	s_waitcnt vmcnt(15)
	s_lshl_b32 s4, s13, 6
	s_ashr_i32 s5, s4, 31
	s_lshl_b64 s[4:5], s[4:5], 1
	s_add_u32 s4, s68, s4
	s_addc_u32 s5, s69, s5
	v_bfe_u32 v69, v172, 6, 1
	v_bfe_u32 v70, v172, 4, 2
	v_lshlrev_b32_e32 v69, 6, v69
	v_lshl_or_b32 v74, v70, 3, v69
	v_mov_b32_e32 v75, 0
	v_lshl_add_u64 v[72:73], s[4:5], 0, v[74:75]
	s_add_i32 s11, s11, s10
	s_sub_i32 s4, s11, s12
	s_lshl_b32 s4, s4, 10
	s_or_b32 s4, s4, s29
	s_mov_b32 s10, 0
	s_waitcnt lgkmcnt(0)
	s_barrier
	v_and_b32_e32 v64, 15, v172
	v_lshrrev_b32_e32 v65, 7, v172
	v_lshl_add_u32 v66, v65, 6, v64
	v_add_u32_e32 v67, s4, v66
	v_lshlrev_b32_e32 v68, 2, v66
	v_add_u32_e32 v68, 0x10800, v68
	v_add_u32_e32 v76, 0, v67
	v_cmp_gt_i32_e32 vcc, s23, v76
	s_and_saveexec_b64 s[4:5], vcc
	ds_read_b32 v77, v68 offset:0
	v_mad_i64_i32 v[78:79], s[12:13], v76, s26, v[72:73]
	s_waitcnt lgkmcnt(0)
	v_mul_f32_e32 v80, v77, v0
	v_mul_f32_e32 v81, v77, v1
	v_mul_f32_e32 v82, v77, v2
	v_mul_f32_e32 v83, v77, v3
	v_mul_f32_e32 v84, 0xbfb8aa3b, v80
	v_mul_f32_e32 v85, 0xbfb8aa3b, v81
	v_mul_f32_e32 v86, 0xbfb8aa3b, v82
	v_mul_f32_e32 v87, 0xbfb8aa3b, v83
	v_exp_f32_e32 v84, v84
	v_exp_f32_e32 v85, v85
	v_exp_f32_e32 v86, v86
	v_exp_f32_e32 v87, v87
	v_mul_f32_e32 v88, v77, v8
	v_mul_f32_e32 v89, v77, v9
	v_mul_f32_e32 v90, v77, v10
	v_mul_f32_e32 v91, v77, v11
	v_add_f32_e32 v84, 1.0, v84
	v_add_f32_e32 v85, 1.0, v85
	v_add_f32_e32 v86, 1.0, v86
	v_add_f32_e32 v87, 1.0, v87
	v_rcp_f32_e32 v84, v84
	v_rcp_f32_e32 v85, v85
	v_rcp_f32_e32 v86, v86
	v_rcp_f32_e32 v87, v87
	s_nop 0
	v_mul_f32_e32 v80, v80, v84
	v_mul_f32_e32 v81, v81, v85
	v_mul_f32_e32 v82, v82, v86
	v_mul_f32_e32 v83, v83, v87
	v_mul_f32_e32 v80, v88, v80
	v_mul_f32_e32 v81, v89, v81
	v_mul_f32_e32 v82, v90, v82
	v_mul_f32_e32 v83, v91, v83
	v_cvt_pk_bf16_f32 v92, v80, v81
	v_cvt_pk_bf16_f32 v93, v82, v83
	global_store_dwordx2 v[78:79], v[92:93], off
	v_mul_f32_e32 v80, v77, v4
	v_mul_f32_e32 v81, v77, v5
	v_mul_f32_e32 v82, v77, v6
	v_mul_f32_e32 v83, v77, v7
	v_mul_f32_e32 v84, 0xbfb8aa3b, v80
	v_mul_f32_e32 v85, 0xbfb8aa3b, v81
	v_mul_f32_e32 v86, 0xbfb8aa3b, v82
	v_mul_f32_e32 v87, 0xbfb8aa3b, v83
	v_exp_f32_e32 v84, v84
	v_exp_f32_e32 v85, v85
	v_exp_f32_e32 v86, v86
	v_exp_f32_e32 v87, v87
	v_mul_f32_e32 v88, v77, v12
	v_mul_f32_e32 v89, v77, v13
	v_mul_f32_e32 v90, v77, v14
	v_mul_f32_e32 v91, v77, v15
	v_add_f32_e32 v84, 1.0, v84
	v_add_f32_e32 v85, 1.0, v85
	v_add_f32_e32 v86, 1.0, v86
	v_add_f32_e32 v87, 1.0, v87
	v_rcp_f32_e32 v84, v84
	v_rcp_f32_e32 v85, v85
	v_rcp_f32_e32 v86, v86
	v_rcp_f32_e32 v87, v87
	s_nop 0
	v_mul_f32_e32 v80, v80, v84
	v_mul_f32_e32 v81, v81, v85
	v_mul_f32_e32 v82, v82, v86
	v_mul_f32_e32 v83, v83, v87
	v_mul_f32_e32 v80, v88, v80
	v_mul_f32_e32 v81, v89, v81
	v_mul_f32_e32 v82, v90, v82
	v_mul_f32_e32 v83, v91, v83
	v_cvt_pk_bf16_f32 v94, v80, v81
	v_cvt_pk_bf16_f32 v95, v82, v83
	global_store_dwordx2 v[78:79], v[94:95], off offset:32
	s_or_b64 exec, exec, s[4:5]
	v_add_u32_e32 v76, 16, v67
	v_cmp_gt_i32_e32 vcc, s23, v76
	s_and_saveexec_b64 s[4:5], vcc
	ds_read_b32 v77, v68 offset:64
	v_mad_i64_i32 v[78:79], s[12:13], v76, s26, v[72:73]
	s_waitcnt lgkmcnt(0)
; DI float fexp2(float x) { return __builtin_amdgcn_exp2f(x); }
; DI void gemm_tile(const GemmDesc& d, int m0, int n0, bf16_t* smem, int dry) {
;     ...
;   } else if (d.epi == EPI_SWIGLU) {
; #pragma unroll 2
;     for (int pass = 0; pass < 8; ++pass) {
;       const int row = pass * 16 + (t >> 4), c4 = t & 15, m = m0 + row;
;       if (m < M) {
;         const float rs = rs_s[row];
;         const int ac = c4 * 4, cb = (ac >> 5) * 64 + (ac & 31);
;         const f32x4 gt = *(const f32x4*)(Ct + row * CS + cb);
;         const f32x4 up = *(const f32x4*)(Ct + row * CS + cb + 32);
;         float v[4];
; #pragma unroll
;         for (int j = 0; j < 4; ++j) {
;           const float gg = gt[j] * rs;
;           v[j] = gg * __builtin_amdgcn_rcpf(1.f + fexp2(-gg * 1.44269504f)) * (up[j] * rs);
;         }
;         u32x2 o; o[0] = pk_bf16(v[0], v[1]); o[1] = pk_bf16(v[2], v[3]);
;         *(u32x2*)(d.act + (size_t)m * DFF + (n0 >> 1) + ac) = o;
;       }
;     }
	v_mul_f32_e32 v80, v77, v16
	v_mul_f32_e32 v81, v77, v17
	v_mul_f32_e32 v82, v77, v18
	v_mul_f32_e32 v83, v77, v19
	v_mul_f32_e32 v84, 0xbfb8aa3b, v80
	v_mul_f32_e32 v85, 0xbfb8aa3b, v81
	v_mul_f32_e32 v86, 0xbfb8aa3b, v82
	v_mul_f32_e32 v87, 0xbfb8aa3b, v83
	v_exp_f32_e32 v84, v84
	v_exp_f32_e32 v85, v85
	v_exp_f32_e32 v86, v86
	v_exp_f32_e32 v87, v87
	v_mul_f32_e32 v88, v77, v24
	v_mul_f32_e32 v89, v77, v25
	v_mul_f32_e32 v90, v77, v26
	v_mul_f32_e32 v91, v77, v27
	v_add_f32_e32 v84, 1.0, v84
	v_add_f32_e32 v85, 1.0, v85
	v_add_f32_e32 v86, 1.0, v86
	v_add_f32_e32 v87, 1.0, v87
	v_rcp_f32_e32 v84, v84
	v_rcp_f32_e32 v85, v85
	v_rcp_f32_e32 v86, v86
	v_rcp_f32_e32 v87, v87
	s_nop 0
	v_mul_f32_e32 v80, v80, v84
	v_mul_f32_e32 v81, v81, v85
	v_mul_f32_e32 v82, v82, v86
	v_mul_f32_e32 v83, v83, v87
	v_mul_f32_e32 v80, v88, v80
	v_mul_f32_e32 v81, v89, v81
	v_mul_f32_e32 v82, v90, v82
	v_mul_f32_e32 v83, v91, v83
	v_cvt_pk_bf16_f32 v92, v80, v81
	v_cvt_pk_bf16_f32 v93, v82, v83
	global_store_dwordx2 v[78:79], v[92:93], off
	v_mul_f32_e32 v80, v77, v20
	v_mul_f32_e32 v81, v77, v21
	v_mul_f32_e32 v82, v77, v22
	v_mul_f32_e32 v83, v77, v23
	v_mul_f32_e32 v84, 0xbfb8aa3b, v80
	v_mul_f32_e32 v85, 0xbfb8aa3b, v81
	v_mul_f32_e32 v86, 0xbfb8aa3b, v82
	v_mul_f32_e32 v87, 0xbfb8aa3b, v83
	v_exp_f32_e32 v84, v84
	v_exp_f32_e32 v85, v85
	v_exp_f32_e32 v86, v86
	v_exp_f32_e32 v87, v87
	v_mul_f32_e32 v88, v77, v28
	v_mul_f32_e32 v89, v77, v29
	v_mul_f32_e32 v90, v77, v30
	v_mul_f32_e32 v91, v77, v31
	v_add_f32_e32 v84, 1.0, v84
	v_add_f32_e32 v85, 1.0, v85
	v_add_f32_e32 v86, 1.0, v86
	v_add_f32_e32 v87, 1.0, v87
	v_rcp_f32_e32 v84, v84
	v_rcp_f32_e32 v85, v85
	v_rcp_f32_e32 v86, v86
	v_rcp_f32_e32 v87, v87
	s_nop 0
	v_mul_f32_e32 v80, v80, v84
	v_mul_f32_e32 v81, v81, v85
	v_mul_f32_e32 v82, v82, v86
	v_mul_f32_e32 v83, v83, v87
	v_mul_f32_e32 v80, v88, v80
	v_mul_f32_e32 v81, v89, v81
	v_mul_f32_e32 v82, v90, v82
	v_mul_f32_e32 v83, v91, v83
	v_cvt_pk_bf16_f32 v94, v80, v81
	v_cvt_pk_bf16_f32 v95, v82, v83
	global_store_dwordx2 v[78:79], v[94:95], off offset:32
	s_or_b64 exec, exec, s[4:5]
	v_add_u32_e32 v76, 32, v67
	v_cmp_gt_i32_e32 vcc, s23, v76
	s_and_saveexec_b64 s[4:5], vcc
	ds_read_b32 v77, v68 offset:128
	v_mad_i64_i32 v[78:79], s[12:13], v76, s26, v[72:73]
	s_waitcnt lgkmcnt(0)
	v_mul_f32_e32 v80, v77, v32
	v_mul_f32_e32 v81, v77, v33
	v_mul_f32_e32 v82, v77, v34
	v_mul_f32_e32 v83, v77, v35
	v_mul_f32_e32 v84, 0xbfb8aa3b, v80
	v_mul_f32_e32 v85, 0xbfb8aa3b, v81
	v_mul_f32_e32 v86, 0xbfb8aa3b, v82
	v_mul_f32_e32 v87, 0xbfb8aa3b, v83
	v_exp_f32_e32 v84, v84
	v_exp_f32_e32 v85, v85
	v_exp_f32_e32 v86, v86
	v_exp_f32_e32 v87, v87
	v_mul_f32_e32 v88, v77, v40
	v_mul_f32_e32 v89, v77, v41
	v_mul_f32_e32 v90, v77, v42
	v_mul_f32_e32 v91, v77, v43
	v_add_f32_e32 v84, 1.0, v84
	v_add_f32_e32 v85, 1.0, v85
	v_add_f32_e32 v86, 1.0, v86
	v_add_f32_e32 v87, 1.0, v87
	v_rcp_f32_e32 v84, v84
	v_rcp_f32_e32 v85, v85
	v_rcp_f32_e32 v86, v86
	v_rcp_f32_e32 v87, v87
	s_nop 0
	v_mul_f32_e32 v80, v80, v84
	v_mul_f32_e32 v81, v81, v85
	v_mul_f32_e32 v82, v82, v86
	v_mul_f32_e32 v83, v83, v87
	v_mul_f32_e32 v80, v88, v80
	v_mul_f32_e32 v81, v89, v81
	v_mul_f32_e32 v82, v90, v82
	v_mul_f32_e32 v83, v91, v83
	v_cvt_pk_bf16_f32 v92, v80, v81
	v_cvt_pk_bf16_f32 v93, v82, v83
	global_store_dwordx2 v[78:79], v[92:93], off
	v_mul_f32_e32 v80, v77, v36
	v_mul_f32_e32 v81, v77, v37
	v_mul_f32_e32 v82, v77, v38
	v_mul_f32_e32 v83, v77, v39
	v_mul_f32_e32 v84, 0xbfb8aa3b, v80
	v_mul_f32_e32 v85, 0xbfb8aa3b, v81
	v_mul_f32_e32 v86, 0xbfb8aa3b, v82
	v_mul_f32_e32 v87, 0xbfb8aa3b, v83
	v_exp_f32_e32 v84, v84
	v_exp_f32_e32 v85, v85
	v_exp_f32_e32 v86, v86
	v_exp_f32_e32 v87, v87
	v_mul_f32_e32 v88, v77, v44
	v_mul_f32_e32 v89, v77, v45
	v_mul_f32_e32 v90, v77, v46
	v_mul_f32_e32 v91, v77, v47
	v_add_f32_e32 v84, 1.0, v84
	v_add_f32_e32 v85, 1.0, v85
	v_add_f32_e32 v86, 1.0, v86
	v_add_f32_e32 v87, 1.0, v87
	v_rcp_f32_e32 v84, v84
	v_rcp_f32_e32 v85, v85
	v_rcp_f32_e32 v86, v86
	v_rcp_f32_e32 v87, v87
	s_nop 0
	v_mul_f32_e32 v80, v80, v84
	v_mul_f32_e32 v81, v81, v85
	v_mul_f32_e32 v82, v82, v86
	v_mul_f32_e32 v83, v83, v87
	v_mul_f32_e32 v80, v88, v80
	v_mul_f32_e32 v81, v89, v81
	v_mul_f32_e32 v82, v90, v82
	v_mul_f32_e32 v83, v91, v83
	v_cvt_pk_bf16_f32 v94, v80, v81
	v_cvt_pk_bf16_f32 v95, v82, v83
	global_store_dwordx2 v[78:79], v[94:95], off offset:32
	s_or_b64 exec, exec, s[4:5]
	v_add_u32_e32 v76, 48, v67
	v_cmp_gt_i32_e32 vcc, s23, v76
	s_and_saveexec_b64 s[4:5], vcc
	ds_read_b32 v77, v68 offset:192
	v_mad_i64_i32 v[78:79], s[12:13], v76, s26, v[72:73]
	s_waitcnt lgkmcnt(0)
	v_mul_f32_e32 v80, v77, v48
	v_mul_f32_e32 v81, v77, v49
	v_mul_f32_e32 v82, v77, v50
	v_mul_f32_e32 v83, v77, v51
	v_mul_f32_e32 v84, 0xbfb8aa3b, v80
	v_mul_f32_e32 v85, 0xbfb8aa3b, v81
	v_mul_f32_e32 v86, 0xbfb8aa3b, v82
	v_mul_f32_e32 v87, 0xbfb8aa3b, v83
	v_exp_f32_e32 v84, v84
	v_exp_f32_e32 v85, v85
	v_exp_f32_e32 v86, v86
	v_exp_f32_e32 v87, v87
	v_mul_f32_e32 v88, v77, v56
	v_mul_f32_e32 v89, v77, v57
	v_mul_f32_e32 v90, v77, v58
	v_mul_f32_e32 v91, v77, v59
	v_add_f32_e32 v84, 1.0, v84
	v_add_f32_e32 v85, 1.0, v85
	v_add_f32_e32 v86, 1.0, v86
	v_add_f32_e32 v87, 1.0, v87
	v_rcp_f32_e32 v84, v84
	v_rcp_f32_e32 v85, v85
	v_rcp_f32_e32 v86, v86
	v_rcp_f32_e32 v87, v87
	s_nop 0
	v_mul_f32_e32 v80, v80, v84
	v_mul_f32_e32 v81, v81, v85
	v_mul_f32_e32 v82, v82, v86
	v_mul_f32_e32 v83, v83, v87
	v_mul_f32_e32 v80, v88, v80
	v_mul_f32_e32 v81, v89, v81
	v_mul_f32_e32 v82, v90, v82
	v_mul_f32_e32 v83, v91, v83
	v_cvt_pk_bf16_f32 v92, v80, v81
	v_cvt_pk_bf16_f32 v93, v82, v83
	global_store_dwordx2 v[78:79], v[92:93], off
	v_mul_f32_e32 v80, v77, v52
	v_mul_f32_e32 v81, v77, v53
	v_mul_f32_e32 v82, v77, v54
	v_mul_f32_e32 v83, v77, v55
	v_mul_f32_e32 v84, 0xbfb8aa3b, v80
	v_mul_f32_e32 v85, 0xbfb8aa3b, v81
	v_mul_f32_e32 v86, 0xbfb8aa3b, v82
	v_mul_f32_e32 v87, 0xbfb8aa3b, v83
	v_exp_f32_e32 v84, v84
	v_exp_f32_e32 v85, v85
	v_exp_f32_e32 v86, v86
	v_exp_f32_e32 v87, v87
	v_mul_f32_e32 v88, v77, v60
	v_mul_f32_e32 v89, v77, v61
	v_mul_f32_e32 v90, v77, v62
	v_mul_f32_e32 v91, v77, v63
	v_add_f32_e32 v84, 1.0, v84
	v_add_f32_e32 v85, 1.0, v85
	v_add_f32_e32 v86, 1.0, v86
	v_add_f32_e32 v87, 1.0, v87
	v_rcp_f32_e32 v84, v84
	v_rcp_f32_e32 v85, v85
	v_rcp_f32_e32 v86, v86
	v_rcp_f32_e32 v87, v87
	s_nop 0
	v_mul_f32_e32 v80, v80, v84
	v_mul_f32_e32 v81, v81, v85
	v_mul_f32_e32 v82, v82, v86
	v_mul_f32_e32 v83, v83, v87
	v_mul_f32_e32 v80, v88, v80
	v_mul_f32_e32 v81, v89, v81
	v_mul_f32_e32 v82, v90, v82
	v_mul_f32_e32 v83, v91, v83
	v_cvt_pk_bf16_f32 v94, v80, v81
	v_cvt_pk_bf16_f32 v95, v82, v83
	global_store_dwordx2 v[78:79], v[94:95], off offset:32
	s_or_b64 exec, exec, s[4:5]
	s_branch .LBB0_1458

; DI int otid() { int t = threadIdx.x; asm volatile("" : "+v"(t)); return t; }
; template <bool SWAP, bool HALF>
; DI void gemm_mainloop(const GemmDesc& d, int m0, int n0, bf16_t* smem, f32x16 (&acc)[2][2], int dry) {
;   const int t = otid(), lane = t & 63, w = t >> 6, wm = w >> 1, wn = w & 1, r = lane & 31, hh = lane >> 5;
;   const int lrow = t >> 3, lkc = t & 7;
;   const bf16_t* ap[4]; const bf16_t* bp[4];
; #pragma unroll
;   for (int i = 0; i < 4; ++i) {
;     int am = m0 + lrow + 32 * i; am = am < M ? am : M - 1;
;     ap[i] = d.A + (size_t)am * d.lda + lkc * 8 + (d.a_grp ? (n0 / d.a_grp) * d.a_grp : 0);
;     bp[i] = d.Bt + (size_t)(n0 + lrow + 32 * i) * d.ldb + lkc * 8;
;   }
; #pragma unroll
;   for (int a = 0; a < 2; ++a)
; #pragma unroll
;     for (int b = 0; b < 2; ++b)
; #pragma unroll
;       for (int i = 0; i < 16; ++i) acc[a][b][i] = 0.f;
;   u32x4 ra0[4], rb0[4], ra1[4], rb1[4];
;   const int nk = d.K >> 6;
;   const int lds_w = lrow * LST + lkc * 8;
;   auto gl = [&](u32x4 (&ra)[4], u32x4 (&rb)[4], int ks) {
; #pragma unroll
;     for (int i = 0; i < 4; ++i) {
;       ra[i] = *(const u32x4*)(ap[i] + (size_t)ks * d.a_cs);
;       __builtin_amdgcn_sched_barrier(0);
;       rb[i] = *(const u32x4*)(bp[i] + (size_t)ks * 64);
;       __builtin_amdgcn_sched_barrier(0);
;     }
;   };
;     ...
;   gl(ra0, rb0, 0);
;   gl(ra1, rb1, 1);
;   lw(ra0, rb0, 0);
;   gl(ra0, rb0, 2);
;   __syncthreads();
;   ldf(0, 0, 0);
.LBB0_1527:
	s_lshr_b32 s1, s12, 3
	s_and_b32 s1, s1, 0xffffff8
	v_readlane_b32 s4, v228, 38
	s_sub_i32 s4, s4, s1
	s_min_i32 s4, s4, 8
	s_abs_i32 s5, s4
	v_cvt_f32_u32_e32 v0, s5
	s_sub_i32 s14, 0, s5
	s_lshl_b32 s10, s1, 3
	s_sub_i32 s10, s12, s10
	v_rcp_iflag_f32_e32 v0, v0
	s_abs_i32 s13, s10
	s_xor_b32 s11, s10, s4
	s_ashr_i32 s11, s11, 31
	v_mul_f32_e32 v0, 0x4f7ffffe, v0
	v_cvt_u32_f32_e32 v0, v0
	v_mov_b32_e32 v150, v172
	v_mov_b32_e32 v32, v172
	v_readfirstlane_b32 s15, v0
	s_mul_i32 s14, s14, s15
	s_mul_hi_u32 s14, s15, s14
	s_add_i32 s15, s15, s14
	s_mul_hi_u32 s14, s13, s15
	s_mul_i32 s15, s14, s5
	s_sub_i32 s13, s13, s15
	s_add_i32 s16, s14, 1
	s_sub_i32 s15, s13, s5
	s_cmp_ge_u32 s13, s5
	s_cselect_b32 s14, s16, s14
	s_cselect_b32 s13, s15, s13
	s_add_i32 s15, s14, 1
	s_cmp_ge_u32 s13, s5
	s_cselect_b32 s5, s15, s14
	s_xor_b32 s5, s5, s11
	s_sub_i32 s11, s5, s11
	s_mul_i32 s4, s11, s4
	s_sub_i32 s4, s10, s4
	s_add_i32 s1, s1, s4
	s_lshl_b32 s1, s1, 10
	s_or_b32 s13, s1, s29
	v_lshlrev_b32_e32 v0, 3, v32
	v_ashrrev_i32_e32 v8, 3, v32
	v_and_b32_e32 v33, 56, v0
	v_add_u32_e32 v9, s13, v8
	v_lshlrev_b32_e32 v144, 1, v33
	v_lshl_add_u64 v[4:5], s[68:69], 0, v[144:145]
	v_min_i32_e32 v0, 0x803f, v9
	v_mad_i64_i32 v[152:153], s[4:5], v0, s26, v[4:5]
	s_lshl_b32 s4, s11, 7
	v_min_i32_e32 v11, 0x801f, v9
	v_add_u32_e32 v10, s4, v8
	v_add_u32_e32 v11, 32, v11
	v_lshl_add_u64 v[6:7], s[6:7], 0, v[144:145]
	v_mad_i64_i32 v[156:157], s[10:11], v11, s26, v[4:5]
	v_add_u32_e32 v11, 32, v10
	v_mad_i64_i32 v[158:159], s[10:11], v11, s26, v[6:7]
	v_min_i32_e32 v11, 0x7fff, v9
	v_min_i32_e32 v9, 0x7fdf, v9
	v_add_u32_e32 v11, 64, v11
	v_add_u32_e32 v9, 0x60, v9
	v_mad_i64_i32 v[160:161], s[10:11], v11, s26, v[4:5]
	v_add_u32_e32 v11, 64, v10
	v_mad_i64_i32 v[164:165], s[10:11], v9, s26, v[4:5]
	v_add_u32_e32 v4, 0x60, v10
	s_movk_i32 s5, 0x48
	s_mov_b32 s1, 0
	v_mad_i64_i32 v[154:155], s[10:11], v10, s26, v[6:7]
	v_mad_i64_i32 v[162:163], s[10:11], v11, s26, v[6:7]
	v_mad_i64_i32 v[166:167], s[10:11], v4, s26, v[6:7]
	v_and_b32_e32 v34, 31, v32
	v_mul_lo_u32 v35, v8, s5
	v_add_lshl_u32 v144, v35, v33, 1
	s_waitcnt vmcnt(15)
	s_waitcnt vmcnt(14)
	s_waitcnt vmcnt(13)
	s_waitcnt vmcnt(12)
	s_waitcnt vmcnt(11)
	s_waitcnt vmcnt(10)
	s_waitcnt vmcnt(9)
	s_waitcnt vmcnt(8)
	v_lshrrev_b32_e32 v0, 1, v32
	v_and_or_b32 v1, v0, s72, v34
	v_and_b32_e32 v0, 16, v0
	s_movk_i32 s5, 0x90
	v_mad_u64_u32 v[168:169], s[10:11], v1, s5, v[0:1]
	v_and_b32_e32 v1, 0x5f, v32
	v_mul_u32_u24_e32 v1, 0x48, v1
	v_lshl_add_u32 v169, v1, 1, v0
	v_bfe_u32 v212, v172, 4, 3
	v_lshlrev_b32_e32 v212, 4, v212
	v_xor_b32_e32 v152, v152, v212
	v_xor_b32_e32 v154, v154, v212
	v_xor_b32_e32 v156, v156, v212
	v_xor_b32_e32 v158, v158, v212
	v_xor_b32_e32 v160, v160, v212
	v_xor_b32_e32 v162, v162, v212
	v_xor_b32_e32 v164, v164, v212
	v_xor_b32_e32 v166, v166, v212
	v_lshrrev_b32_e32 v213, 6, v172
	s_nop 1
	v_readfirstlane_b32 s101, v213
	s_lshl_b32 s101, s101, 10
	s_add_u32 m0, s101, 0x0
	s_nop 0
	global_load_lds_dwordx4 v[152:153], off
	s_add_u32 m0, s101, 0x4000
	s_nop 0
	global_load_lds_dwordx4 v[154:155], off
	s_add_u32 m0, s101, 0x1000
	s_nop 0
	global_load_lds_dwordx4 v[156:157], off
	s_add_u32 m0, s101, 0x5000
	s_nop 0
	global_load_lds_dwordx4 v[158:159], off
	s_add_u32 m0, s101, 0x2000
	s_nop 0
	global_load_lds_dwordx4 v[160:161], off
	s_add_u32 m0, s101, 0x6000
	s_nop 0
	global_load_lds_dwordx4 v[162:163], off
	s_add_u32 m0, s101, 0x3000
	s_nop 0
	global_load_lds_dwordx4 v[164:165], off
	s_add_u32 m0, s101, 0x7000
	s_nop 0
	global_load_lds_dwordx4 v[166:167], off
	v_and_b32_e32 v212, 15, v172
	v_bfe_u32 v213, v172, 4, 2
	v_lshrrev_b32_e32 v214, 1, v212
	v_xor_b32_e32 v213, v213, v214
	v_lshlrev_b32_e32 v213, 4, v213
	v_lshl_or_b32 v212, v212, 7, v213
	v_lshrrev_b32_e32 v214, 7, v172
	v_lshl_add_u32 v168, v214, 13, v212
	v_bfe_u32 v214, v172, 6, 1
	v_lshl_add_u32 v169, v214, 13, v212
	v_add_u32_e32 v169, 0x4000, v169
	v_xor_b32_e32 v220, 64, v168
	v_xor_b32_e32 v221, 64, v169
	s_waitcnt vmcnt(0)
	s_waitcnt lgkmcnt(0)
	s_barrier
	v_mov_b32_e32 v0, 0
	v_add_u32_e32 v170, 0x9000, v144
	v_mov_b32_e32 v1, v0
	v_mov_b32_e32 v2, v0
	v_mov_b32_e32 v3, v0
	v_mov_b32_e32 v4, v0
	v_mov_b32_e32 v5, v0
	v_mov_b32_e32 v6, v0
	v_mov_b32_e32 v7, v0
	v_mov_b32_e32 v8, v0
	v_mov_b32_e32 v9, v0
	v_mov_b32_e32 v10, v0
	v_mov_b32_e32 v11, v0
	v_mov_b32_e32 v12, v0
	v_mov_b32_e32 v13, v0
	v_mov_b32_e32 v14, v0
	v_mov_b32_e32 v15, v0
	v_mov_b32_e32 v16, v0
	v_mov_b32_e32 v17, v0
	v_mov_b32_e32 v18, v0
	v_mov_b32_e32 v19, v0
	v_mov_b32_e32 v20, v0
	v_mov_b32_e32 v21, v0
	v_mov_b32_e32 v22, v0
	v_mov_b32_e32 v23, v0
	v_mov_b32_e32 v24, v0
	v_mov_b32_e32 v25, v0
	v_mov_b32_e32 v26, v0
	v_mov_b32_e32 v27, v0
	v_mov_b32_e32 v28, v0
	v_mov_b32_e32 v29, v0
	v_mov_b32_e32 v30, v0
	v_mov_b32_e32 v31, v0
	v_mov_b32_e32 v32, v0
	v_mov_b32_e32 v33, v0
	v_mov_b32_e32 v34, v0
	v_mov_b32_e32 v35, v0
	v_mov_b32_e32 v36, v0
	v_mov_b32_e32 v37, v0
	v_mov_b32_e32 v38, v0
	v_mov_b32_e32 v39, v0
	v_mov_b32_e32 v40, v0
	v_mov_b32_e32 v41, v0
	v_mov_b32_e32 v42, v0
	v_mov_b32_e32 v43, v0
	v_mov_b32_e32 v44, v0
	v_mov_b32_e32 v45, v0
	v_mov_b32_e32 v46, v0
	v_mov_b32_e32 v47, v0
	v_mov_b32_e32 v48, v0
	v_mov_b32_e32 v49, v0
	v_mov_b32_e32 v50, v0
	v_mov_b32_e32 v51, v0
	v_mov_b32_e32 v52, v0
	v_mov_b32_e32 v53, v0
	v_mov_b32_e32 v54, v0
	v_mov_b32_e32 v55, v0
	v_mov_b32_e32 v56, v0
	v_mov_b32_e32 v57, v0
	v_mov_b32_e32 v58, v0
	v_mov_b32_e32 v59, v0
	v_mov_b32_e32 v60, v0
	v_mov_b32_e32 v61, v0
	v_mov_b32_e32 v62, v0
	v_mov_b32_e32 v63, v0
	ds_read_b128 v[64:67], v168 offset:0
	ds_read_b128 v[68:71], v168 offset:2048
	ds_read_b128 v[72:75], v168 offset:4096
	ds_read_b128 v[76:79], v168 offset:6144
	ds_read_b128 v[80:83], v169 offset:0
	ds_read_b128 v[84:87], v169 offset:2048
	ds_read_b128 v[88:91], v169 offset:4096
	ds_read_b128 v[92:95], v169 offset:6144
	s_add_i32 s5, s1, 1
	s_min_u32 s5, s5, 43
	s_lshl_b32 s18, s5, 7
	s_add_u32 m0, s101, 0x8000
	v_lshl_add_u64 v[210:211], v[152:153], 0, s[18:19]
	global_load_lds_dwordx4 v[210:211], off
	s_add_u32 m0, s101, 0xc000
	v_lshl_add_u64 v[210:211], v[154:155], 0, s[18:19]
	global_load_lds_dwordx4 v[210:211], off
	ds_read_b128 v[96:99], v220 offset:0
	ds_read_b128 v[100:103], v220 offset:2048
	ds_read_b128 v[104:107], v220 offset:4096
	ds_read_b128 v[108:111], v220 offset:6144
	ds_read_b128 v[112:115], v221 offset:0
	ds_read_b128 v[116:119], v221 offset:2048
	ds_read_b128 v[120:123], v221 offset:4096
	ds_read_b128 v[124:127], v221 offset:6144
	s_waitcnt lgkmcnt(8)
; #define MFMA32(a, b, c) __builtin_amdgcn_mfma_f32_32x32x16_bf16((a), (b), (c), 0, 0, 0)
; #define SB_ __builtin_amdgcn_sched_barrier(0)
; template <bool SWAP, bool HALF>
; DI void gemm_mainloop(const GemmDesc& d, int m0, int n0, bf16_t* smem, f32x16 (&acc)[2][2], int dry) {
;     ...
;   auto ldf = [&](int buf, int kk, int set) {
;     const bf16_t* Ab = smem + buf * 2 * TILE_EL + ((HALF ? 0 : wm * 64) + r) * LST + 8 * hh + kk * 16;
;     const bf16_t* Bb = smem + buf * 2 * TILE_EL + TILE_EL + ((HALF ? w * 32 : wn * 64) + r) * LST + 8 * hh + kk * 16;
; #pragma unroll
;     for (int i = 0; i < 2; ++i) { fa[set][i] = *(const bf16x8*)(Ab + i * 32 * LST); if (!HALF || i == 0) fb[set][i] = *(const bf16x8*)(Bb + i * 32 * LST); }
;   };
;   auto mma = [&](int set) {
; #pragma unroll
;     for (int a = 0; a < 2; ++a)
; #pragma unroll
;       for (int b = 0; b < (HALF ? 1 : 2); ++b) {
;         if (SWAP) acc[a][b] = MFMA32(fb[set][b], fa[set][a], acc[a][b]);
;         else      acc[a][b] = MFMA32(fa[set][a], fb[set][b], acc[a][b]);
;       }
;   };
;     ...
;   auto stage = [&](int cur, u32x4 (&ran)[4], u32x4 (&rbn)[4], int ks) {
;     ldf(cur, 1, 1); SB_;
;     mma(0); SB_;
;     ldf(cur, 2, 0); SB_;
;     lw(ran, rbn, cur ^ 1);
;     gl(ran, rbn, (ks + 3 < nk) ? ks + 3 : nk - 1);
;     SB_;
;     mma(1); SB_;
;     __syncthreads();
;     ldf(cur, 3, 1); SB_;
;     mma(0); SB_;
;     ldf(cur ^ 1, 0, 0);
;     SB_;
;     mma(1); SB_;
;     __syncthreads();
;   };
;   gl(ra0, rb0, 0);
;   gl(ra1, rb1, 1);
;   lw(ra0, rb0, 0);
;   gl(ra0, rb0, 2);
;   __syncthreads();
;   ldf(0, 0, 0);
; #pragma unroll 1
;   for (int ks = 0; ks < nk; ks += 2) {
;     stage(0, ra1, rb1, ks);
;     stage(1, ra0, rb0, ks + 1);
;   }
	v_mfma_f32_16x16x32_bf16 v[0:3], v[80:83], v[64:67], v[0:3]
	v_mfma_f32_16x16x32_bf16 v[4:7], v[84:87], v[64:67], v[4:7]
	s_add_u32 m0, s101, 0x9000
	v_lshl_add_u64 v[210:211], v[156:157], 0, s[18:19]
	global_load_lds_dwordx4 v[210:211], off
	v_mfma_f32_16x16x32_bf16 v[8:11], v[88:91], v[64:67], v[8:11]
	v_mfma_f32_16x16x32_bf16 v[12:15], v[92:95], v[64:67], v[12:15]
	s_add_u32 m0, s101, 0xd000
	v_lshl_add_u64 v[210:211], v[158:159], 0, s[18:19]
	global_load_lds_dwordx4 v[210:211], off
	v_mfma_f32_16x16x32_bf16 v[16:19], v[80:83], v[68:71], v[16:19]
	v_mfma_f32_16x16x32_bf16 v[20:23], v[84:87], v[68:71], v[20:23]
	s_add_u32 m0, s101, 0xa000
	v_lshl_add_u64 v[210:211], v[160:161], 0, s[18:19]
	global_load_lds_dwordx4 v[210:211], off
	v_mfma_f32_16x16x32_bf16 v[24:27], v[88:91], v[68:71], v[24:27]
	v_mfma_f32_16x16x32_bf16 v[28:31], v[92:95], v[68:71], v[28:31]
	s_add_u32 m0, s101, 0xe000
	v_lshl_add_u64 v[210:211], v[162:163], 0, s[18:19]
	global_load_lds_dwordx4 v[210:211], off
	v_mfma_f32_16x16x32_bf16 v[32:35], v[80:83], v[72:75], v[32:35]
	v_mfma_f32_16x16x32_bf16 v[36:39], v[84:87], v[72:75], v[36:39]
	s_add_u32 m0, s101, 0xb000
	v_lshl_add_u64 v[210:211], v[164:165], 0, s[18:19]
	global_load_lds_dwordx4 v[210:211], off
	v_mfma_f32_16x16x32_bf16 v[40:43], v[88:91], v[72:75], v[40:43]
	v_mfma_f32_16x16x32_bf16 v[44:47], v[92:95], v[72:75], v[44:47]
	s_add_u32 m0, s101, 0xf000
	v_lshl_add_u64 v[210:211], v[166:167], 0, s[18:19]
	global_load_lds_dwordx4 v[210:211], off
	v_mfma_f32_16x16x32_bf16 v[48:51], v[80:83], v[76:79], v[48:51]
	v_mfma_f32_16x16x32_bf16 v[52:55], v[84:87], v[76:79], v[52:55]
	v_mfma_f32_16x16x32_bf16 v[56:59], v[88:91], v[76:79], v[56:59]
	v_mfma_f32_16x16x32_bf16 v[60:63], v[92:95], v[76:79], v[60:63]
	s_waitcnt vmcnt(0)
	s_waitcnt lgkmcnt(0)
	s_barrier
.LBB0_1528:
	ds_read_b128 v[64:67], v168 offset:32768
	ds_read_b128 v[68:71], v168 offset:34816
	ds_read_b128 v[72:75], v168 offset:36864
	ds_read_b128 v[76:79], v168 offset:38912
	ds_read_b128 v[80:83], v169 offset:32768
	ds_read_b128 v[84:87], v169 offset:34816
	ds_read_b128 v[88:91], v169 offset:36864
	ds_read_b128 v[92:95], v169 offset:38912
	s_add_i32 s5, s1, 2
	s_min_u32 s5, s5, 43
	s_lshl_b32 s18, s5, 7
	s_add_u32 m0, s101, 0x0
	v_lshl_add_u64 v[210:211], v[152:153], 0, s[18:19]
	global_load_lds_dwordx4 v[210:211], off
	s_add_u32 m0, s101, 0x4000
	v_lshl_add_u64 v[210:211], v[154:155], 0, s[18:19]
	global_load_lds_dwordx4 v[210:211], off
	ds_read_b128 v[128:131], v220 offset:32768
	ds_read_b128 v[132:135], v220 offset:34816
	ds_read_b128 v[136:139], v220 offset:36864
	ds_read_b128 v[140:143], v220 offset:38912
	ds_read_b128 v[192:195], v221 offset:32768
	ds_read_b128 v[196:199], v221 offset:34816
	ds_read_b128 v[200:203], v221 offset:36864
	ds_read_b128 v[204:207], v221 offset:38912
	v_mfma_f32_16x16x32_bf16 v[0:3], v[112:115], v[96:99], v[0:3]
	v_mfma_f32_16x16x32_bf16 v[4:7], v[116:119], v[96:99], v[4:7]
	s_add_u32 m0, s101, 0x1000
	v_lshl_add_u64 v[210:211], v[156:157], 0, s[18:19]
	global_load_lds_dwordx4 v[210:211], off
	v_mfma_f32_16x16x32_bf16 v[8:11], v[120:123], v[96:99], v[8:11]
	v_mfma_f32_16x16x32_bf16 v[12:15], v[124:127], v[96:99], v[12:15]
	s_add_u32 m0, s101, 0x5000
	v_lshl_add_u64 v[210:211], v[158:159], 0, s[18:19]
	global_load_lds_dwordx4 v[210:211], off
	v_mfma_f32_16x16x32_bf16 v[16:19], v[112:115], v[100:103], v[16:19]
	v_mfma_f32_16x16x32_bf16 v[20:23], v[116:119], v[100:103], v[20:23]
	s_add_u32 m0, s101, 0x2000
	v_lshl_add_u64 v[210:211], v[160:161], 0, s[18:19]
	global_load_lds_dwordx4 v[210:211], off
	v_mfma_f32_16x16x32_bf16 v[24:27], v[120:123], v[100:103], v[24:27]
	v_mfma_f32_16x16x32_bf16 v[28:31], v[124:127], v[100:103], v[28:31]
	s_add_u32 m0, s101, 0x6000
	v_lshl_add_u64 v[210:211], v[162:163], 0, s[18:19]
	global_load_lds_dwordx4 v[210:211], off
	v_mfma_f32_16x16x32_bf16 v[32:35], v[112:115], v[104:107], v[32:35]
	v_mfma_f32_16x16x32_bf16 v[36:39], v[116:119], v[104:107], v[36:39]
	s_add_u32 m0, s101, 0x3000
	v_lshl_add_u64 v[210:211], v[164:165], 0, s[18:19]
	global_load_lds_dwordx4 v[210:211], off
	v_mfma_f32_16x16x32_bf16 v[40:43], v[120:123], v[104:107], v[40:43]
	v_mfma_f32_16x16x32_bf16 v[44:47], v[124:127], v[104:107], v[44:47]
	s_add_u32 m0, s101, 0x7000
	v_lshl_add_u64 v[210:211], v[166:167], 0, s[18:19]
	global_load_lds_dwordx4 v[210:211], off
	v_mfma_f32_16x16x32_bf16 v[48:51], v[112:115], v[108:111], v[48:51]
	v_mfma_f32_16x16x32_bf16 v[52:55], v[116:119], v[108:111], v[52:55]
	v_mfma_f32_16x16x32_bf16 v[56:59], v[120:123], v[108:111], v[56:59]
	v_mfma_f32_16x16x32_bf16 v[60:63], v[124:127], v[108:111], v[60:63]
	s_waitcnt lgkmcnt(8)
	v_mfma_f32_16x16x32_bf16 v[0:3], v[80:83], v[64:67], v[0:3]
	v_mfma_f32_16x16x32_bf16 v[4:7], v[84:87], v[64:67], v[4:7]
	v_mfma_f32_16x16x32_bf16 v[8:11], v[88:91], v[64:67], v[8:11]
	v_mfma_f32_16x16x32_bf16 v[12:15], v[92:95], v[64:67], v[12:15]
	v_mfma_f32_16x16x32_bf16 v[16:19], v[80:83], v[68:71], v[16:19]
	v_mfma_f32_16x16x32_bf16 v[20:23], v[84:87], v[68:71], v[20:23]
	v_mfma_f32_16x16x32_bf16 v[24:27], v[88:91], v[68:71], v[24:27]
	v_mfma_f32_16x16x32_bf16 v[28:31], v[92:95], v[68:71], v[28:31]
	v_mfma_f32_16x16x32_bf16 v[32:35], v[80:83], v[72:75], v[32:35]
	v_mfma_f32_16x16x32_bf16 v[36:39], v[84:87], v[72:75], v[36:39]
	v_mfma_f32_16x16x32_bf16 v[40:43], v[88:91], v[72:75], v[40:43]
	v_mfma_f32_16x16x32_bf16 v[44:47], v[92:95], v[72:75], v[44:47]
	v_mfma_f32_16x16x32_bf16 v[48:51], v[80:83], v[76:79], v[48:51]
	v_mfma_f32_16x16x32_bf16 v[52:55], v[84:87], v[76:79], v[52:55]
	v_mfma_f32_16x16x32_bf16 v[56:59], v[88:91], v[76:79], v[56:59]
	v_mfma_f32_16x16x32_bf16 v[60:63], v[92:95], v[76:79], v[60:63]
	s_waitcnt vmcnt(0)
	s_waitcnt lgkmcnt(0)
	s_barrier
; #define MFMA32(a, b, c) __builtin_amdgcn_mfma_f32_32x32x16_bf16((a), (b), (c), 0, 0, 0)
; #define SB_ __builtin_amdgcn_sched_barrier(0)
; template <bool SWAP, bool HALF>
; DI void gemm_mainloop(const GemmDesc& d, int m0, int n0, bf16_t* smem, f32x16 (&acc)[2][2], int dry) {
;     ...
;   auto ldf = [&](int buf, int kk, int set) {
;     const bf16_t* Ab = smem + buf * 2 * TILE_EL + ((HALF ? 0 : wm * 64) + r) * LST + 8 * hh + kk * 16;
;     const bf16_t* Bb = smem + buf * 2 * TILE_EL + TILE_EL + ((HALF ? w * 32 : wn * 64) + r) * LST + 8 * hh + kk * 16;
; #pragma unroll
;     for (int i = 0; i < 2; ++i) { fa[set][i] = *(const bf16x8*)(Ab + i * 32 * LST); if (!HALF || i == 0) fb[set][i] = *(const bf16x8*)(Bb + i * 32 * LST); }
;   };
;   auto mma = [&](int set) {
; #pragma unroll
;     for (int a = 0; a < 2; ++a)
; #pragma unroll
;       for (int b = 0; b < (HALF ? 1 : 2); ++b) {
;         if (SWAP) acc[a][b] = MFMA32(fb[set][b], fa[set][a], acc[a][b]);
;         else      acc[a][b] = MFMA32(fa[set][a], fb[set][b], acc[a][b]);
;       }
;   };
;     ...
;   auto stage = [&](int cur, u32x4 (&ran)[4], u32x4 (&rbn)[4], int ks) {
;     ldf(cur, 1, 1); SB_;
;     mma(0); SB_;
;     ldf(cur, 2, 0); SB_;
;     lw(ran, rbn, cur ^ 1);
;     gl(ran, rbn, (ks + 3 < nk) ? ks + 3 : nk - 1);
;     SB_;
;     mma(1); SB_;
;     __syncthreads();
;     ldf(cur, 3, 1); SB_;
;     mma(0); SB_;
;     ldf(cur ^ 1, 0, 0);
;     SB_;
;     mma(1); SB_;
;     __syncthreads();
;   };
;   gl(ra0, rb0, 0);
;   gl(ra1, rb1, 1);
;   lw(ra0, rb0, 0);
;   gl(ra0, rb0, 2);
;   __syncthreads();
;   ldf(0, 0, 0);
; #pragma unroll 1
;   for (int ks = 0; ks < nk; ks += 2) {
;     stage(0, ra1, rb1, ks);
;     stage(1, ra0, rb0, ks + 1);
;   }
	ds_read_b128 v[64:67], v168 offset:0
	ds_read_b128 v[68:71], v168 offset:2048
	ds_read_b128 v[72:75], v168 offset:4096
	ds_read_b128 v[76:79], v168 offset:6144
	ds_read_b128 v[80:83], v169 offset:0
	ds_read_b128 v[84:87], v169 offset:2048
	ds_read_b128 v[88:91], v169 offset:4096
	ds_read_b128 v[92:95], v169 offset:6144
	s_add_i32 s5, s1, 3
	s_min_u32 s5, s5, 43
	s_lshl_b32 s18, s5, 7
	s_add_u32 m0, s101, 0x8000
	v_lshl_add_u64 v[210:211], v[152:153], 0, s[18:19]
	global_load_lds_dwordx4 v[210:211], off
	s_add_u32 m0, s101, 0xc000
	v_lshl_add_u64 v[210:211], v[154:155], 0, s[18:19]
	global_load_lds_dwordx4 v[210:211], off
	ds_read_b128 v[96:99], v220 offset:0
	ds_read_b128 v[100:103], v220 offset:2048
	ds_read_b128 v[104:107], v220 offset:4096
	ds_read_b128 v[108:111], v220 offset:6144
	ds_read_b128 v[112:115], v221 offset:0
	ds_read_b128 v[116:119], v221 offset:2048
	ds_read_b128 v[120:123], v221 offset:4096
	ds_read_b128 v[124:127], v221 offset:6144
	v_mfma_f32_16x16x32_bf16 v[0:3], v[192:195], v[128:131], v[0:3]
	v_mfma_f32_16x16x32_bf16 v[4:7], v[196:199], v[128:131], v[4:7]
	s_add_u32 m0, s101, 0x9000
	v_lshl_add_u64 v[210:211], v[156:157], 0, s[18:19]
	global_load_lds_dwordx4 v[210:211], off
	v_mfma_f32_16x16x32_bf16 v[8:11], v[200:203], v[128:131], v[8:11]
	v_mfma_f32_16x16x32_bf16 v[12:15], v[204:207], v[128:131], v[12:15]
	s_add_u32 m0, s101, 0xd000
	v_lshl_add_u64 v[210:211], v[158:159], 0, s[18:19]
	global_load_lds_dwordx4 v[210:211], off
	v_mfma_f32_16x16x32_bf16 v[16:19], v[192:195], v[132:135], v[16:19]
	v_mfma_f32_16x16x32_bf16 v[20:23], v[196:199], v[132:135], v[20:23]
	s_add_u32 m0, s101, 0xa000
	v_lshl_add_u64 v[210:211], v[160:161], 0, s[18:19]
	global_load_lds_dwordx4 v[210:211], off
	v_mfma_f32_16x16x32_bf16 v[24:27], v[200:203], v[132:135], v[24:27]
	v_mfma_f32_16x16x32_bf16 v[28:31], v[204:207], v[132:135], v[28:31]
	s_add_u32 m0, s101, 0xe000
	v_lshl_add_u64 v[210:211], v[162:163], 0, s[18:19]
	global_load_lds_dwordx4 v[210:211], off
	v_mfma_f32_16x16x32_bf16 v[32:35], v[192:195], v[136:139], v[32:35]
	v_mfma_f32_16x16x32_bf16 v[36:39], v[196:199], v[136:139], v[36:39]
	s_add_u32 m0, s101, 0xb000
	v_lshl_add_u64 v[210:211], v[164:165], 0, s[18:19]
	global_load_lds_dwordx4 v[210:211], off
	v_mfma_f32_16x16x32_bf16 v[40:43], v[200:203], v[136:139], v[40:43]
	v_mfma_f32_16x16x32_bf16 v[44:47], v[204:207], v[136:139], v[44:47]
	s_add_u32 m0, s101, 0xf000
	v_lshl_add_u64 v[210:211], v[166:167], 0, s[18:19]
	global_load_lds_dwordx4 v[210:211], off
	v_mfma_f32_16x16x32_bf16 v[48:51], v[192:195], v[140:143], v[48:51]
	v_mfma_f32_16x16x32_bf16 v[52:55], v[196:199], v[140:143], v[52:55]
	v_mfma_f32_16x16x32_bf16 v[56:59], v[200:203], v[140:143], v[56:59]
	v_mfma_f32_16x16x32_bf16 v[60:63], v[204:207], v[140:143], v[60:63]
	s_waitcnt lgkmcnt(8)
	v_mfma_f32_16x16x32_bf16 v[0:3], v[80:83], v[64:67], v[0:3]
	v_mfma_f32_16x16x32_bf16 v[4:7], v[84:87], v[64:67], v[4:7]
	v_mfma_f32_16x16x32_bf16 v[8:11], v[88:91], v[64:67], v[8:11]
	v_mfma_f32_16x16x32_bf16 v[12:15], v[92:95], v[64:67], v[12:15]
	v_mfma_f32_16x16x32_bf16 v[16:19], v[80:83], v[68:71], v[16:19]
	v_mfma_f32_16x16x32_bf16 v[20:23], v[84:87], v[68:71], v[20:23]
	v_mfma_f32_16x16x32_bf16 v[24:27], v[88:91], v[68:71], v[24:27]
	v_mfma_f32_16x16x32_bf16 v[28:31], v[92:95], v[68:71], v[28:31]
	v_mfma_f32_16x16x32_bf16 v[32:35], v[80:83], v[72:75], v[32:35]
	v_mfma_f32_16x16x32_bf16 v[36:39], v[84:87], v[72:75], v[36:39]
	v_mfma_f32_16x16x32_bf16 v[40:43], v[88:91], v[72:75], v[40:43]
	v_mfma_f32_16x16x32_bf16 v[44:47], v[92:95], v[72:75], v[44:47]
	v_mfma_f32_16x16x32_bf16 v[48:51], v[80:83], v[76:79], v[48:51]
	v_mfma_f32_16x16x32_bf16 v[52:55], v[84:87], v[76:79], v[52:55]
	v_mfma_f32_16x16x32_bf16 v[56:59], v[88:91], v[76:79], v[56:59]
	v_mfma_f32_16x16x32_bf16 v[60:63], v[92:95], v[76:79], v[60:63]
	s_add_i32 s5, s1, 2
	s_cmp_lt_u32 s1, 40
	s_mov_b32 s1, s5
	s_waitcnt vmcnt(0)
	s_waitcnt lgkmcnt(0)
	s_barrier
	s_cbranch_scc1 .LBB0_1528
	ds_read_b128 v[64:67], v168 offset:32768
	ds_read_b128 v[68:71], v168 offset:34816
	ds_read_b128 v[72:75], v168 offset:36864
	ds_read_b128 v[76:79], v168 offset:38912
	ds_read_b128 v[80:83], v169 offset:32768
	ds_read_b128 v[84:87], v169 offset:34816
	ds_read_b128 v[88:91], v169 offset:36864
	ds_read_b128 v[92:95], v169 offset:38912
	ds_read_b128 v[128:131], v220 offset:32768
	ds_read_b128 v[132:135], v220 offset:34816
	ds_read_b128 v[136:139], v220 offset:36864
	ds_read_b128 v[140:143], v220 offset:38912
	ds_read_b128 v[192:195], v221 offset:32768
	ds_read_b128 v[196:199], v221 offset:34816
	ds_read_b128 v[200:203], v221 offset:36864
	ds_read_b128 v[204:207], v221 offset:38912
	v_mfma_f32_16x16x32_bf16 v[0:3], v[112:115], v[96:99], v[0:3]
	v_mfma_f32_16x16x32_bf16 v[4:7], v[116:119], v[96:99], v[4:7]
	v_mfma_f32_16x16x32_bf16 v[8:11], v[120:123], v[96:99], v[8:11]
	v_mfma_f32_16x16x32_bf16 v[12:15], v[124:127], v[96:99], v[12:15]
	v_mfma_f32_16x16x32_bf16 v[16:19], v[112:115], v[100:103], v[16:19]
	v_mfma_f32_16x16x32_bf16 v[20:23], v[116:119], v[100:103], v[20:23]
	v_mfma_f32_16x16x32_bf16 v[24:27], v[120:123], v[100:103], v[24:27]
	v_mfma_f32_16x16x32_bf16 v[28:31], v[124:127], v[100:103], v[28:31]
	v_mfma_f32_16x16x32_bf16 v[32:35], v[112:115], v[104:107], v[32:35]
	v_mfma_f32_16x16x32_bf16 v[36:39], v[116:119], v[104:107], v[36:39]
	v_mfma_f32_16x16x32_bf16 v[40:43], v[120:123], v[104:107], v[40:43]
	v_mfma_f32_16x16x32_bf16 v[44:47], v[124:127], v[104:107], v[44:47]
	v_mfma_f32_16x16x32_bf16 v[48:51], v[112:115], v[108:111], v[48:51]
	v_mfma_f32_16x16x32_bf16 v[52:55], v[116:119], v[108:111], v[52:55]
	v_mfma_f32_16x16x32_bf16 v[56:59], v[120:123], v[108:111], v[56:59]
	v_mfma_f32_16x16x32_bf16 v[60:63], v[124:127], v[108:111], v[60:63]
	s_waitcnt lgkmcnt(8)
	v_mfma_f32_16x16x32_bf16 v[0:3], v[80:83], v[64:67], v[0:3]
	v_mfma_f32_16x16x32_bf16 v[4:7], v[84:87], v[64:67], v[4:7]
	v_mfma_f32_16x16x32_bf16 v[8:11], v[88:91], v[64:67], v[8:11]
	v_mfma_f32_16x16x32_bf16 v[12:15], v[92:95], v[64:67], v[12:15]
	v_mfma_f32_16x16x32_bf16 v[16:19], v[80:83], v[68:71], v[16:19]
	v_mfma_f32_16x16x32_bf16 v[20:23], v[84:87], v[68:71], v[20:23]
	v_mfma_f32_16x16x32_bf16 v[24:27], v[88:91], v[68:71], v[24:27]
	v_mfma_f32_16x16x32_bf16 v[28:31], v[92:95], v[68:71], v[28:31]
	v_mfma_f32_16x16x32_bf16 v[32:35], v[80:83], v[72:75], v[32:35]
	v_mfma_f32_16x16x32_bf16 v[36:39], v[84:87], v[72:75], v[36:39]
	v_mfma_f32_16x16x32_bf16 v[40:43], v[88:91], v[72:75], v[40:43]
	v_mfma_f32_16x16x32_bf16 v[44:47], v[92:95], v[72:75], v[44:47]
	v_mfma_f32_16x16x32_bf16 v[48:51], v[80:83], v[76:79], v[48:51]
	v_mfma_f32_16x16x32_bf16 v[52:55], v[84:87], v[76:79], v[52:55]
	v_mfma_f32_16x16x32_bf16 v[56:59], v[88:91], v[76:79], v[56:59]
	v_mfma_f32_16x16x32_bf16 v[60:63], v[92:95], v[76:79], v[60:63]
	s_waitcnt lgkmcnt(0)
	s_barrier
; #define MFMA32(a, b, c) __builtin_amdgcn_mfma_f32_32x32x16_bf16((a), (b), (c), 0, 0, 0)
; DI float ssq_f(u64 v) { return (float)v * (1.f / 1048576.f); }
; template <bool SWAP, bool HALF>
; DI void gemm_mainloop(const GemmDesc& d, int m0, int n0, bf16_t* smem, f32x16 (&acc)[2][2], int dry) {
;     ...
;   auto mma = [&](int set) {
; #pragma unroll
;     for (int a = 0; a < 2; ++a)
; #pragma unroll
;       for (int b = 0; b < (HALF ? 1 : 2); ++b) {
;         if (SWAP) acc[a][b] = MFMA32(fb[set][b], fa[set][a], acc[a][b]);
;         else      acc[a][b] = MFMA32(fa[set][a], fb[set][b], acc[a][b]);
;       }
;   };
; DI void gemm_tile(const GemmDesc& d, int m0, int n0, bf16_t* smem, int dry) {
;     ...
;   u32x2 hpre[16];
;   if (d.epi == EPI_RESID) {
; #pragma unroll
;     for (int pass = 0; pass < 16; ++pass) {
;       int m = m0 + pass * 8 + (t >> 5); m = m < M ? m : M - 1;
;       hpre[pass] = *(const u32x2*)(d.hb + (size_t)m * D + d.c_off + n0 + (t & 31) * 4);
;     }
;   } else if (t < 128) {
;     rs_s[t] = rsqrtf(ssq_f(myss) * d.inv_dim + EPS);
;   }
;   if (half) {
; #pragma unroll
;     for (int a = 0; a < 2; ++a)
; #pragma unroll
;       for (int g = 0; g < 4; ++g) {
;         f32x4 o;
; #pragma unroll
;         for (int j = 0; j < 4; ++j) o[j] = acc[a][0][4 * g + j];
;         *(f32x4*)(Ct + (a * 32 + r) * CS + w * 32 + 8 * g + 4 * hh) = o;
;       }
;   } else {
; #pragma unroll
;     for (int a = 0; a < 2; ++a)
; #pragma unroll
;       for (int b = 0; b < 2; ++b)
; #pragma unroll
;         for (int g = 0; g < 4; ++g) {
;           f32x4 o;
; #pragma unroll
;           for (int j = 0; j < 4; ++j) o[j] = acc[a][b][4 * g + j];
;           *(f32x4*)(Ct + (wm * 64 + a * 32 + r) * CS + wn * 64 + b * 32 + 8 * g + 4 * hh) = o;
;         }
;   }
;   __syncthreads();
	v_mfma_f32_16x16x32_bf16 v[0:3], v[192:195], v[128:131], v[0:3]
	v_mfma_f32_16x16x32_bf16 v[4:7], v[196:199], v[128:131], v[4:7]
	v_mfma_f32_16x16x32_bf16 v[8:11], v[200:203], v[128:131], v[8:11]
	v_mfma_f32_16x16x32_bf16 v[12:15], v[204:207], v[128:131], v[12:15]
	v_mfma_f32_16x16x32_bf16 v[16:19], v[192:195], v[132:135], v[16:19]
	v_mfma_f32_16x16x32_bf16 v[20:23], v[196:199], v[132:135], v[20:23]
	v_mfma_f32_16x16x32_bf16 v[24:27], v[200:203], v[132:135], v[24:27]
	v_mfma_f32_16x16x32_bf16 v[28:31], v[204:207], v[132:135], v[28:31]
	v_mfma_f32_16x16x32_bf16 v[32:35], v[192:195], v[136:139], v[32:35]
	v_mfma_f32_16x16x32_bf16 v[36:39], v[196:199], v[136:139], v[36:39]
	v_mfma_f32_16x16x32_bf16 v[40:43], v[200:203], v[136:139], v[40:43]
	v_mfma_f32_16x16x32_bf16 v[44:47], v[204:207], v[136:139], v[44:47]
	v_mfma_f32_16x16x32_bf16 v[48:51], v[192:195], v[140:143], v[48:51]
	v_mfma_f32_16x16x32_bf16 v[52:55], v[196:199], v[140:143], v[52:55]
	v_mfma_f32_16x16x32_bf16 v[56:59], v[200:203], v[140:143], v[56:59]
	v_mfma_f32_16x16x32_bf16 v[60:63], v[204:207], v[140:143], v[60:63]
	s_waitcnt vmcnt(7)
	v_ashrrev_i32_e32 v98, 5, v150
	v_add_u32_e32 v92, s13, v98
	s_ashr_i32 s5, s4, 31
	s_lshl_b64 s[10:11], s[4:5], 1
	v_add_u32_e32 v70, 16, v92
	v_add_u32_e32 v72, 24, v92
	s_add_u32 s10, s56, s10
	v_lshlrev_b32_e32 v64, 3, v150
	v_min_i32_e32 v66, 0x803f, v92
	v_add_u32_e32 v68, 8, v92
	v_min_i32_e32 v70, 0x803f, v70
	v_min_i32_e32 v72, 0x803f, v72
	s_addc_u32 s11, s57, s11
	v_and_b32_e32 v144, 0xf8, v64
	v_ashrrev_i32_e32 v67, 31, v66
	v_min_i32_e32 v68, 0x803f, v68
	v_ashrrev_i32_e32 v71, 31, v70
	v_ashrrev_i32_e32 v73, 31, v72
	v_lshl_add_u64 v[64:65], s[10:11], 0, v[144:145]
	v_lshlrev_b64 v[66:67], 11, v[66:67]
	v_ashrrev_i32_e32 v69, 31, v68
	v_lshlrev_b64 v[70:71], 11, v[70:71]
	v_lshlrev_b64 v[72:73], 11, v[72:73]
	v_lshl_add_u64 v[66:67], v[64:65], 0, v[66:67]
	v_lshlrev_b64 v[68:69], 11, v[68:69]
	v_lshl_add_u64 v[70:71], v[64:65], 0, v[70:71]
	v_lshl_add_u64 v[72:73], v[64:65], 0, v[72:73]
	v_lshl_add_u64 v[68:69], v[64:65], 0, v[68:69]
	global_load_dwordx2 v[96:97], v[66:67], off
	global_load_dwordx2 v[94:95], v[68:69], off
	global_load_dwordx2 v[90:91], v[70:71], off
	global_load_dwordx2 v[88:89], v[72:73], off
	v_add_u32_e32 v66, 32, v92
	v_add_u32_e32 v70, 48, v92
	v_add_u32_e32 v72, 56, v92
	v_min_i32_e32 v66, 0x803f, v66
	v_add_u32_e32 v68, 40, v92
	v_min_i32_e32 v70, 0x803f, v70
	v_min_i32_e32 v72, 0x803f, v72
	v_ashrrev_i32_e32 v67, 31, v66
	v_min_i32_e32 v68, 0x803f, v68
	v_ashrrev_i32_e32 v71, 31, v70
	v_ashrrev_i32_e32 v73, 31, v72
	v_lshlrev_b64 v[66:67], 11, v[66:67]
	v_ashrrev_i32_e32 v69, 31, v68
	v_lshlrev_b64 v[70:71], 11, v[70:71]
	v_lshlrev_b64 v[72:73], 11, v[72:73]
	v_lshl_add_u64 v[66:67], v[64:65], 0, v[66:67]
	v_lshlrev_b64 v[68:69], 11, v[68:69]
	v_lshl_add_u64 v[70:71], v[64:65], 0, v[70:71]
	v_lshl_add_u64 v[72:73], v[64:65], 0, v[72:73]
	v_lshl_add_u64 v[68:69], v[64:65], 0, v[68:69]
	global_load_dwordx2 v[86:87], v[66:67], off
	global_load_dwordx2 v[84:85], v[68:69], off
	global_load_dwordx2 v[82:83], v[70:71], off
	global_load_dwordx2 v[80:81], v[72:73], off
	v_add_u32_e32 v66, 64, v92
	v_add_u32_e32 v70, 0x50, v92
	v_add_u32_e32 v72, 0x58, v92
	v_min_i32_e32 v66, 0x803f, v66
	v_add_u32_e32 v68, 0x48, v92
	v_min_i32_e32 v70, 0x803f, v70
	v_min_i32_e32 v72, 0x803f, v72
	v_ashrrev_i32_e32 v67, 31, v66
	v_min_i32_e32 v68, 0x803f, v68
	v_ashrrev_i32_e32 v71, 31, v70
	v_ashrrev_i32_e32 v73, 31, v72
	v_lshlrev_b64 v[66:67], 11, v[66:67]
	v_ashrrev_i32_e32 v69, 31, v68
	v_lshlrev_b64 v[70:71], 11, v[70:71]
	v_lshlrev_b64 v[72:73], 11, v[72:73]
	v_lshl_add_u64 v[66:67], v[64:65], 0, v[66:67]
	v_lshlrev_b64 v[68:69], 11, v[68:69]
	v_lshl_add_u64 v[70:71], v[64:65], 0, v[70:71]
	v_lshl_add_u64 v[72:73], v[64:65], 0, v[72:73]
	v_lshl_add_u64 v[68:69], v[64:65], 0, v[68:69]
	global_load_dwordx2 v[78:79], v[66:67], off
	global_load_dwordx2 v[76:77], v[68:69], off
	global_load_dwordx2 v[74:75], v[70:71], off
	s_nop 0
	global_load_dwordx2 v[72:73], v[72:73], off
	v_add_u32_e32 v70, 0x70, v92
	v_min_i32_e32 v70, 0x803f, v70
	v_ashrrev_i32_e32 v71, 31, v70
	v_lshlrev_b64 v[70:71], 11, v[70:71]
	v_add_u32_e32 v66, 0x60, v92
	v_add_u32_e32 v68, 0x68, v92
	s_waitcnt vmcnt(18)
	v_lshl_add_u64 v[100:101], v[64:65], 0, v[70:71]
	v_add_u32_e32 v70, 0x78, v92
	v_min_i32_e32 v66, 0x803f, v66
	v_min_i32_e32 v68, 0x803f, v68
	v_min_i32_e32 v70, 0x803f, v70
	v_ashrrev_i32_e32 v67, 31, v66
	v_ashrrev_i32_e32 v69, 31, v68
	v_ashrrev_i32_e32 v71, 31, v70
	v_lshlrev_b64 v[66:67], 11, v[66:67]
	v_lshlrev_b64 v[68:69], 11, v[68:69]
	v_lshlrev_b64 v[70:71], 11, v[70:71]
	v_lshl_add_u64 v[66:67], v[64:65], 0, v[66:67]
	v_lshl_add_u64 v[68:69], v[64:65], 0, v[68:69]
	v_lshl_add_u64 v[64:65], v[64:65], 0, v[70:71]
	global_load_dwordx2 v[70:71], v[66:67], off
	s_nop 0
	global_load_dwordx2 v[68:69], v[68:69], off
	s_nop 0
	global_load_dwordx2 v[66:67], v[100:101], off
	s_nop 0
	global_load_dwordx2 v[64:65], v[64:65], off
	v_and_b32_e32 v99, 31, v150
	v_lshrrev_b32_e32 v100, 1, v150
	v_lshlrev_b32_e32 v93, 2, v150
	v_and_or_b32 v101, v100, s72, v99
	v_and_b32_e32 v100, 16, v100
	s_movk_i32 s1, 0x100
	v_and_or_b32 v100, v93, s1, v100
	v_mad_u64_u32 v[100:101], s[10:11], v101, s22, v[100:101]
	v_and_b32_e32 v212, 15, v172
	v_lshrrev_b32_e32 v213, 1, v172
	v_and_or_b32 v212, v213, s72, v212
	v_lshlrev_b32_e32 v213, 2, v172
	v_and_b32_e32 v214, 0x30, v172
	v_and_b32_e32 v213, 0x100, v213
	v_or_b32_e32 v213, v213, v214
	v_mad_u32_u24 v100, v212, s22, v213
	ds_write_b128 v100, v[0:3]
	ds_write_b128 v100, v[4:7] offset:64
	ds_write_b128 v100, v[8:11] offset:128
	ds_write_b128 v100, v[12:15] offset:192
	ds_write_b128 v100, v[16:19] offset:8448
	ds_write_b128 v100, v[20:23] offset:8512
	ds_write_b128 v100, v[24:27] offset:8576
	ds_write_b128 v100, v[28:31] offset:8640
	ds_write_b128 v100, v[32:35] offset:16896
	ds_write_b128 v100, v[36:39] offset:16960
	ds_write_b128 v100, v[40:43] offset:17024
	ds_write_b128 v100, v[44:47] offset:17088
	ds_write_b128 v100, v[48:51] offset:25344
	ds_write_b128 v100, v[52:55] offset:25408
	ds_write_b128 v100, v[56:59] offset:25472
	ds_write_b128 v100, v[60:63] offset:25536
	v_lshl_or_b32 v0, v99, 2, s4
	v_lshlrev_b32_e32 v2, 4, v99
	v_cmp_gt_i32_e64 s[4:5], s23, v92
	v_mov_b32_e32 v4, 0
	v_ashrrev_i32_e32 v93, 31, v92
	v_ashrrev_i32_e32 v1, 31, v0
	s_waitcnt lgkmcnt(0)
	s_barrier
; DI void ssq_add(u64* p, float part) { atomicAdd(p, (u64)(part * 1048576.f + 0.5f)); }
; DI void gemm_tile(const GemmDesc& d, int m0, int n0, bf16_t* smem, int dry) {
;     ...
;   if (d.epi == EPI_RESID) {
; #pragma unroll
;     for (int pass = 0; pass < 16; ++pass) {
;       const int row = pass * 8 + (t >> 5), c4 = t & 31, m = m0 + row;
;       float part = 0.f;
;       if (m < M) {
;         const f32x4 v = *(const f32x4*)(Ct + row * CS + c4 * 4);
;         const int n = d.c_off + n0 + c4 * 4;
;         f32x4 hv;
;         hv[0] = __uint_as_float(hpre[pass][0] << 16); hv[1] = __uint_as_float(hpre[pass][0] & 0xffff0000u);
;         hv[2] = __uint_as_float(hpre[pass][1] << 16); hv[3] = __uint_as_float(hpre[pass][1] & 0xffff0000u);
; #pragma unroll
;         for (int j = 0; j < 4; ++j) { hv[j] += v[j]; part += hv[j] * hv[j]; }
;         u32x2 o; o[0] = pk_bf16(hv[0], hv[1]); o[1] = pk_bf16(hv[2], hv[3]);
;         *(u32x2*)(d.hb + (size_t)m * D + n) = o;
;       }
;       part = hsum32(part);
;       if (c4 == 0 && m < M) ssq_add(d.ssq_out + m, part);
;     }
	s_and_saveexec_b64 s[10:11], s[4:5]
	s_cbranch_execz .LBB0_1531
	v_mad_u64_u32 v[4:5], s[14:15], v98, s22, v[2:3]
	ds_read_b128 v[4:7], v4
	s_waitcnt vmcnt(15)
	v_lshlrev_b32_e32 v8, 16, v96
	v_and_b32_e32 v9, 0xffff0000, v96
	v_and_b32_e32 v11, 0xffff0000, v97
	v_lshlrev_b32_e32 v10, 16, v97
	s_waitcnt lgkmcnt(0)
	v_pk_add_f32 v[8:9], v[4:5], v[8:9]
	v_pk_add_f32 v[6:7], v[6:7], v[10:11]
	v_pk_mul_f32 v[4:5], v[8:9], v[8:9]
	v_pk_mul_f32 v[10:11], v[6:7], v[6:7]
	v_add_f32_e32 v3, v4, v5
	v_cvt_pk_bf16_f32 v8, v8, v9
	v_cvt_pk_bf16_f32 v9, v6, v7
	v_lshlrev_b64 v[6:7], 11, v[92:93]
	v_add_f32_e32 v3, v10, v3
	v_lshl_add_u64 v[6:7], s[56:57], 0, v[6:7]
	v_add_f32_e32 v4, v11, v3
	v_lshl_add_u64 v[6:7], v[0:1], 1, v[6:7]
	global_store_dwordx2 v[6:7], v[8:9], off
